# QABS, QIDX and PLAIN epilogues on the accumulator layout too (row sums of squares via in-lane sums + DPP tree); Gram K-loop variants only for the early DMA window, dead SWIGLU row loops dropped
# speedup vs baseline: 1.0725x; 1.0033x over previous
; DI void lds_barrier() { asm volatile("s_waitcnt lgkmcnt(0)\n\ts_barrier" ::: "memory"); }
; #define G_LOAD(RA, RB, KT) { size_t as_ = astep, bs_ = bstep; asm volatile("" : "+s"(as_), "+s"(bs_)); \
;       _Pragma("unroll") for (int i = 0; i < 4; ++i) { RA[i] = *(const u32x4*)(Ag + i * as_ + (KT) * 64); RB[i] = *(const u32x4*)(Bg + i * bs_ + (KT) * 64); } }
; DI void gemm_run(const GemmCfg c, char* smem, float* const g_h, u16* const g_hb, float* const g_out, const int final_out) {
;     ...
;     G_LOAD(ra0, rb0, 0);
;     __syncthreads();
;     G_STORE(ra0, rb0, 0);
;     G_LOAD(ra0, rb0, 1);
;     lds_barrier();
;     int kt = 0;
;     for (; kt + 3 < nk; kt += 2) {
;       K_STEP(0, 1, kt + 2, true, true);
;       lds_barrier();
;       K_STEP(1, 0, kt + 3, true, true);
;       lds_barrier();
;     }
.Lgemm_kloop_r1e:
	s_waitcnt lgkmcnt(8)
	v_mfma_f32_16x16x32_bf16 v[64:67], v[160:163], v[204:207], v[64:67]
	s_waitcnt lgkmcnt(7)
	v_mfma_f32_16x16x32_bf16 v[68:71], v[160:163], v[222:225], v[68:71]
	s_waitcnt lgkmcnt(6)
	v_mfma_f32_16x16x32_bf16 v[72:75], v[160:163], v[226:229], v[72:75]
	s_waitcnt lgkmcnt(5)
	v_mfma_f32_16x16x32_bf16 v[76:79], v[160:163], v[230:233], v[76:79]
	s_waitcnt lgkmcnt(4)
	v_mfma_f32_16x16x32_bf16 v[80:83], v[160:163], v[234:237], v[80:83]
	s_waitcnt lgkmcnt(3)
	v_mfma_f32_16x16x32_bf16 v[84:87], v[160:163], v[238:241], v[84:87]
	s_waitcnt lgkmcnt(2)
	v_mfma_f32_16x16x32_bf16 v[88:91], v[160:163], v[242:245], v[88:91]
	s_waitcnt lgkmcnt(1)
	v_mfma_f32_16x16x32_bf16 v[92:95], v[160:163], v[246:249], v[92:95]
	ds_read_b128 v[160:163], v215
	v_mfma_f32_16x16x32_bf16 v[96:99], v[176:179], v[204:207], v[96:99]
	v_mfma_f32_16x16x32_bf16 v[100:103], v[176:179], v[222:225], v[100:103]
	v_mfma_f32_16x16x32_bf16 v[104:107], v[176:179], v[226:229], v[104:107]
	v_mfma_f32_16x16x32_bf16 v[108:111], v[176:179], v[230:233], v[108:111]
	v_mfma_f32_16x16x32_bf16 v[112:115], v[176:179], v[234:237], v[112:115]
	v_mfma_f32_16x16x32_bf16 v[116:119], v[176:179], v[238:241], v[116:119]
	v_mfma_f32_16x16x32_bf16 v[120:123], v[176:179], v[242:245], v[120:123]
	v_mfma_f32_16x16x32_bf16 v[124:127], v[176:179], v[246:249], v[124:127]
	ds_read_b128 v[176:179], v215 offset:2048
	v_mfma_f32_16x16x32_bf16 v[0:3], v[180:183], v[204:207], v[0:3]
	v_mfma_f32_16x16x32_bf16 v[4:7], v[180:183], v[222:225], v[4:7]
	v_mfma_f32_16x16x32_bf16 v[8:11], v[180:183], v[226:229], v[8:11]
	v_mfma_f32_16x16x32_bf16 v[12:15], v[180:183], v[230:233], v[12:15]
	v_mfma_f32_16x16x32_bf16 v[16:19], v[180:183], v[234:237], v[16:19]
	v_mfma_f32_16x16x32_bf16 v[20:23], v[180:183], v[238:241], v[20:23]
	v_mfma_f32_16x16x32_bf16 v[24:27], v[180:183], v[242:245], v[24:27]
	v_mfma_f32_16x16x32_bf16 v[28:31], v[180:183], v[246:249], v[28:31]
	ds_read_b128 v[180:183], v215 offset:4096
	s_waitcnt lgkmcnt(3)
	v_mfma_f32_16x16x32_bf16 v[32:35], v[200:203], v[204:207], v[32:35]
	ds_read_b128 v[204:207], v197
	v_mfma_f32_16x16x32_bf16 v[36:39], v[200:203], v[222:225], v[36:39]
	ds_read_b128 v[222:225], v197 offset:2048
	v_mfma_f32_16x16x32_bf16 v[40:43], v[200:203], v[226:229], v[40:43]
	ds_read_b128 v[226:229], v197 offset:4096
	v_mfma_f32_16x16x32_bf16 v[44:47], v[200:203], v[230:233], v[44:47]
	ds_read_b128 v[230:233], v197 offset:6144
	v_mfma_f32_16x16x32_bf16 v[48:51], v[200:203], v[234:237], v[48:51]
	ds_read_b128 v[234:237], v197 offset:8192
	v_mfma_f32_16x16x32_bf16 v[52:55], v[200:203], v[238:241], v[52:55]
	ds_read_b128 v[238:241], v197 offset:10240
	v_mfma_f32_16x16x32_bf16 v[56:59], v[200:203], v[242:245], v[56:59]
	ds_read_b128 v[242:245], v197 offset:12288
	v_mfma_f32_16x16x32_bf16 v[60:63], v[200:203], v[246:249], v[60:63]
	ds_read_b128 v[246:249], v197 offset:14336
	ds_read_b128 v[200:203], v215 offset:6144
	s_waitcnt lgkmcnt(8)
	v_mfma_f32_16x16x32_bf16 v[64:67], v[160:163], v[204:207], v[64:67]
	s_waitcnt lgkmcnt(7)
	v_mfma_f32_16x16x32_bf16 v[68:71], v[160:163], v[222:225], v[68:71]
	s_waitcnt lgkmcnt(6)
	v_mfma_f32_16x16x32_bf16 v[72:75], v[160:163], v[226:229], v[72:75]
	v_mfma_f32_16x16x32_bf16 v[140:143], v[160:163], v[160:163], v[140:143]
	s_waitcnt lgkmcnt(5)
	v_mfma_f32_16x16x32_bf16 v[76:79], v[160:163], v[230:233], v[76:79]
	s_waitcnt lgkmcnt(4)
	v_mfma_f32_16x16x32_bf16 v[80:83], v[160:163], v[234:237], v[80:83]
	s_waitcnt lgkmcnt(3)
	v_mfma_f32_16x16x32_bf16 v[84:87], v[160:163], v[238:241], v[84:87]
	s_waitcnt lgkmcnt(2)
	v_mfma_f32_16x16x32_bf16 v[88:91], v[160:163], v[242:245], v[88:91]
	s_waitcnt lgkmcnt(1)
	v_mfma_f32_16x16x32_bf16 v[92:95], v[160:163], v[246:249], v[92:95]
	s_waitcnt vmcnt(0) lgkmcnt(0)
	s_barrier
	s_add_u32 m0, s8, 0x0
	ds_read_b128 v[160:163], v194 offset:36864
	v_mfma_f32_16x16x32_bf16 v[96:99], v[176:179], v[204:207], v[96:99]
	global_load_lds_dwordx4 v130, s[4:5]
	s_add_u32 m0, s8, 0x12000
	v_mfma_f32_16x16x32_bf16 v[100:103], v[176:179], v[222:225], v[100:103]
	global_load_lds_dwordx4 v134, s[6:7]
	s_add_u32 m0, s8, 0x400
	v_mfma_f32_16x16x32_bf16 v[104:107], v[176:179], v[226:229], v[104:107]
	v_mfma_f32_16x16x32_bf16 v[144:147], v[176:179], v[176:179], v[144:147]
	global_load_lds_dwordx4 v131, s[4:5]
	s_add_u32 m0, s8, 0x12400
	v_mfma_f32_16x16x32_bf16 v[108:111], v[176:179], v[230:233], v[108:111]
	global_load_lds_dwordx4 v135, s[6:7]
	s_add_u32 m0, s8, 0x800
	v_mfma_f32_16x16x32_bf16 v[112:115], v[176:179], v[234:237], v[112:115]
	global_load_lds_dwordx4 v132, s[4:5]
	s_add_u32 m0, s8, 0x12800
	v_mfma_f32_16x16x32_bf16 v[116:119], v[176:179], v[238:241], v[116:119]
	global_load_lds_dwordx4 v136, s[6:7]
	s_add_u32 m0, s8, 0xc00
	v_mfma_f32_16x16x32_bf16 v[120:123], v[176:179], v[242:245], v[120:123]
	global_load_lds_dwordx4 v133, s[4:5]
	s_add_u32 m0, s8, 0x12c00
	v_mfma_f32_16x16x32_bf16 v[124:127], v[176:179], v[246:249], v[124:127]
	global_load_lds_dwordx4 v137, s[6:7]
	ds_read_b128 v[176:179], v194 offset:38912
	v_mfma_f32_16x16x32_bf16 v[0:3], v[180:183], v[204:207], v[0:3]
	s_add_u32 s4, s4, 0x80
	s_addc_u32 s5, s5, 0
	s_add_u32 s6, s6, 0x80
	s_addc_u32 s7, s7, 0
	v_mfma_f32_16x16x32_bf16 v[4:7], v[180:183], v[222:225], v[4:7]
	v_mfma_f32_16x16x32_bf16 v[8:11], v[180:183], v[226:229], v[8:11]
	v_mfma_f32_16x16x32_bf16 v[148:151], v[180:183], v[180:183], v[148:151]
	v_mfma_f32_16x16x32_bf16 v[12:15], v[180:183], v[230:233], v[12:15]
	v_mfma_f32_16x16x32_bf16 v[16:19], v[180:183], v[234:237], v[16:19]
	v_mfma_f32_16x16x32_bf16 v[20:23], v[180:183], v[238:241], v[20:23]
	v_mfma_f32_16x16x32_bf16 v[24:27], v[180:183], v[242:245], v[24:27]
	v_mfma_f32_16x16x32_bf16 v[28:31], v[180:183], v[246:249], v[28:31]
	ds_read_b128 v[180:183], v194 offset:40960
	v_mfma_f32_16x16x32_bf16 v[32:35], v[200:203], v[204:207], v[32:35]
	ds_read_b128 v[204:207], v195 offset:36864
	v_mfma_f32_16x16x32_bf16 v[36:39], v[200:203], v[222:225], v[36:39]
	ds_read_b128 v[222:225], v195 offset:38912
	v_mfma_f32_16x16x32_bf16 v[40:43], v[200:203], v[226:229], v[40:43]
	v_mfma_f32_16x16x32_bf16 v[152:155], v[200:203], v[200:203], v[152:155]
	ds_read_b128 v[226:229], v195 offset:40960
	v_mfma_f32_16x16x32_bf16 v[44:47], v[200:203], v[230:233], v[44:47]
	ds_read_b128 v[230:233], v195 offset:43008
	v_mfma_f32_16x16x32_bf16 v[48:51], v[200:203], v[234:237], v[48:51]
	ds_read_b128 v[234:237], v195 offset:45056
	v_mfma_f32_16x16x32_bf16 v[52:55], v[200:203], v[238:241], v[52:55]
	ds_read_b128 v[238:241], v195 offset:47104
	v_mfma_f32_16x16x32_bf16 v[56:59], v[200:203], v[242:245], v[56:59]
	ds_read_b128 v[242:245], v195 offset:49152
	v_mfma_f32_16x16x32_bf16 v[60:63], v[200:203], v[246:249], v[60:63]
	ds_read_b128 v[246:249], v195 offset:51200
	ds_read_b128 v[200:203], v194 offset:43008
	s_waitcnt lgkmcnt(8)
; DI void lds_barrier() { asm volatile("s_waitcnt lgkmcnt(0)\n\ts_barrier" ::: "memory"); }
; #define G_LOAD(RA, RB, KT) { size_t as_ = astep, bs_ = bstep; asm volatile("" : "+s"(as_), "+s"(bs_)); \
;       _Pragma("unroll") for (int i = 0; i < 4; ++i) { RA[i] = *(const u32x4*)(Ag + i * as_ + (KT) * 64); RB[i] = *(const u32x4*)(Bg + i * bs_ + (KT) * 64); } }
; DI void gemm_run(const GemmCfg c, char* smem, float* const g_h, u16* const g_hb, float* const g_out, const int final_out) {
;     ...
;     G_LOAD(ra0, rb0, 0);
;     __syncthreads();
;     G_STORE(ra0, rb0, 0);
;     G_LOAD(ra0, rb0, 1);
;     lds_barrier();
;     int kt = 0;
;     for (; kt + 3 < nk; kt += 2) {
;       K_STEP(0, 1, kt + 2, true, true);
;       lds_barrier();
;       K_STEP(1, 0, kt + 3, true, true);
;       lds_barrier();
;     }
	v_mfma_f32_16x16x32_bf16 v[64:67], v[160:163], v[204:207], v[64:67]
	s_waitcnt lgkmcnt(7)
	v_mfma_f32_16x16x32_bf16 v[68:71], v[160:163], v[222:225], v[68:71]
	s_waitcnt lgkmcnt(6)
	v_mfma_f32_16x16x32_bf16 v[72:75], v[160:163], v[226:229], v[72:75]
	s_waitcnt lgkmcnt(5)
	v_mfma_f32_16x16x32_bf16 v[76:79], v[160:163], v[230:233], v[76:79]
	s_waitcnt lgkmcnt(4)
	v_mfma_f32_16x16x32_bf16 v[80:83], v[160:163], v[234:237], v[80:83]
	s_waitcnt lgkmcnt(3)
	v_mfma_f32_16x16x32_bf16 v[84:87], v[160:163], v[238:241], v[84:87]
	s_waitcnt lgkmcnt(2)
	v_mfma_f32_16x16x32_bf16 v[88:91], v[160:163], v[242:245], v[88:91]
	s_waitcnt lgkmcnt(1)
	v_mfma_f32_16x16x32_bf16 v[92:95], v[160:163], v[246:249], v[92:95]
	ds_read_b128 v[160:163], v215 offset:36864
	v_mfma_f32_16x16x32_bf16 v[96:99], v[176:179], v[204:207], v[96:99]
	v_mfma_f32_16x16x32_bf16 v[100:103], v[176:179], v[222:225], v[100:103]
	v_mfma_f32_16x16x32_bf16 v[104:107], v[176:179], v[226:229], v[104:107]
	v_mfma_f32_16x16x32_bf16 v[108:111], v[176:179], v[230:233], v[108:111]
	v_mfma_f32_16x16x32_bf16 v[112:115], v[176:179], v[234:237], v[112:115]
	v_mfma_f32_16x16x32_bf16 v[116:119], v[176:179], v[238:241], v[116:119]
	v_mfma_f32_16x16x32_bf16 v[120:123], v[176:179], v[242:245], v[120:123]
	v_mfma_f32_16x16x32_bf16 v[124:127], v[176:179], v[246:249], v[124:127]
	ds_read_b128 v[176:179], v215 offset:38912
	v_mfma_f32_16x16x32_bf16 v[0:3], v[180:183], v[204:207], v[0:3]
	v_mfma_f32_16x16x32_bf16 v[4:7], v[180:183], v[222:225], v[4:7]
	v_mfma_f32_16x16x32_bf16 v[8:11], v[180:183], v[226:229], v[8:11]
	v_mfma_f32_16x16x32_bf16 v[12:15], v[180:183], v[230:233], v[12:15]
	v_mfma_f32_16x16x32_bf16 v[16:19], v[180:183], v[234:237], v[16:19]
	v_mfma_f32_16x16x32_bf16 v[20:23], v[180:183], v[238:241], v[20:23]
	v_mfma_f32_16x16x32_bf16 v[24:27], v[180:183], v[242:245], v[24:27]
	v_mfma_f32_16x16x32_bf16 v[28:31], v[180:183], v[246:249], v[28:31]
	ds_read_b128 v[180:183], v215 offset:40960
	s_waitcnt lgkmcnt(3)
	v_mfma_f32_16x16x32_bf16 v[32:35], v[200:203], v[204:207], v[32:35]
	ds_read_b128 v[204:207], v197 offset:36864
	v_mfma_f32_16x16x32_bf16 v[36:39], v[200:203], v[222:225], v[36:39]
	ds_read_b128 v[222:225], v197 offset:38912
	v_mfma_f32_16x16x32_bf16 v[40:43], v[200:203], v[226:229], v[40:43]
	ds_read_b128 v[226:229], v197 offset:40960
	v_mfma_f32_16x16x32_bf16 v[44:47], v[200:203], v[230:233], v[44:47]
	ds_read_b128 v[230:233], v197 offset:43008
	v_mfma_f32_16x16x32_bf16 v[48:51], v[200:203], v[234:237], v[48:51]
	ds_read_b128 v[234:237], v197 offset:45056
	v_mfma_f32_16x16x32_bf16 v[52:55], v[200:203], v[238:241], v[52:55]
	ds_read_b128 v[238:241], v197 offset:47104
	v_mfma_f32_16x16x32_bf16 v[56:59], v[200:203], v[242:245], v[56:59]
	ds_read_b128 v[242:245], v197 offset:49152
	v_mfma_f32_16x16x32_bf16 v[60:63], v[200:203], v[246:249], v[60:63]
	ds_read_b128 v[246:249], v197 offset:51200
	ds_read_b128 v[200:203], v215 offset:43008
	s_waitcnt lgkmcnt(8)
	v_mfma_f32_16x16x32_bf16 v[64:67], v[160:163], v[204:207], v[64:67]
	s_waitcnt lgkmcnt(7)
	v_mfma_f32_16x16x32_bf16 v[68:71], v[160:163], v[222:225], v[68:71]
	s_waitcnt lgkmcnt(6)
	v_mfma_f32_16x16x32_bf16 v[72:75], v[160:163], v[226:229], v[72:75]
	v_mfma_f32_16x16x32_bf16 v[140:143], v[160:163], v[160:163], v[140:143]
	s_waitcnt lgkmcnt(5)
	v_mfma_f32_16x16x32_bf16 v[76:79], v[160:163], v[230:233], v[76:79]
	s_waitcnt lgkmcnt(4)
	v_mfma_f32_16x16x32_bf16 v[80:83], v[160:163], v[234:237], v[80:83]
	s_waitcnt lgkmcnt(3)
	v_mfma_f32_16x16x32_bf16 v[84:87], v[160:163], v[238:241], v[84:87]
	s_waitcnt lgkmcnt(2)
	v_mfma_f32_16x16x32_bf16 v[88:91], v[160:163], v[242:245], v[88:91]
	s_waitcnt lgkmcnt(1)
	v_mfma_f32_16x16x32_bf16 v[92:95], v[160:163], v[246:249], v[92:95]
	s_waitcnt vmcnt(0) lgkmcnt(0)
	s_barrier
	s_add_u32 m0, s8, 0x9000
	ds_read_b128 v[160:163], v194
	v_mfma_f32_16x16x32_bf16 v[96:99], v[176:179], v[204:207], v[96:99]
	global_load_lds_dwordx4 v130, s[4:5]
	s_add_u32 m0, s8, 0x1b000
	v_mfma_f32_16x16x32_bf16 v[100:103], v[176:179], v[222:225], v[100:103]
	global_load_lds_dwordx4 v134, s[6:7]
	s_add_u32 m0, s8, 0x9400
	v_mfma_f32_16x16x32_bf16 v[104:107], v[176:179], v[226:229], v[104:107]
	v_mfma_f32_16x16x32_bf16 v[144:147], v[176:179], v[176:179], v[144:147]
	global_load_lds_dwordx4 v131, s[4:5]
	s_add_u32 m0, s8, 0x1b400
	v_mfma_f32_16x16x32_bf16 v[108:111], v[176:179], v[230:233], v[108:111]
	global_load_lds_dwordx4 v135, s[6:7]
	s_add_u32 m0, s8, 0x9800
	v_mfma_f32_16x16x32_bf16 v[112:115], v[176:179], v[234:237], v[112:115]
	global_load_lds_dwordx4 v132, s[4:5]
	s_add_u32 m0, s8, 0x1b800
	v_mfma_f32_16x16x32_bf16 v[116:119], v[176:179], v[238:241], v[116:119]
	global_load_lds_dwordx4 v136, s[6:7]
	s_add_u32 m0, s8, 0x9c00
	v_mfma_f32_16x16x32_bf16 v[120:123], v[176:179], v[242:245], v[120:123]
	global_load_lds_dwordx4 v133, s[4:5]
	s_add_u32 m0, s8, 0x1bc00
	v_mfma_f32_16x16x32_bf16 v[124:127], v[176:179], v[246:249], v[124:127]
	global_load_lds_dwordx4 v137, s[6:7]
	ds_read_b128 v[176:179], v194 offset:2048
	v_mfma_f32_16x16x32_bf16 v[0:3], v[180:183], v[204:207], v[0:3]
	s_add_u32 s4, s4, 0x80
	s_addc_u32 s5, s5, 0
	s_add_u32 s6, s6, 0x80
	s_addc_u32 s7, s7, 0
	v_mfma_f32_16x16x32_bf16 v[4:7], v[180:183], v[222:225], v[4:7]
	v_mfma_f32_16x16x32_bf16 v[8:11], v[180:183], v[226:229], v[8:11]
	v_mfma_f32_16x16x32_bf16 v[148:151], v[180:183], v[180:183], v[148:151]
	v_mfma_f32_16x16x32_bf16 v[12:15], v[180:183], v[230:233], v[12:15]
	v_mfma_f32_16x16x32_bf16 v[16:19], v[180:183], v[234:237], v[16:19]
	v_mfma_f32_16x16x32_bf16 v[20:23], v[180:183], v[238:241], v[20:23]
	v_mfma_f32_16x16x32_bf16 v[24:27], v[180:183], v[242:245], v[24:27]
	v_mfma_f32_16x16x32_bf16 v[28:31], v[180:183], v[246:249], v[28:31]
	ds_read_b128 v[180:183], v194 offset:4096
	v_mfma_f32_16x16x32_bf16 v[32:35], v[200:203], v[204:207], v[32:35]
	ds_read_b128 v[204:207], v195
	v_mfma_f32_16x16x32_bf16 v[36:39], v[200:203], v[222:225], v[36:39]
	ds_read_b128 v[222:225], v195 offset:2048
	v_mfma_f32_16x16x32_bf16 v[40:43], v[200:203], v[226:229], v[40:43]
	v_mfma_f32_16x16x32_bf16 v[152:155], v[200:203], v[200:203], v[152:155]
	ds_read_b128 v[226:229], v195 offset:4096
	v_mfma_f32_16x16x32_bf16 v[44:47], v[200:203], v[230:233], v[44:47]
	ds_read_b128 v[230:233], v195 offset:6144
	v_mfma_f32_16x16x32_bf16 v[48:51], v[200:203], v[234:237], v[48:51]
	ds_read_b128 v[234:237], v195 offset:8192
	v_mfma_f32_16x16x32_bf16 v[52:55], v[200:203], v[238:241], v[52:55]
	ds_read_b128 v[238:241], v195 offset:10240
	v_mfma_f32_16x16x32_bf16 v[56:59], v[200:203], v[242:245], v[56:59]
	ds_read_b128 v[242:245], v195 offset:12288
	v_mfma_f32_16x16x32_bf16 v[60:63], v[200:203], v[246:249], v[60:63]
	ds_read_b128 v[246:249], v195 offset:14336
	ds_read_b128 v[200:203], v194 offset:6144
	s_add_i32 s1, s1, 2
	s_cmp_lt_i32 s1, s0
	s_cbranch_scc1 .Lgemm_kloop_r1e
; DI void lds_barrier() { asm volatile("s_waitcnt lgkmcnt(0)\n\ts_barrier" ::: "memory"); }
; DI void gemm_run(const GemmCfg c, char* smem, float* const g_h, u16* const g_hb, float* const g_out, const int final_out) {
;     ...
;     K_STEP(0, 1, 0, true, false);
;     lds_barrier();
;     K_STEP(1, 0, 0, false, false);
;     lds_barrier();
	s_waitcnt lgkmcnt(8)
	v_mfma_f32_16x16x32_bf16 v[64:67], v[160:163], v[204:207], v[64:67]
	s_waitcnt lgkmcnt(7)
	v_mfma_f32_16x16x32_bf16 v[68:71], v[160:163], v[222:225], v[68:71]
	s_waitcnt lgkmcnt(6)
	v_mfma_f32_16x16x32_bf16 v[72:75], v[160:163], v[226:229], v[72:75]
	s_waitcnt lgkmcnt(5)
	v_mfma_f32_16x16x32_bf16 v[76:79], v[160:163], v[230:233], v[76:79]
	s_waitcnt lgkmcnt(4)
	v_mfma_f32_16x16x32_bf16 v[80:83], v[160:163], v[234:237], v[80:83]
	s_waitcnt lgkmcnt(3)
	v_mfma_f32_16x16x32_bf16 v[84:87], v[160:163], v[238:241], v[84:87]
	s_waitcnt lgkmcnt(2)
	v_mfma_f32_16x16x32_bf16 v[88:91], v[160:163], v[242:245], v[88:91]
	s_waitcnt lgkmcnt(1)
	v_mfma_f32_16x16x32_bf16 v[92:95], v[160:163], v[246:249], v[92:95]
	ds_read_b128 v[160:163], v215
	v_mfma_f32_16x16x32_bf16 v[96:99], v[176:179], v[204:207], v[96:99]
	v_mfma_f32_16x16x32_bf16 v[100:103], v[176:179], v[222:225], v[100:103]
	v_mfma_f32_16x16x32_bf16 v[104:107], v[176:179], v[226:229], v[104:107]
	v_mfma_f32_16x16x32_bf16 v[108:111], v[176:179], v[230:233], v[108:111]
	v_mfma_f32_16x16x32_bf16 v[112:115], v[176:179], v[234:237], v[112:115]
	v_mfma_f32_16x16x32_bf16 v[116:119], v[176:179], v[238:241], v[116:119]
	v_mfma_f32_16x16x32_bf16 v[120:123], v[176:179], v[242:245], v[120:123]
	v_mfma_f32_16x16x32_bf16 v[124:127], v[176:179], v[246:249], v[124:127]
	ds_read_b128 v[176:179], v215 offset:2048
	v_mfma_f32_16x16x32_bf16 v[0:3], v[180:183], v[204:207], v[0:3]
	v_mfma_f32_16x16x32_bf16 v[4:7], v[180:183], v[222:225], v[4:7]
	v_mfma_f32_16x16x32_bf16 v[8:11], v[180:183], v[226:229], v[8:11]
	v_mfma_f32_16x16x32_bf16 v[12:15], v[180:183], v[230:233], v[12:15]
	v_mfma_f32_16x16x32_bf16 v[16:19], v[180:183], v[234:237], v[16:19]
	v_mfma_f32_16x16x32_bf16 v[20:23], v[180:183], v[238:241], v[20:23]
	v_mfma_f32_16x16x32_bf16 v[24:27], v[180:183], v[242:245], v[24:27]
	v_mfma_f32_16x16x32_bf16 v[28:31], v[180:183], v[246:249], v[28:31]
	ds_read_b128 v[180:183], v215 offset:4096
	s_waitcnt lgkmcnt(3)
	v_mfma_f32_16x16x32_bf16 v[32:35], v[200:203], v[204:207], v[32:35]
	ds_read_b128 v[204:207], v197
	v_mfma_f32_16x16x32_bf16 v[36:39], v[200:203], v[222:225], v[36:39]
	ds_read_b128 v[222:225], v197 offset:2048
	v_mfma_f32_16x16x32_bf16 v[40:43], v[200:203], v[226:229], v[40:43]
	ds_read_b128 v[226:229], v197 offset:4096
	v_mfma_f32_16x16x32_bf16 v[44:47], v[200:203], v[230:233], v[44:47]
	ds_read_b128 v[230:233], v197 offset:6144
	v_mfma_f32_16x16x32_bf16 v[48:51], v[200:203], v[234:237], v[48:51]
	ds_read_b128 v[234:237], v197 offset:8192
	v_mfma_f32_16x16x32_bf16 v[52:55], v[200:203], v[238:241], v[52:55]
	ds_read_b128 v[238:241], v197 offset:10240
	v_mfma_f32_16x16x32_bf16 v[56:59], v[200:203], v[242:245], v[56:59]
	ds_read_b128 v[242:245], v197 offset:12288
	v_mfma_f32_16x16x32_bf16 v[60:63], v[200:203], v[246:249], v[60:63]
	ds_read_b128 v[246:249], v197 offset:14336
	ds_read_b128 v[200:203], v215 offset:6144
	s_waitcnt lgkmcnt(8)
	v_mfma_f32_16x16x32_bf16 v[64:67], v[160:163], v[204:207], v[64:67]
	s_waitcnt lgkmcnt(7)
	v_mfma_f32_16x16x32_bf16 v[68:71], v[160:163], v[222:225], v[68:71]
	s_waitcnt lgkmcnt(6)
	v_mfma_f32_16x16x32_bf16 v[72:75], v[160:163], v[226:229], v[72:75]
	v_mfma_f32_16x16x32_bf16 v[140:143], v[160:163], v[160:163], v[140:143]
	s_waitcnt lgkmcnt(5)
	v_mfma_f32_16x16x32_bf16 v[76:79], v[160:163], v[230:233], v[76:79]
	s_waitcnt lgkmcnt(4)
	v_mfma_f32_16x16x32_bf16 v[80:83], v[160:163], v[234:237], v[80:83]
	s_waitcnt lgkmcnt(3)
	v_mfma_f32_16x16x32_bf16 v[84:87], v[160:163], v[238:241], v[84:87]
	s_waitcnt lgkmcnt(2)
	v_mfma_f32_16x16x32_bf16 v[88:91], v[160:163], v[242:245], v[88:91]
	s_waitcnt lgkmcnt(1)
	v_mfma_f32_16x16x32_bf16 v[92:95], v[160:163], v[246:249], v[92:95]
	s_waitcnt vmcnt(0) lgkmcnt(0)
	s_barrier
	ds_read_b128 v[160:163], v194 offset:36864
	v_mfma_f32_16x16x32_bf16 v[96:99], v[176:179], v[204:207], v[96:99]
	v_mfma_f32_16x16x32_bf16 v[100:103], v[176:179], v[222:225], v[100:103]
	v_mfma_f32_16x16x32_bf16 v[104:107], v[176:179], v[226:229], v[104:107]
	v_mfma_f32_16x16x32_bf16 v[144:147], v[176:179], v[176:179], v[144:147]
	v_mfma_f32_16x16x32_bf16 v[108:111], v[176:179], v[230:233], v[108:111]
	v_mfma_f32_16x16x32_bf16 v[112:115], v[176:179], v[234:237], v[112:115]
	v_mfma_f32_16x16x32_bf16 v[116:119], v[176:179], v[238:241], v[116:119]
	v_mfma_f32_16x16x32_bf16 v[120:123], v[176:179], v[242:245], v[120:123]
	v_mfma_f32_16x16x32_bf16 v[124:127], v[176:179], v[246:249], v[124:127]
	ds_read_b128 v[176:179], v194 offset:38912
	v_mfma_f32_16x16x32_bf16 v[0:3], v[180:183], v[204:207], v[0:3]
	v_mfma_f32_16x16x32_bf16 v[4:7], v[180:183], v[222:225], v[4:7]
	v_mfma_f32_16x16x32_bf16 v[8:11], v[180:183], v[226:229], v[8:11]
	v_mfma_f32_16x16x32_bf16 v[148:151], v[180:183], v[180:183], v[148:151]
	v_mfma_f32_16x16x32_bf16 v[12:15], v[180:183], v[230:233], v[12:15]
	v_mfma_f32_16x16x32_bf16 v[16:19], v[180:183], v[234:237], v[16:19]
	v_mfma_f32_16x16x32_bf16 v[20:23], v[180:183], v[238:241], v[20:23]
	v_mfma_f32_16x16x32_bf16 v[24:27], v[180:183], v[242:245], v[24:27]
	v_mfma_f32_16x16x32_bf16 v[28:31], v[180:183], v[246:249], v[28:31]
	ds_read_b128 v[180:183], v194 offset:40960
	v_mfma_f32_16x16x32_bf16 v[32:35], v[200:203], v[204:207], v[32:35]
	ds_read_b128 v[204:207], v195 offset:36864
	v_mfma_f32_16x16x32_bf16 v[36:39], v[200:203], v[222:225], v[36:39]
	ds_read_b128 v[222:225], v195 offset:38912
	v_mfma_f32_16x16x32_bf16 v[40:43], v[200:203], v[226:229], v[40:43]
	v_mfma_f32_16x16x32_bf16 v[152:155], v[200:203], v[200:203], v[152:155]
	ds_read_b128 v[226:229], v195 offset:40960
	v_mfma_f32_16x16x32_bf16 v[44:47], v[200:203], v[230:233], v[44:47]
	ds_read_b128 v[230:233], v195 offset:43008
	v_mfma_f32_16x16x32_bf16 v[48:51], v[200:203], v[234:237], v[48:51]
	ds_read_b128 v[234:237], v195 offset:45056
	v_mfma_f32_16x16x32_bf16 v[52:55], v[200:203], v[238:241], v[52:55]
	ds_read_b128 v[238:241], v195 offset:47104
	v_mfma_f32_16x16x32_bf16 v[56:59], v[200:203], v[242:245], v[56:59]
	ds_read_b128 v[242:245], v195 offset:49152
	v_mfma_f32_16x16x32_bf16 v[60:63], v[200:203], v[246:249], v[60:63]
	ds_read_b128 v[246:249], v195 offset:51200
	ds_read_b128 v[200:203], v194 offset:43008
	s_waitcnt lgkmcnt(8)
; DI void lds_barrier() { asm volatile("s_waitcnt lgkmcnt(0)\n\ts_barrier" ::: "memory"); }
; DI void gemm_run(const GemmCfg c, char* smem, float* const g_h, u16* const g_hb, float* const g_out, const int final_out) {
;     ...
;     K_STEP(0, 1, 0, true, false);
;     lds_barrier();
;     K_STEP(1, 0, 0, false, false);
;     lds_barrier();
	v_mfma_f32_16x16x32_bf16 v[64:67], v[160:163], v[204:207], v[64:67]
	s_waitcnt lgkmcnt(7)
	v_mfma_f32_16x16x32_bf16 v[68:71], v[160:163], v[222:225], v[68:71]
	s_waitcnt lgkmcnt(6)
	v_mfma_f32_16x16x32_bf16 v[72:75], v[160:163], v[226:229], v[72:75]
	s_waitcnt lgkmcnt(5)
	v_mfma_f32_16x16x32_bf16 v[76:79], v[160:163], v[230:233], v[76:79]
	s_waitcnt lgkmcnt(4)
	v_mfma_f32_16x16x32_bf16 v[80:83], v[160:163], v[234:237], v[80:83]
	s_waitcnt lgkmcnt(3)
	v_mfma_f32_16x16x32_bf16 v[84:87], v[160:163], v[238:241], v[84:87]
	s_waitcnt lgkmcnt(2)
	v_mfma_f32_16x16x32_bf16 v[88:91], v[160:163], v[242:245], v[88:91]
	s_waitcnt lgkmcnt(1)
	v_mfma_f32_16x16x32_bf16 v[92:95], v[160:163], v[246:249], v[92:95]
	ds_read_b128 v[160:163], v215 offset:36864
	v_mfma_f32_16x16x32_bf16 v[96:99], v[176:179], v[204:207], v[96:99]
	v_mfma_f32_16x16x32_bf16 v[100:103], v[176:179], v[222:225], v[100:103]
	v_mfma_f32_16x16x32_bf16 v[104:107], v[176:179], v[226:229], v[104:107]
	v_mfma_f32_16x16x32_bf16 v[108:111], v[176:179], v[230:233], v[108:111]
	v_mfma_f32_16x16x32_bf16 v[112:115], v[176:179], v[234:237], v[112:115]
	v_mfma_f32_16x16x32_bf16 v[116:119], v[176:179], v[238:241], v[116:119]
	v_mfma_f32_16x16x32_bf16 v[120:123], v[176:179], v[242:245], v[120:123]
	v_mfma_f32_16x16x32_bf16 v[124:127], v[176:179], v[246:249], v[124:127]
	ds_read_b128 v[176:179], v215 offset:38912
	v_mfma_f32_16x16x32_bf16 v[0:3], v[180:183], v[204:207], v[0:3]
	v_mfma_f32_16x16x32_bf16 v[4:7], v[180:183], v[222:225], v[4:7]
	v_mfma_f32_16x16x32_bf16 v[8:11], v[180:183], v[226:229], v[8:11]
	v_mfma_f32_16x16x32_bf16 v[12:15], v[180:183], v[230:233], v[12:15]
	v_mfma_f32_16x16x32_bf16 v[16:19], v[180:183], v[234:237], v[16:19]
	v_mfma_f32_16x16x32_bf16 v[20:23], v[180:183], v[238:241], v[20:23]
	v_mfma_f32_16x16x32_bf16 v[24:27], v[180:183], v[242:245], v[24:27]
	v_mfma_f32_16x16x32_bf16 v[28:31], v[180:183], v[246:249], v[28:31]
	ds_read_b128 v[180:183], v215 offset:40960
	s_waitcnt lgkmcnt(3)
	v_mfma_f32_16x16x32_bf16 v[32:35], v[200:203], v[204:207], v[32:35]
	ds_read_b128 v[204:207], v197 offset:36864
	v_mfma_f32_16x16x32_bf16 v[36:39], v[200:203], v[222:225], v[36:39]
	ds_read_b128 v[222:225], v197 offset:38912
	v_mfma_f32_16x16x32_bf16 v[40:43], v[200:203], v[226:229], v[40:43]
	ds_read_b128 v[226:229], v197 offset:40960
	v_mfma_f32_16x16x32_bf16 v[44:47], v[200:203], v[230:233], v[44:47]
	ds_read_b128 v[230:233], v197 offset:43008
	v_mfma_f32_16x16x32_bf16 v[48:51], v[200:203], v[234:237], v[48:51]
	ds_read_b128 v[234:237], v197 offset:45056
	v_mfma_f32_16x16x32_bf16 v[52:55], v[200:203], v[238:241], v[52:55]
	ds_read_b128 v[238:241], v197 offset:47104
	v_mfma_f32_16x16x32_bf16 v[56:59], v[200:203], v[242:245], v[56:59]
	ds_read_b128 v[242:245], v197 offset:49152
	v_mfma_f32_16x16x32_bf16 v[60:63], v[200:203], v[246:249], v[60:63]
	ds_read_b128 v[246:249], v197 offset:51200
	ds_read_b128 v[200:203], v215 offset:43008
	s_waitcnt lgkmcnt(8)
	v_mfma_f32_16x16x32_bf16 v[64:67], v[160:163], v[204:207], v[64:67]
	s_waitcnt lgkmcnt(7)
	v_mfma_f32_16x16x32_bf16 v[68:71], v[160:163], v[222:225], v[68:71]
	s_waitcnt lgkmcnt(6)
	v_mfma_f32_16x16x32_bf16 v[72:75], v[160:163], v[226:229], v[72:75]
	v_mfma_f32_16x16x32_bf16 v[140:143], v[160:163], v[160:163], v[140:143]
	s_waitcnt lgkmcnt(5)
	v_mfma_f32_16x16x32_bf16 v[76:79], v[160:163], v[230:233], v[76:79]
	s_waitcnt lgkmcnt(4)
	v_mfma_f32_16x16x32_bf16 v[80:83], v[160:163], v[234:237], v[80:83]
	s_waitcnt lgkmcnt(3)
	v_mfma_f32_16x16x32_bf16 v[84:87], v[160:163], v[238:241], v[84:87]
	s_waitcnt lgkmcnt(2)
	v_mfma_f32_16x16x32_bf16 v[88:91], v[160:163], v[242:245], v[88:91]
	s_waitcnt lgkmcnt(1)
	v_mfma_f32_16x16x32_bf16 v[92:95], v[160:163], v[246:249], v[92:95]
	v_mfma_f32_16x16x32_bf16 v[96:99], v[176:179], v[204:207], v[96:99]
	v_mfma_f32_16x16x32_bf16 v[100:103], v[176:179], v[222:225], v[100:103]
	v_mfma_f32_16x16x32_bf16 v[104:107], v[176:179], v[226:229], v[104:107]
	v_mfma_f32_16x16x32_bf16 v[144:147], v[176:179], v[176:179], v[144:147]
	v_mfma_f32_16x16x32_bf16 v[108:111], v[176:179], v[230:233], v[108:111]
	v_mfma_f32_16x16x32_bf16 v[112:115], v[176:179], v[234:237], v[112:115]
	v_mfma_f32_16x16x32_bf16 v[116:119], v[176:179], v[238:241], v[116:119]
	v_mfma_f32_16x16x32_bf16 v[120:123], v[176:179], v[242:245], v[120:123]
	v_mfma_f32_16x16x32_bf16 v[124:127], v[176:179], v[246:249], v[124:127]
	v_mfma_f32_16x16x32_bf16 v[0:3], v[180:183], v[204:207], v[0:3]
	v_mfma_f32_16x16x32_bf16 v[4:7], v[180:183], v[222:225], v[4:7]
	v_mfma_f32_16x16x32_bf16 v[8:11], v[180:183], v[226:229], v[8:11]
	v_mfma_f32_16x16x32_bf16 v[148:151], v[180:183], v[180:183], v[148:151]
	v_mfma_f32_16x16x32_bf16 v[12:15], v[180:183], v[230:233], v[12:15]
	v_mfma_f32_16x16x32_bf16 v[16:19], v[180:183], v[234:237], v[16:19]
	v_mfma_f32_16x16x32_bf16 v[20:23], v[180:183], v[238:241], v[20:23]
	v_mfma_f32_16x16x32_bf16 v[24:27], v[180:183], v[242:245], v[24:27]
	v_mfma_f32_16x16x32_bf16 v[28:31], v[180:183], v[246:249], v[28:31]
	s_waitcnt lgkmcnt(0)
	v_mfma_f32_16x16x32_bf16 v[32:35], v[200:203], v[204:207], v[32:35]
	v_mfma_f32_16x16x32_bf16 v[36:39], v[200:203], v[222:225], v[36:39]
	v_mfma_f32_16x16x32_bf16 v[40:43], v[200:203], v[226:229], v[40:43]
	v_mfma_f32_16x16x32_bf16 v[152:155], v[200:203], v[200:203], v[152:155]
	v_mfma_f32_16x16x32_bf16 v[44:47], v[200:203], v[230:233], v[44:47]
	v_mfma_f32_16x16x32_bf16 v[48:51], v[200:203], v[234:237], v[48:51]
	v_mfma_f32_16x16x32_bf16 v[52:55], v[200:203], v[238:241], v[52:55]
	v_mfma_f32_16x16x32_bf16 v[56:59], v[200:203], v[242:245], v[56:59]
	v_mfma_f32_16x16x32_bf16 v[60:63], v[200:203], v[246:249], v[60:63]
	s_branch .Lgemm_kdone
; DI void lds_barrier() { asm volatile("s_waitcnt lgkmcnt(0)\n\ts_barrier" ::: "memory"); }
; #define G_LOAD(RA, RB, KT) { size_t as_ = astep, bs_ = bstep; asm volatile("" : "+s"(as_), "+s"(bs_)); \
;       _Pragma("unroll") for (int i = 0; i < 4; ++i) { RA[i] = *(const u32x4*)(Ag + i * as_ + (KT) * 64); RB[i] = *(const u32x4*)(Bg + i * bs_ + (KT) * 64); } }
; DI void gemm_run(const GemmCfg c, char* smem, float* const g_h, u16* const g_hb, float* const g_out, const int final_out) {
;     ...
;     G_LOAD(ra0, rb0, 0);
;     __syncthreads();
;     G_STORE(ra0, rb0, 0);
;     G_LOAD(ra0, rb0, 1);
;     lds_barrier();
;     int kt = 0;
;     for (; kt + 3 < nk; kt += 2) {
;       K_STEP(0, 1, kt + 2, true, true);
;       lds_barrier();
;       K_STEP(1, 0, kt + 3, true, true);
;       lds_barrier();
;     }
.Lgemm_kloop_nl:
	s_waitcnt lgkmcnt(8)
	v_mfma_f32_16x16x32_bf16 v[64:67], v[160:163], v[204:207], v[64:67]
	s_waitcnt lgkmcnt(7)
	v_mfma_f32_16x16x32_bf16 v[68:71], v[160:163], v[222:225], v[68:71]
	s_waitcnt lgkmcnt(6)
	v_mfma_f32_16x16x32_bf16 v[72:75], v[160:163], v[226:229], v[72:75]
	s_waitcnt lgkmcnt(5)
	v_mfma_f32_16x16x32_bf16 v[76:79], v[160:163], v[230:233], v[76:79]
	s_waitcnt lgkmcnt(4)
	v_mfma_f32_16x16x32_bf16 v[80:83], v[160:163], v[234:237], v[80:83]
	s_waitcnt lgkmcnt(3)
	v_mfma_f32_16x16x32_bf16 v[84:87], v[160:163], v[238:241], v[84:87]
	s_waitcnt lgkmcnt(2)
	v_mfma_f32_16x16x32_bf16 v[88:91], v[160:163], v[242:245], v[88:91]
	s_waitcnt lgkmcnt(1)
	v_mfma_f32_16x16x32_bf16 v[92:95], v[160:163], v[246:249], v[92:95]
	ds_read_b128 v[160:163], v215
	v_mfma_f32_16x16x32_bf16 v[96:99], v[176:179], v[204:207], v[96:99]
	v_mfma_f32_16x16x32_bf16 v[100:103], v[176:179], v[222:225], v[100:103]
	v_mfma_f32_16x16x32_bf16 v[104:107], v[176:179], v[226:229], v[104:107]
	v_mfma_f32_16x16x32_bf16 v[108:111], v[176:179], v[230:233], v[108:111]
	v_mfma_f32_16x16x32_bf16 v[112:115], v[176:179], v[234:237], v[112:115]
	v_mfma_f32_16x16x32_bf16 v[116:119], v[176:179], v[238:241], v[116:119]
	v_mfma_f32_16x16x32_bf16 v[120:123], v[176:179], v[242:245], v[120:123]
	v_mfma_f32_16x16x32_bf16 v[124:127], v[176:179], v[246:249], v[124:127]
	ds_read_b128 v[176:179], v215 offset:2048
	v_mfma_f32_16x16x32_bf16 v[0:3], v[180:183], v[204:207], v[0:3]
	v_mfma_f32_16x16x32_bf16 v[4:7], v[180:183], v[222:225], v[4:7]
	v_mfma_f32_16x16x32_bf16 v[8:11], v[180:183], v[226:229], v[8:11]
	v_mfma_f32_16x16x32_bf16 v[12:15], v[180:183], v[230:233], v[12:15]
	v_mfma_f32_16x16x32_bf16 v[16:19], v[180:183], v[234:237], v[16:19]
	v_mfma_f32_16x16x32_bf16 v[20:23], v[180:183], v[238:241], v[20:23]
	v_mfma_f32_16x16x32_bf16 v[24:27], v[180:183], v[242:245], v[24:27]
	v_mfma_f32_16x16x32_bf16 v[28:31], v[180:183], v[246:249], v[28:31]
	ds_read_b128 v[180:183], v215 offset:4096
	s_waitcnt lgkmcnt(3)
	v_mfma_f32_16x16x32_bf16 v[32:35], v[200:203], v[204:207], v[32:35]
	ds_read_b128 v[204:207], v197
	v_mfma_f32_16x16x32_bf16 v[36:39], v[200:203], v[222:225], v[36:39]
	ds_read_b128 v[222:225], v197 offset:2048
	v_mfma_f32_16x16x32_bf16 v[40:43], v[200:203], v[226:229], v[40:43]
	ds_read_b128 v[226:229], v197 offset:4096
	v_mfma_f32_16x16x32_bf16 v[44:47], v[200:203], v[230:233], v[44:47]
	ds_read_b128 v[230:233], v197 offset:6144
	v_mfma_f32_16x16x32_bf16 v[48:51], v[200:203], v[234:237], v[48:51]
	ds_read_b128 v[234:237], v197 offset:8192
	v_mfma_f32_16x16x32_bf16 v[52:55], v[200:203], v[238:241], v[52:55]
	ds_read_b128 v[238:241], v197 offset:10240
	v_mfma_f32_16x16x32_bf16 v[56:59], v[200:203], v[242:245], v[56:59]
	ds_read_b128 v[242:245], v197 offset:12288
	v_mfma_f32_16x16x32_bf16 v[60:63], v[200:203], v[246:249], v[60:63]
	ds_read_b128 v[246:249], v197 offset:14336
	ds_read_b128 v[200:203], v215 offset:6144
	s_waitcnt lgkmcnt(8)
	v_mfma_f32_16x16x32_bf16 v[64:67], v[160:163], v[204:207], v[64:67]
	s_waitcnt lgkmcnt(7)
	v_mfma_f32_16x16x32_bf16 v[68:71], v[160:163], v[222:225], v[68:71]
	s_waitcnt lgkmcnt(6)
	v_mfma_f32_16x16x32_bf16 v[72:75], v[160:163], v[226:229], v[72:75]
	s_waitcnt lgkmcnt(5)
	v_mfma_f32_16x16x32_bf16 v[76:79], v[160:163], v[230:233], v[76:79]
	s_waitcnt lgkmcnt(4)
	v_mfma_f32_16x16x32_bf16 v[80:83], v[160:163], v[234:237], v[80:83]
	s_waitcnt lgkmcnt(3)
	v_mfma_f32_16x16x32_bf16 v[84:87], v[160:163], v[238:241], v[84:87]
	s_waitcnt lgkmcnt(2)
	v_mfma_f32_16x16x32_bf16 v[88:91], v[160:163], v[242:245], v[88:91]
	s_waitcnt lgkmcnt(1)
	v_mfma_f32_16x16x32_bf16 v[92:95], v[160:163], v[246:249], v[92:95]
	s_waitcnt vmcnt(0) lgkmcnt(0)
	s_barrier
	ds_read_b128 v[160:163], v194 offset:36864
	v_mfma_f32_16x16x32_bf16 v[96:99], v[176:179], v[204:207], v[96:99]
	v_mfma_f32_16x16x32_bf16 v[100:103], v[176:179], v[222:225], v[100:103]
	v_mfma_f32_16x16x32_bf16 v[104:107], v[176:179], v[226:229], v[104:107]
	v_mfma_f32_16x16x32_bf16 v[108:111], v[176:179], v[230:233], v[108:111]
	v_mfma_f32_16x16x32_bf16 v[112:115], v[176:179], v[234:237], v[112:115]
	v_mfma_f32_16x16x32_bf16 v[116:119], v[176:179], v[238:241], v[116:119]
	v_mfma_f32_16x16x32_bf16 v[120:123], v[176:179], v[242:245], v[120:123]
	v_mfma_f32_16x16x32_bf16 v[124:127], v[176:179], v[246:249], v[124:127]
	s_add_u32 m0, s8, 0x0
	ds_read_b128 v[176:179], v194 offset:38912
	v_mfma_f32_16x16x32_bf16 v[0:3], v[180:183], v[204:207], v[0:3]
	global_load_lds_dwordx4 v130, s[4:5]
	s_add_u32 m0, s8, 0x12000
	v_mfma_f32_16x16x32_bf16 v[4:7], v[180:183], v[222:225], v[4:7]
	global_load_lds_dwordx4 v134, s[6:7]
	s_add_u32 m0, s8, 0x400
	v_mfma_f32_16x16x32_bf16 v[8:11], v[180:183], v[226:229], v[8:11]
	global_load_lds_dwordx4 v131, s[4:5]
	s_add_u32 m0, s8, 0x12400
	v_mfma_f32_16x16x32_bf16 v[12:15], v[180:183], v[230:233], v[12:15]
	global_load_lds_dwordx4 v135, s[6:7]
	s_add_u32 m0, s8, 0x800
	v_mfma_f32_16x16x32_bf16 v[16:19], v[180:183], v[234:237], v[16:19]
	global_load_lds_dwordx4 v132, s[4:5]
	s_add_u32 m0, s8, 0x12800
	v_mfma_f32_16x16x32_bf16 v[20:23], v[180:183], v[238:241], v[20:23]
	global_load_lds_dwordx4 v136, s[6:7]
	s_add_u32 m0, s8, 0xc00
	v_mfma_f32_16x16x32_bf16 v[24:27], v[180:183], v[242:245], v[24:27]
	global_load_lds_dwordx4 v133, s[4:5]
	s_add_u32 m0, s8, 0x12c00
	v_mfma_f32_16x16x32_bf16 v[28:31], v[180:183], v[246:249], v[28:31]
	global_load_lds_dwordx4 v137, s[6:7]
	ds_read_b128 v[180:183], v194 offset:40960
	v_mfma_f32_16x16x32_bf16 v[32:35], v[200:203], v[204:207], v[32:35]
	s_add_u32 s4, s4, 0x80
	s_addc_u32 s5, s5, 0
	s_add_u32 s6, s6, 0x80
	s_addc_u32 s7, s7, 0
	ds_read_b128 v[204:207], v195 offset:36864
	v_mfma_f32_16x16x32_bf16 v[36:39], v[200:203], v[222:225], v[36:39]
	ds_read_b128 v[222:225], v195 offset:38912
	v_mfma_f32_16x16x32_bf16 v[40:43], v[200:203], v[226:229], v[40:43]
	ds_read_b128 v[226:229], v195 offset:40960
	v_mfma_f32_16x16x32_bf16 v[44:47], v[200:203], v[230:233], v[44:47]
	ds_read_b128 v[230:233], v195 offset:43008
	v_mfma_f32_16x16x32_bf16 v[48:51], v[200:203], v[234:237], v[48:51]
	ds_read_b128 v[234:237], v195 offset:45056
	v_mfma_f32_16x16x32_bf16 v[52:55], v[200:203], v[238:241], v[52:55]
	ds_read_b128 v[238:241], v195 offset:47104
	v_mfma_f32_16x16x32_bf16 v[56:59], v[200:203], v[242:245], v[56:59]
	ds_read_b128 v[242:245], v195 offset:49152
	v_mfma_f32_16x16x32_bf16 v[60:63], v[200:203], v[246:249], v[60:63]
	ds_read_b128 v[246:249], v195 offset:51200
	ds_read_b128 v[200:203], v194 offset:43008
	s_waitcnt lgkmcnt(8)
; DI void lds_barrier() { asm volatile("s_waitcnt lgkmcnt(0)\n\ts_barrier" ::: "memory"); }
; #define G_LOAD(RA, RB, KT) { size_t as_ = astep, bs_ = bstep; asm volatile("" : "+s"(as_), "+s"(bs_)); \
;       _Pragma("unroll") for (int i = 0; i < 4; ++i) { RA[i] = *(const u32x4*)(Ag + i * as_ + (KT) * 64); RB[i] = *(const u32x4*)(Bg + i * bs_ + (KT) * 64); } }
; DI void gemm_run(const GemmCfg c, char* smem, float* const g_h, u16* const g_hb, float* const g_out, const int final_out) {
;     ...
;     G_LOAD(ra0, rb0, 0);
;     __syncthreads();
;     G_STORE(ra0, rb0, 0);
;     G_LOAD(ra0, rb0, 1);
;     lds_barrier();
;     int kt = 0;
;     for (; kt + 3 < nk; kt += 2) {
;       K_STEP(0, 1, kt + 2, true, true);
;       lds_barrier();
;       K_STEP(1, 0, kt + 3, true, true);
;       lds_barrier();
;     }
	v_mfma_f32_16x16x32_bf16 v[64:67], v[160:163], v[204:207], v[64:67]
	s_waitcnt lgkmcnt(7)
	v_mfma_f32_16x16x32_bf16 v[68:71], v[160:163], v[222:225], v[68:71]
	s_waitcnt lgkmcnt(6)
	v_mfma_f32_16x16x32_bf16 v[72:75], v[160:163], v[226:229], v[72:75]
	s_waitcnt lgkmcnt(5)
	v_mfma_f32_16x16x32_bf16 v[76:79], v[160:163], v[230:233], v[76:79]
	s_waitcnt lgkmcnt(4)
	v_mfma_f32_16x16x32_bf16 v[80:83], v[160:163], v[234:237], v[80:83]
	s_waitcnt lgkmcnt(3)
	v_mfma_f32_16x16x32_bf16 v[84:87], v[160:163], v[238:241], v[84:87]
	s_waitcnt lgkmcnt(2)
	v_mfma_f32_16x16x32_bf16 v[88:91], v[160:163], v[242:245], v[88:91]
	s_waitcnt lgkmcnt(1)
	v_mfma_f32_16x16x32_bf16 v[92:95], v[160:163], v[246:249], v[92:95]
	ds_read_b128 v[160:163], v215 offset:36864
	v_mfma_f32_16x16x32_bf16 v[96:99], v[176:179], v[204:207], v[96:99]
	v_mfma_f32_16x16x32_bf16 v[100:103], v[176:179], v[222:225], v[100:103]
	v_mfma_f32_16x16x32_bf16 v[104:107], v[176:179], v[226:229], v[104:107]
	v_mfma_f32_16x16x32_bf16 v[108:111], v[176:179], v[230:233], v[108:111]
	v_mfma_f32_16x16x32_bf16 v[112:115], v[176:179], v[234:237], v[112:115]
	v_mfma_f32_16x16x32_bf16 v[116:119], v[176:179], v[238:241], v[116:119]
	v_mfma_f32_16x16x32_bf16 v[120:123], v[176:179], v[242:245], v[120:123]
	v_mfma_f32_16x16x32_bf16 v[124:127], v[176:179], v[246:249], v[124:127]
	ds_read_b128 v[176:179], v215 offset:38912
	v_mfma_f32_16x16x32_bf16 v[0:3], v[180:183], v[204:207], v[0:3]
	v_mfma_f32_16x16x32_bf16 v[4:7], v[180:183], v[222:225], v[4:7]
	v_mfma_f32_16x16x32_bf16 v[8:11], v[180:183], v[226:229], v[8:11]
	v_mfma_f32_16x16x32_bf16 v[12:15], v[180:183], v[230:233], v[12:15]
	v_mfma_f32_16x16x32_bf16 v[16:19], v[180:183], v[234:237], v[16:19]
	v_mfma_f32_16x16x32_bf16 v[20:23], v[180:183], v[238:241], v[20:23]
	v_mfma_f32_16x16x32_bf16 v[24:27], v[180:183], v[242:245], v[24:27]
	v_mfma_f32_16x16x32_bf16 v[28:31], v[180:183], v[246:249], v[28:31]
	ds_read_b128 v[180:183], v215 offset:40960
	s_waitcnt lgkmcnt(3)
	v_mfma_f32_16x16x32_bf16 v[32:35], v[200:203], v[204:207], v[32:35]
	ds_read_b128 v[204:207], v197 offset:36864
	v_mfma_f32_16x16x32_bf16 v[36:39], v[200:203], v[222:225], v[36:39]
	ds_read_b128 v[222:225], v197 offset:38912
	v_mfma_f32_16x16x32_bf16 v[40:43], v[200:203], v[226:229], v[40:43]
	ds_read_b128 v[226:229], v197 offset:40960
	v_mfma_f32_16x16x32_bf16 v[44:47], v[200:203], v[230:233], v[44:47]
	ds_read_b128 v[230:233], v197 offset:43008
	v_mfma_f32_16x16x32_bf16 v[48:51], v[200:203], v[234:237], v[48:51]
	ds_read_b128 v[234:237], v197 offset:45056
	v_mfma_f32_16x16x32_bf16 v[52:55], v[200:203], v[238:241], v[52:55]
	ds_read_b128 v[238:241], v197 offset:47104
	v_mfma_f32_16x16x32_bf16 v[56:59], v[200:203], v[242:245], v[56:59]
	ds_read_b128 v[242:245], v197 offset:49152
	v_mfma_f32_16x16x32_bf16 v[60:63], v[200:203], v[246:249], v[60:63]
	ds_read_b128 v[246:249], v197 offset:51200
	ds_read_b128 v[200:203], v215 offset:43008
	s_waitcnt lgkmcnt(8)
	v_mfma_f32_16x16x32_bf16 v[64:67], v[160:163], v[204:207], v[64:67]
	s_waitcnt lgkmcnt(7)
	v_mfma_f32_16x16x32_bf16 v[68:71], v[160:163], v[222:225], v[68:71]
	s_waitcnt lgkmcnt(6)
	v_mfma_f32_16x16x32_bf16 v[72:75], v[160:163], v[226:229], v[72:75]
	s_waitcnt lgkmcnt(5)
	v_mfma_f32_16x16x32_bf16 v[76:79], v[160:163], v[230:233], v[76:79]
	s_waitcnt lgkmcnt(4)
	v_mfma_f32_16x16x32_bf16 v[80:83], v[160:163], v[234:237], v[80:83]
	s_waitcnt lgkmcnt(3)
	v_mfma_f32_16x16x32_bf16 v[84:87], v[160:163], v[238:241], v[84:87]
	s_waitcnt lgkmcnt(2)
	v_mfma_f32_16x16x32_bf16 v[88:91], v[160:163], v[242:245], v[88:91]
	s_waitcnt lgkmcnt(1)
	v_mfma_f32_16x16x32_bf16 v[92:95], v[160:163], v[246:249], v[92:95]
	s_waitcnt vmcnt(0) lgkmcnt(0)
	s_barrier
	ds_read_b128 v[160:163], v194
	v_mfma_f32_16x16x32_bf16 v[96:99], v[176:179], v[204:207], v[96:99]
	v_mfma_f32_16x16x32_bf16 v[100:103], v[176:179], v[222:225], v[100:103]
	v_mfma_f32_16x16x32_bf16 v[104:107], v[176:179], v[226:229], v[104:107]
	v_mfma_f32_16x16x32_bf16 v[108:111], v[176:179], v[230:233], v[108:111]
	v_mfma_f32_16x16x32_bf16 v[112:115], v[176:179], v[234:237], v[112:115]
	v_mfma_f32_16x16x32_bf16 v[116:119], v[176:179], v[238:241], v[116:119]
	v_mfma_f32_16x16x32_bf16 v[120:123], v[176:179], v[242:245], v[120:123]
	v_mfma_f32_16x16x32_bf16 v[124:127], v[176:179], v[246:249], v[124:127]
	s_add_u32 m0, s8, 0x9000
	ds_read_b128 v[176:179], v194 offset:2048
	v_mfma_f32_16x16x32_bf16 v[0:3], v[180:183], v[204:207], v[0:3]
	global_load_lds_dwordx4 v130, s[4:5]
	s_add_u32 m0, s8, 0x1b000
	v_mfma_f32_16x16x32_bf16 v[4:7], v[180:183], v[222:225], v[4:7]
	global_load_lds_dwordx4 v134, s[6:7]
	s_add_u32 m0, s8, 0x9400
	v_mfma_f32_16x16x32_bf16 v[8:11], v[180:183], v[226:229], v[8:11]
	global_load_lds_dwordx4 v131, s[4:5]
	s_add_u32 m0, s8, 0x1b400
	v_mfma_f32_16x16x32_bf16 v[12:15], v[180:183], v[230:233], v[12:15]
	global_load_lds_dwordx4 v135, s[6:7]
	s_add_u32 m0, s8, 0x9800
	v_mfma_f32_16x16x32_bf16 v[16:19], v[180:183], v[234:237], v[16:19]
	global_load_lds_dwordx4 v132, s[4:5]
	s_add_u32 m0, s8, 0x1b800
	v_mfma_f32_16x16x32_bf16 v[20:23], v[180:183], v[238:241], v[20:23]
	global_load_lds_dwordx4 v136, s[6:7]
	s_add_u32 m0, s8, 0x9c00
	v_mfma_f32_16x16x32_bf16 v[24:27], v[180:183], v[242:245], v[24:27]
	global_load_lds_dwordx4 v133, s[4:5]
	s_add_u32 m0, s8, 0x1bc00
	v_mfma_f32_16x16x32_bf16 v[28:31], v[180:183], v[246:249], v[28:31]
	global_load_lds_dwordx4 v137, s[6:7]
	ds_read_b128 v[180:183], v194 offset:4096
	v_mfma_f32_16x16x32_bf16 v[32:35], v[200:203], v[204:207], v[32:35]
	s_add_u32 s4, s4, 0x80
	s_addc_u32 s5, s5, 0
	s_add_u32 s6, s6, 0x80
	s_addc_u32 s7, s7, 0
	ds_read_b128 v[204:207], v195
	v_mfma_f32_16x16x32_bf16 v[36:39], v[200:203], v[222:225], v[36:39]
	ds_read_b128 v[222:225], v195 offset:2048
	v_mfma_f32_16x16x32_bf16 v[40:43], v[200:203], v[226:229], v[40:43]
	ds_read_b128 v[226:229], v195 offset:4096
	v_mfma_f32_16x16x32_bf16 v[44:47], v[200:203], v[230:233], v[44:47]
	ds_read_b128 v[230:233], v195 offset:6144
	v_mfma_f32_16x16x32_bf16 v[48:51], v[200:203], v[234:237], v[48:51]
	ds_read_b128 v[234:237], v195 offset:8192
	v_mfma_f32_16x16x32_bf16 v[52:55], v[200:203], v[238:241], v[52:55]
	ds_read_b128 v[238:241], v195 offset:10240
	v_mfma_f32_16x16x32_bf16 v[56:59], v[200:203], v[242:245], v[56:59]
	ds_read_b128 v[242:245], v195 offset:12288
	v_mfma_f32_16x16x32_bf16 v[60:63], v[200:203], v[246:249], v[60:63]
	ds_read_b128 v[246:249], v195 offset:14336
	ds_read_b128 v[200:203], v194 offset:6144
	s_add_i32 s1, s1, 2
	s_cmp_lt_i32 s1, s0
	s_cbranch_scc1 .Lgemm_kloop_nl
; DI void lds_barrier() { asm volatile("s_waitcnt lgkmcnt(0)\n\ts_barrier" ::: "memory"); }
; DI void gemm_run(const GemmCfg c, char* smem, float* const g_h, u16* const g_hb, float* const g_out, const int final_out) {
;     ...
;     K_STEP(0, 1, 0, true, false);
;     lds_barrier();
;     K_STEP(1, 0, 0, false, false);
;     lds_barrier();
	s_waitcnt lgkmcnt(8)
	v_mfma_f32_16x16x32_bf16 v[64:67], v[160:163], v[204:207], v[64:67]
	s_waitcnt lgkmcnt(7)
	v_mfma_f32_16x16x32_bf16 v[68:71], v[160:163], v[222:225], v[68:71]
	s_waitcnt lgkmcnt(6)
	v_mfma_f32_16x16x32_bf16 v[72:75], v[160:163], v[226:229], v[72:75]
	s_waitcnt lgkmcnt(5)
	v_mfma_f32_16x16x32_bf16 v[76:79], v[160:163], v[230:233], v[76:79]
	s_waitcnt lgkmcnt(4)
	v_mfma_f32_16x16x32_bf16 v[80:83], v[160:163], v[234:237], v[80:83]
	s_waitcnt lgkmcnt(3)
	v_mfma_f32_16x16x32_bf16 v[84:87], v[160:163], v[238:241], v[84:87]
	s_waitcnt lgkmcnt(2)
	v_mfma_f32_16x16x32_bf16 v[88:91], v[160:163], v[242:245], v[88:91]
	s_waitcnt lgkmcnt(1)
	v_mfma_f32_16x16x32_bf16 v[92:95], v[160:163], v[246:249], v[92:95]
	ds_read_b128 v[160:163], v215
	v_mfma_f32_16x16x32_bf16 v[96:99], v[176:179], v[204:207], v[96:99]
	v_mfma_f32_16x16x32_bf16 v[100:103], v[176:179], v[222:225], v[100:103]
	v_mfma_f32_16x16x32_bf16 v[104:107], v[176:179], v[226:229], v[104:107]
	v_mfma_f32_16x16x32_bf16 v[108:111], v[176:179], v[230:233], v[108:111]
	v_mfma_f32_16x16x32_bf16 v[112:115], v[176:179], v[234:237], v[112:115]
	v_mfma_f32_16x16x32_bf16 v[116:119], v[176:179], v[238:241], v[116:119]
	v_mfma_f32_16x16x32_bf16 v[120:123], v[176:179], v[242:245], v[120:123]
	v_mfma_f32_16x16x32_bf16 v[124:127], v[176:179], v[246:249], v[124:127]
	ds_read_b128 v[176:179], v215 offset:2048
	v_mfma_f32_16x16x32_bf16 v[0:3], v[180:183], v[204:207], v[0:3]
	v_mfma_f32_16x16x32_bf16 v[4:7], v[180:183], v[222:225], v[4:7]
	v_mfma_f32_16x16x32_bf16 v[8:11], v[180:183], v[226:229], v[8:11]
	v_mfma_f32_16x16x32_bf16 v[12:15], v[180:183], v[230:233], v[12:15]
	v_mfma_f32_16x16x32_bf16 v[16:19], v[180:183], v[234:237], v[16:19]
	v_mfma_f32_16x16x32_bf16 v[20:23], v[180:183], v[238:241], v[20:23]
	v_mfma_f32_16x16x32_bf16 v[24:27], v[180:183], v[242:245], v[24:27]
	v_mfma_f32_16x16x32_bf16 v[28:31], v[180:183], v[246:249], v[28:31]
	ds_read_b128 v[180:183], v215 offset:4096
	s_waitcnt lgkmcnt(3)
	v_mfma_f32_16x16x32_bf16 v[32:35], v[200:203], v[204:207], v[32:35]
	ds_read_b128 v[204:207], v197
	v_mfma_f32_16x16x32_bf16 v[36:39], v[200:203], v[222:225], v[36:39]
	ds_read_b128 v[222:225], v197 offset:2048
	v_mfma_f32_16x16x32_bf16 v[40:43], v[200:203], v[226:229], v[40:43]
	ds_read_b128 v[226:229], v197 offset:4096
	v_mfma_f32_16x16x32_bf16 v[44:47], v[200:203], v[230:233], v[44:47]
	ds_read_b128 v[230:233], v197 offset:6144
	v_mfma_f32_16x16x32_bf16 v[48:51], v[200:203], v[234:237], v[48:51]
	ds_read_b128 v[234:237], v197 offset:8192
	v_mfma_f32_16x16x32_bf16 v[52:55], v[200:203], v[238:241], v[52:55]
	ds_read_b128 v[238:241], v197 offset:10240
	v_mfma_f32_16x16x32_bf16 v[56:59], v[200:203], v[242:245], v[56:59]
	ds_read_b128 v[242:245], v197 offset:12288
	v_mfma_f32_16x16x32_bf16 v[60:63], v[200:203], v[246:249], v[60:63]
	ds_read_b128 v[246:249], v197 offset:14336
	ds_read_b128 v[200:203], v215 offset:6144
	s_waitcnt lgkmcnt(8)
	v_mfma_f32_16x16x32_bf16 v[64:67], v[160:163], v[204:207], v[64:67]
	s_waitcnt lgkmcnt(7)
	v_mfma_f32_16x16x32_bf16 v[68:71], v[160:163], v[222:225], v[68:71]
	s_waitcnt lgkmcnt(6)
	v_mfma_f32_16x16x32_bf16 v[72:75], v[160:163], v[226:229], v[72:75]
	s_waitcnt lgkmcnt(5)
	v_mfma_f32_16x16x32_bf16 v[76:79], v[160:163], v[230:233], v[76:79]
	s_waitcnt lgkmcnt(4)
	v_mfma_f32_16x16x32_bf16 v[80:83], v[160:163], v[234:237], v[80:83]
	s_waitcnt lgkmcnt(3)
	v_mfma_f32_16x16x32_bf16 v[84:87], v[160:163], v[238:241], v[84:87]
	s_waitcnt lgkmcnt(2)
	v_mfma_f32_16x16x32_bf16 v[88:91], v[160:163], v[242:245], v[88:91]
	s_waitcnt lgkmcnt(1)
	v_mfma_f32_16x16x32_bf16 v[92:95], v[160:163], v[246:249], v[92:95]
	s_waitcnt vmcnt(0) lgkmcnt(0)
	s_barrier
	ds_read_b128 v[160:163], v194 offset:36864
	v_mfma_f32_16x16x32_bf16 v[96:99], v[176:179], v[204:207], v[96:99]
	v_mfma_f32_16x16x32_bf16 v[100:103], v[176:179], v[222:225], v[100:103]
	v_mfma_f32_16x16x32_bf16 v[104:107], v[176:179], v[226:229], v[104:107]
	v_mfma_f32_16x16x32_bf16 v[108:111], v[176:179], v[230:233], v[108:111]
	v_mfma_f32_16x16x32_bf16 v[112:115], v[176:179], v[234:237], v[112:115]
	v_mfma_f32_16x16x32_bf16 v[116:119], v[176:179], v[238:241], v[116:119]
	v_mfma_f32_16x16x32_bf16 v[120:123], v[176:179], v[242:245], v[120:123]
	v_mfma_f32_16x16x32_bf16 v[124:127], v[176:179], v[246:249], v[124:127]
	ds_read_b128 v[176:179], v194 offset:38912
	v_mfma_f32_16x16x32_bf16 v[0:3], v[180:183], v[204:207], v[0:3]
	v_mfma_f32_16x16x32_bf16 v[4:7], v[180:183], v[222:225], v[4:7]
	v_mfma_f32_16x16x32_bf16 v[8:11], v[180:183], v[226:229], v[8:11]
	v_mfma_f32_16x16x32_bf16 v[12:15], v[180:183], v[230:233], v[12:15]
	v_mfma_f32_16x16x32_bf16 v[16:19], v[180:183], v[234:237], v[16:19]
	v_mfma_f32_16x16x32_bf16 v[20:23], v[180:183], v[238:241], v[20:23]
	v_mfma_f32_16x16x32_bf16 v[24:27], v[180:183], v[242:245], v[24:27]
	v_mfma_f32_16x16x32_bf16 v[28:31], v[180:183], v[246:249], v[28:31]
	ds_read_b128 v[180:183], v194 offset:40960
	v_mfma_f32_16x16x32_bf16 v[32:35], v[200:203], v[204:207], v[32:35]
	ds_read_b128 v[204:207], v195 offset:36864
	v_mfma_f32_16x16x32_bf16 v[36:39], v[200:203], v[222:225], v[36:39]
	ds_read_b128 v[222:225], v195 offset:38912
	v_mfma_f32_16x16x32_bf16 v[40:43], v[200:203], v[226:229], v[40:43]
	ds_read_b128 v[226:229], v195 offset:40960
	v_mfma_f32_16x16x32_bf16 v[44:47], v[200:203], v[230:233], v[44:47]
	ds_read_b128 v[230:233], v195 offset:43008
	v_mfma_f32_16x16x32_bf16 v[48:51], v[200:203], v[234:237], v[48:51]
	ds_read_b128 v[234:237], v195 offset:45056
	v_mfma_f32_16x16x32_bf16 v[52:55], v[200:203], v[238:241], v[52:55]
	ds_read_b128 v[238:241], v195 offset:47104
	v_mfma_f32_16x16x32_bf16 v[56:59], v[200:203], v[242:245], v[56:59]
	ds_read_b128 v[242:245], v195 offset:49152
	v_mfma_f32_16x16x32_bf16 v[60:63], v[200:203], v[246:249], v[60:63]
	ds_read_b128 v[246:249], v195 offset:51200
	ds_read_b128 v[200:203], v194 offset:43008
	s_waitcnt lgkmcnt(8)
; DI void lds_barrier() { asm volatile("s_waitcnt lgkmcnt(0)\n\ts_barrier" ::: "memory"); }
; DI void gemm_run(const GemmCfg c, char* smem, float* const g_h, u16* const g_hb, float* const g_out, const int final_out) {
;     ...
;     K_STEP(0, 1, 0, true, false);
;     lds_barrier();
;     K_STEP(1, 0, 0, false, false);
;     lds_barrier();
	v_mfma_f32_16x16x32_bf16 v[64:67], v[160:163], v[204:207], v[64:67]
	s_waitcnt lgkmcnt(7)
	v_mfma_f32_16x16x32_bf16 v[68:71], v[160:163], v[222:225], v[68:71]
	s_waitcnt lgkmcnt(6)
	v_mfma_f32_16x16x32_bf16 v[72:75], v[160:163], v[226:229], v[72:75]
	s_waitcnt lgkmcnt(5)
	v_mfma_f32_16x16x32_bf16 v[76:79], v[160:163], v[230:233], v[76:79]
	s_waitcnt lgkmcnt(4)
	v_mfma_f32_16x16x32_bf16 v[80:83], v[160:163], v[234:237], v[80:83]
	s_waitcnt lgkmcnt(3)
	v_mfma_f32_16x16x32_bf16 v[84:87], v[160:163], v[238:241], v[84:87]
	s_waitcnt lgkmcnt(2)
	v_mfma_f32_16x16x32_bf16 v[88:91], v[160:163], v[242:245], v[88:91]
	s_waitcnt lgkmcnt(1)
	v_mfma_f32_16x16x32_bf16 v[92:95], v[160:163], v[246:249], v[92:95]
	ds_read_b128 v[160:163], v215 offset:36864
	v_mfma_f32_16x16x32_bf16 v[96:99], v[176:179], v[204:207], v[96:99]
	v_mfma_f32_16x16x32_bf16 v[100:103], v[176:179], v[222:225], v[100:103]
	v_mfma_f32_16x16x32_bf16 v[104:107], v[176:179], v[226:229], v[104:107]
	v_mfma_f32_16x16x32_bf16 v[108:111], v[176:179], v[230:233], v[108:111]
	v_mfma_f32_16x16x32_bf16 v[112:115], v[176:179], v[234:237], v[112:115]
	v_mfma_f32_16x16x32_bf16 v[116:119], v[176:179], v[238:241], v[116:119]
	v_mfma_f32_16x16x32_bf16 v[120:123], v[176:179], v[242:245], v[120:123]
	v_mfma_f32_16x16x32_bf16 v[124:127], v[176:179], v[246:249], v[124:127]
	ds_read_b128 v[176:179], v215 offset:38912
	v_mfma_f32_16x16x32_bf16 v[0:3], v[180:183], v[204:207], v[0:3]
	v_mfma_f32_16x16x32_bf16 v[4:7], v[180:183], v[222:225], v[4:7]
	v_mfma_f32_16x16x32_bf16 v[8:11], v[180:183], v[226:229], v[8:11]
	v_mfma_f32_16x16x32_bf16 v[12:15], v[180:183], v[230:233], v[12:15]
	v_mfma_f32_16x16x32_bf16 v[16:19], v[180:183], v[234:237], v[16:19]
	v_mfma_f32_16x16x32_bf16 v[20:23], v[180:183], v[238:241], v[20:23]
	v_mfma_f32_16x16x32_bf16 v[24:27], v[180:183], v[242:245], v[24:27]
	v_mfma_f32_16x16x32_bf16 v[28:31], v[180:183], v[246:249], v[28:31]
	ds_read_b128 v[180:183], v215 offset:40960
	s_waitcnt lgkmcnt(3)
	v_mfma_f32_16x16x32_bf16 v[32:35], v[200:203], v[204:207], v[32:35]
	ds_read_b128 v[204:207], v197 offset:36864
	v_mfma_f32_16x16x32_bf16 v[36:39], v[200:203], v[222:225], v[36:39]
	ds_read_b128 v[222:225], v197 offset:38912
	v_mfma_f32_16x16x32_bf16 v[40:43], v[200:203], v[226:229], v[40:43]
	ds_read_b128 v[226:229], v197 offset:40960
	v_mfma_f32_16x16x32_bf16 v[44:47], v[200:203], v[230:233], v[44:47]
	ds_read_b128 v[230:233], v197 offset:43008
	v_mfma_f32_16x16x32_bf16 v[48:51], v[200:203], v[234:237], v[48:51]
	ds_read_b128 v[234:237], v197 offset:45056
	v_mfma_f32_16x16x32_bf16 v[52:55], v[200:203], v[238:241], v[52:55]
	ds_read_b128 v[238:241], v197 offset:47104
	v_mfma_f32_16x16x32_bf16 v[56:59], v[200:203], v[242:245], v[56:59]
	ds_read_b128 v[242:245], v197 offset:49152
	v_mfma_f32_16x16x32_bf16 v[60:63], v[200:203], v[246:249], v[60:63]
	ds_read_b128 v[246:249], v197 offset:51200
	ds_read_b128 v[200:203], v215 offset:43008
	s_waitcnt lgkmcnt(8)
	v_mfma_f32_16x16x32_bf16 v[64:67], v[160:163], v[204:207], v[64:67]
	s_waitcnt lgkmcnt(7)
	v_mfma_f32_16x16x32_bf16 v[68:71], v[160:163], v[222:225], v[68:71]
	s_waitcnt lgkmcnt(6)
	v_mfma_f32_16x16x32_bf16 v[72:75], v[160:163], v[226:229], v[72:75]
	s_waitcnt lgkmcnt(5)
	v_mfma_f32_16x16x32_bf16 v[76:79], v[160:163], v[230:233], v[76:79]
	s_waitcnt lgkmcnt(4)
	v_mfma_f32_16x16x32_bf16 v[80:83], v[160:163], v[234:237], v[80:83]
	s_waitcnt lgkmcnt(3)
	v_mfma_f32_16x16x32_bf16 v[84:87], v[160:163], v[238:241], v[84:87]
	s_waitcnt lgkmcnt(2)
	v_mfma_f32_16x16x32_bf16 v[88:91], v[160:163], v[242:245], v[88:91]
	s_waitcnt lgkmcnt(1)
	v_mfma_f32_16x16x32_bf16 v[92:95], v[160:163], v[246:249], v[92:95]
	v_mfma_f32_16x16x32_bf16 v[96:99], v[176:179], v[204:207], v[96:99]
	v_mfma_f32_16x16x32_bf16 v[100:103], v[176:179], v[222:225], v[100:103]
	v_mfma_f32_16x16x32_bf16 v[104:107], v[176:179], v[226:229], v[104:107]
	v_mfma_f32_16x16x32_bf16 v[108:111], v[176:179], v[230:233], v[108:111]
	v_mfma_f32_16x16x32_bf16 v[112:115], v[176:179], v[234:237], v[112:115]
	v_mfma_f32_16x16x32_bf16 v[116:119], v[176:179], v[238:241], v[116:119]
	v_mfma_f32_16x16x32_bf16 v[120:123], v[176:179], v[242:245], v[120:123]
	v_mfma_f32_16x16x32_bf16 v[124:127], v[176:179], v[246:249], v[124:127]
	v_mfma_f32_16x16x32_bf16 v[0:3], v[180:183], v[204:207], v[0:3]
	v_mfma_f32_16x16x32_bf16 v[4:7], v[180:183], v[222:225], v[4:7]
	v_mfma_f32_16x16x32_bf16 v[8:11], v[180:183], v[226:229], v[8:11]
	v_mfma_f32_16x16x32_bf16 v[12:15], v[180:183], v[230:233], v[12:15]
	v_mfma_f32_16x16x32_bf16 v[16:19], v[180:183], v[234:237], v[16:19]
	v_mfma_f32_16x16x32_bf16 v[20:23], v[180:183], v[238:241], v[20:23]
	v_mfma_f32_16x16x32_bf16 v[24:27], v[180:183], v[242:245], v[24:27]
	v_mfma_f32_16x16x32_bf16 v[28:31], v[180:183], v[246:249], v[28:31]
	s_waitcnt lgkmcnt(0)
	v_mfma_f32_16x16x32_bf16 v[32:35], v[200:203], v[204:207], v[32:35]
	v_mfma_f32_16x16x32_bf16 v[36:39], v[200:203], v[222:225], v[36:39]
	v_mfma_f32_16x16x32_bf16 v[40:43], v[200:203], v[226:229], v[40:43]
	v_mfma_f32_16x16x32_bf16 v[44:47], v[200:203], v[230:233], v[44:47]
	v_mfma_f32_16x16x32_bf16 v[48:51], v[200:203], v[234:237], v[48:51]
	v_mfma_f32_16x16x32_bf16 v[52:55], v[200:203], v[238:241], v[52:55]
	v_mfma_f32_16x16x32_bf16 v[56:59], v[200:203], v[242:245], v[56:59]
	v_mfma_f32_16x16x32_bf16 v[60:63], v[200:203], v[246:249], v[60:63]
	s_branch .Lgemm_kdone

; DI int crow(int i, int hh) { return (i & 3) + 8 * (i >> 2) + 4 * hh; }
; DI void epi_slab(const GemmCfg c, const f32x16 (&acc)[4], float* sW, const float* rss, const size_t row0, const int g, const int lane,
;                  float* const g_h, u16* const g_hb, float* const g_out, const int final_out) {
;   int ln_ = lane;
;   asm volatile("" : "+v"(ln_));
;   const int l31 = ln_ & 31, hh = ln_ >> 5;
; #pragma unroll
;   for (int nb = 0; nb < 4; ++nb)
; #pragma unroll
;     for (int i = 0; i < 16; ++i) sW[crow(i, hh) * 132 + nb * 32 + l31] = acc[nb][i];
;   asm volatile("s_waitcnt lgkmcnt(0)" ::: "memory");
;   const int K = c.K;
;   const float invK = 1.0f / (float)K;
;   if (c.epi == EPI_SWIGLU) {
; DI void gemm_run(const GemmCfg c, char* smem, float* const g_h, u16* const g_hb, float* const g_out, const int final_out) {
;     ...
;       const size_t row0 = (size_t)tm * 256 + wm * 64 + mb * 32;
;       if (row0 < (size_t)M) epi_slab(c, acc[mb], sW, s_rowss + wm * 64 + mb * 32, row0, tn * 2 + wn, lane, g_h, g_hb, g_out, final_out);
.LBB0_124:
	s_ashr_i32 s79, s78, 31
	s_lshl_b64 s[4:5], s[78:79], 8
	s_add_u32 s6, s4, s86
	s_addc_u32 s7, s5, s87
	s_lshl_b32 s1, s49, 1
	s_or_b32 s8, s1, s75
	s_lshl_b32 s64, s8, 7
	s_cmp_gt_i32 s8, 1
	s_cselect_b64 s[84:85], -1, 0
	s_cmp_gt_u32 s1, 3
	s_cselect_b64 s[26:27], -1, 0
	s_cmp_eq_u32 s8, 4
	s_cselect_b64 s[70:71], -1, 0
	s_cmp_lt_i32 s8, s20
	s_cselect_b64 s[72:73], -1, 0
	s_cmp_lt_i32 s8, 8
	s_cselect_b64 vcc, -1, 0
	v_mov_b32_e32 v128, 0x3e38aa3b
	v_cndmask_b32_e32 v130, 1.0, v128, vcc
	s_and_b64 s[8:9], vcc, exec
	s_waitcnt lgkmcnt(0)
	v_mov_b64_e32 v[128:129], 0x4080
	s_cselect_b32 s8, 0, 0x100
	v_cmp_lt_u64_e64 s[44:45], s[6:7], v[128:129]
	v_mov_b64_e32 v[128:129], 0x407f
	s_add_u32 s58, s66, s8
	v_cmp_gt_u64_e32 vcc, s[6:7], v[128:129]
	s_addc_u32 s59, s67, 0
	s_barrier
	s_cbranch_vccnz .LBB0_279
	s_cmp_eq_u32 s52, 2
	s_cbranch_scc1 .Lqkv2
	s_cmp_eq_u32 s52, 5
	s_cbranch_scc1 .Lqabs2
	s_cmp_eq_u32 s52, 4
	s_cbranch_scc1 .Lqidx2
	s_cmp_eq_u32 s52, 6
	s_cbranch_scc1 .Lplain2
	s_cmp_eq_u32 s52, 0
	s_cbranch_scc1 .Lswg2
	v_mov_b32_e32 v131, v185
	s_movk_i32 s8, 0x210
	v_ashrrev_i32_e32 v128, 5, v131
	v_and_b32_e32 v132, 31, v131
	v_mul_lo_u32 v133, v128, s8
	v_lshlrev_b32_e32 v129, 2, v132
	v_lshlrev_b32_e32 v134, 2, v133
	v_add3_u32 v129, s53, v129, v134
	v_lshrrev_b32_e32 v242, 4, v131
	v_mul_u32_u24_e32 v242, 0x840, v242
	v_and_b32_e32 v243, 15, v131
	v_lshl_add_u32 v242, v243, 2, v242
	v_add_u32_e32 v234, s53, v242
	v_add_u32_e32 v235, 0x210, v234
	v_add_u32_e32 v236, 0x420, v234
	v_add_u32_e32 v237, 0x630, v234
	v_add_u32_e32 v238, 0x2100, v234
	v_add_u32_e32 v239, 0x2310, v234
	v_add_u32_e32 v240, 0x2520, v234
	v_add_u32_e32 v241, 0x2730, v234
	ds_write2_b32 v234, v64, v68 offset1:16
	ds_write2_b32 v234, v72, v76 offset0:32 offset1:48
	ds_write2_b32 v234, v80, v84 offset0:64 offset1:80
	ds_write2_b32 v234, v88, v92 offset0:96 offset1:112
	ds_write2_b32 v235, v65, v69 offset1:16
	ds_write2_b32 v235, v73, v77 offset0:32 offset1:48
	ds_write2_b32 v235, v81, v85 offset0:64 offset1:80
	ds_write2_b32 v235, v89, v93 offset0:96 offset1:112
	ds_write2_b32 v236, v66, v70 offset1:16
	ds_write2_b32 v236, v74, v78 offset0:32 offset1:48
	ds_write2_b32 v236, v82, v86 offset0:64 offset1:80
	ds_write2_b32 v236, v90, v94 offset0:96 offset1:112
	ds_write2_b32 v237, v67, v71 offset1:16
	ds_write2_b32 v237, v75, v79 offset0:32 offset1:48
	ds_write2_b32 v237, v83, v87 offset0:64 offset1:80
	ds_write2_b32 v237, v91, v95 offset0:96 offset1:112
	ds_write2_b32 v238, v96, v100 offset1:16
	ds_write2_b32 v238, v104, v108 offset0:32 offset1:48
	ds_write2_b32 v238, v112, v116 offset0:64 offset1:80
	ds_write2_b32 v238, v120, v124 offset0:96 offset1:112
	ds_write2_b32 v239, v97, v101 offset1:16
	ds_write2_b32 v239, v105, v109 offset0:32 offset1:48
	ds_write2_b32 v239, v113, v117 offset0:64 offset1:80
	ds_write2_b32 v239, v121, v125 offset0:96 offset1:112
	ds_write2_b32 v240, v98, v102 offset1:16
	ds_write2_b32 v240, v106, v110 offset0:32 offset1:48
	ds_write2_b32 v240, v114, v118 offset0:64 offset1:80
	ds_write2_b32 v240, v122, v126 offset0:96 offset1:112
	ds_write2_b32 v241, v99, v103 offset1:16
	ds_write2_b32 v241, v107, v111 offset0:32 offset1:48
	ds_write2_b32 v241, v115, v119 offset0:64 offset1:80
	ds_write2_b32 v241, v123, v127 offset0:96 offset1:112
	v_add_u32_e32 v64, 0x3800, v129
	v_add_u32_e32 v65, 0x1000, v129
	v_add_u32_e32 v66, 0x1400, v129
	v_add_u32_e32 v67, 0x2000, v129
	v_add_u32_e32 v68, 0x2400, v129
	v_add_u32_e32 v70, 0x3400, v129
	v_add_u32_e32 v69, 0x3000, v129
	v_add_u32_e32 v71, 0x3600, v129
	s_waitcnt lgkmcnt(0)
	s_mov_b64 s[22:23], -1
	s_mov_b64 s[50:51], 0
	s_cmp_lt_i32 s52, 1
	s_mov_b64 s[14:15], 0
	s_cbranch_scc1 .LBB0_272
	s_cmp_eq_u32 s52, 1
	s_mov_b64 s[14:15], -1
	s_cbranch_scc0 .LBB0_192
; DI void epi_slab(const GemmCfg c, const f32x16 (&acc)[4], float* sW, const float* rss, const size_t row0, const int g, const int lane,
;                  float* const g_h, u16* const g_hb, float* const g_out, const int final_out) {
;     ...
;   } else if (c.epi == EPI_RESID) {
;     const int c4 = l31 * 4;
;     const int col = g * 128 + c4;
;     const float sc = (K == DFF ? 0.5f : 1.f);
; #pragma unroll
;     for (int hb_ = 0; hb_ < 2; ++hb_) {
;       f32x4 hv[8];
; #pragma unroll
;       for (int i8 = 0; i8 < 8; ++i8) hv[i8] = *(const f32x4*)(g_h + (row0 + hh + 2 * (hb_ * 8 + i8)) * D + col);
; #pragma unroll
;       for (int i8 = 0; i8 < 8; ++i8) {
;         const int r = hh + 2 * (hb_ * 8 + i8);
;         const size_t row = row0 + r;
;         f32x4 v = *(const f32x4*)(sW + r * 132 + c4);
;         f32x4 o = hv[i8] + v * sc;
;         *(f32x4*)(g_h + row * D + col) = o;
;         *(u32x2*)(g_hb + row * D + col) = MK2(pack2(o[0], o[1]), pack2(o[2], o[3]));
;         if (final_out) {
;           const int b = (int)(row / T), t = (int)(row % T);
;           if (t >= 16) *(f32x4*)(g_out + ((size_t)b * 2048 + (t - 16)) * D + col) = o;
;         }
;       }
	v_lshl_or_b32 v98, v132, 2, s64
	v_ashrrev_i32_e32 v129, 31, v128
	v_ashrrev_i32_e32 v99, 31, v98
	v_readlane_b32 s8, v254, 60
	v_lshl_add_u64 v[104:105], s[6:7], 0, v[128:129]
	v_lshlrev_b64 v[106:107], 2, v[98:99]
	v_readlane_b32 s9, v254, 61
	v_lshlrev_b64 v[64:65], 12, v[104:105]
	v_lshl_add_u32 v108, v132, 4, s53
	v_lshl_add_u64 v[96:97], s[8:9], 0, v[106:107]
	v_lshl_add_u64 v[102:103], v[96:97], 0, v[64:65]
	s_movk_i32 s8, 0x2000
	v_add_co_u32_e32 v64, vcc, s8, v102
	s_movk_i32 s8, 0x4000
	s_nop 0
	v_addc_co_u32_e32 v65, vcc, 0, v103, vcc
	global_load_dwordx4 v[92:95], v[102:103], off
	global_load_dwordx4 v[88:91], v[64:65], off
	v_add_co_u32_e32 v64, vcc, s8, v102
	s_movk_i32 s8, 0x6000
	s_nop 0
	v_addc_co_u32_e32 v65, vcc, 0, v103, vcc
	v_add_co_u32_e32 v66, vcc, s8, v102
	s_mov_b32 s8, 0x8000
	s_nop 0
	v_addc_co_u32_e32 v67, vcc, 0, v103, vcc
	global_load_dwordx4 v[84:87], v[64:65], off
	global_load_dwordx4 v[80:83], v[66:67], off
	v_add_co_u32_e32 v64, vcc, s8, v102
	s_mov_b32 s8, 0xa000
	s_nop 0
	v_addc_co_u32_e32 v65, vcc, 0, v103, vcc
	v_add_co_u32_e32 v66, vcc, s8, v102
	s_mov_b32 s8, 0xc000
	s_nop 0
	v_addc_co_u32_e32 v67, vcc, 0, v103, vcc
	global_load_dwordx4 v[76:79], v[64:65], off
	global_load_dwordx4 v[72:75], v[66:67], off
	v_add_co_u32_e32 v64, vcc, s8, v102
	s_mov_b32 s8, 0xe000
	s_nop 0
	v_addc_co_u32_e32 v65, vcc, 0, v103, vcc
	v_add_co_u32_e32 v66, vcc, s8, v102
	v_add_u32_e32 v100, v108, v133
	s_nop 0
	v_addc_co_u32_e32 v67, vcc, 0, v103, vcc
	global_load_dwordx4 v[68:71], v[64:65], off
	s_nop 0
	global_load_dwordx4 v[64:67], v[66:67], off
	v_readlane_b32 s8, v255, 3
	ds_read_b128 v[110:113], v100
	v_readlane_b32 s9, v255, 4
	v_mov_b32_e32 v171, v170
	s_waitcnt vmcnt(7) lgkmcnt(0)
	v_pk_fma_f32 v[94:95], v[170:171], v[112:113], v[94:95]
	v_lshl_add_u64 v[100:101], v[98:99], 1, s[8:9]
	v_mov_b32_e32 v148, 0x11f69000
	v_mov_b32_e32 v149, 0
	v_lshl_add_u64 v[146:147], v[148:149], 0, s[8:9]
	v_lshrrev_b32_e32 v148, 6, v98
	v_lshlrev_b32_e32 v148, 2, v148
	v_lshl_add_u64 v[146:147], v[146:147], 0, v[148:149]
	v_mov_b32_e32 v143, 0
	v_readlane_b32 s8, v252, 47
	v_readlane_b32 s9, v252, 48
	v_readlane_b32 s8, v255, 13
	v_readlane_b32 s9, v255, 14
	v_readlane_b32 s22, v252, 61
	v_readlane_b32 s23, v252, 62
	v_pk_fma_f32 v[92:93], v[172:173], v[110:111], v[92:93]
	v_lshlrev_b64 v[110:111], 11, v[104:105]
	v_cndmask_b32_e64 v109, 0, 1, s[8:9]
	v_lshl_add_u64 v[98:99], s[22:23], 0, v[106:107]
	v_cvt_pk_bf16_f32 v106, v92, v93
	v_cvt_pk_bf16_f32 v107, v94, v95
	v_lshrrev_b32_e32 v142, 5, v110
	v_lshl_add_u64 v[110:111], v[100:101], 0, v[110:111]
	v_cmp_ne_u32_e64 s[46:47], 1, v109
	s_andn2_b64 vcc, exec, s[8:9]
	v_readlane_b32 s10, v252, 49
	v_readlane_b32 s11, v252, 50
	v_readlane_b32 s12, v252, 51
	v_readlane_b32 s13, v252, 52
	v_readlane_b32 s14, v252, 53
	v_readlane_b32 s15, v252, 54
	v_readlane_b32 s16, v252, 55
	v_readlane_b32 s17, v252, 56
	v_readlane_b32 s18, v252, 57
	v_readlane_b32 s19, v252, 58
	v_readlane_b32 s20, v252, 59
	v_readlane_b32 s21, v252, 60
	global_store_dwordx4 v[102:103], v[92:95], off
	global_store_dwordx2 v[110:111], v[106:107], off
	v_mov_b32_e32 v141, 0
	v_dot2c_f32_bf16_e32 v141, v106, v106
	v_dot2c_f32_bf16_e32 v141, v107, v107
	s_nop 4
	v_add_f32_dpp v141, v141, v141 quad_perm:[1,0,3,2] row_mask:0xf bank_mask:0xf
	s_nop 1
	v_add_f32_dpp v141, v141, v141 quad_perm:[2,3,0,1] row_mask:0xf bank_mask:0xf
	s_nop 1
	v_add_f32_dpp v141, v141, v141 row_half_mirror row_mask:0xf bank_mask:0xf
	s_nop 1
	v_add_f32_dpp v141, v141, v141 row_mirror row_mask:0xf bank_mask:0xf
	v_lshl_add_u64 v[144:145], v[142:143], 0, v[146:147]
	global_store_dword v[144:145], v141, off
	s_cbranch_vccnz .LBB0_131
	s_mov_b32 s8, 0xe03f80ff
	v_mul_hi_u32 v164, v104, s8
	v_mad_u64_u32 v[106:107], s[14:15], v105, s8, v[164:165]
	v_mov_b32_e32 v164, v107
	v_mov_b32_e32 v107, v165
	s_mov_b32 s8, 0xfe03f80f
	v_mad_u64_u32 v[106:107], s[14:15], v104, s8, v[106:107]
	v_mov_b32_e32 v106, v107
	v_mov_b32_e32 v107, v165
	v_lshl_add_u64 v[106:107], v[164:165], 0, v[106:107]
	v_mad_u64_u32 v[106:107], s[14:15], v105, s8, v[106:107]
	v_alignbit_b32 v109, v107, v106, 11
	s_movk_i32 s8, 0x810
	v_mad_u64_u32 v[110:111], s[14:15], v109, s8, 0
	v_lshrrev_b32_e32 v109, 11, v107
	v_mad_u32_u24 v109, v109, s8, v111
	v_sub_co_u32_e32 v104, vcc, v104, v110
	s_nop 1
	v_subb_co_u32_e32 v105, vcc, v105, v109, vcc
	v_cmp_lt_u64_e32 vcc, 15, v[104:105]
	s_and_saveexec_b64 s[14:15], vcc
	s_cbranch_execz .LBB0_130
	v_lshrrev_b64 v[106:107], 11, v[106:107]
	v_mov_b32_e32 v110, v165
	v_mov_b32_e32 v111, v106
	v_ashrrev_i64 v[106:107], 21, v[110:111]
	v_add_u32_e32 v164, -16, v104
	v_lshl_add_u64 v[104:105], v[106:107], 0, v[164:165]
	v_lshlrev_b64 v[104:105], 12, v[104:105]
	v_lshl_add_u64 v[104:105], v[98:99], 0, v[104:105]
	global_store_dwordx4 v[104:105], v[92:95], off

; DI float shx(float v, int mask, int lane) { return __int_as_float(__builtin_amdgcn_ds_bpermute((lane ^ mask) << 2, __float_as_int(v))); }
; DI void epi_slab(const GemmCfg c, const f32x16 (&acc)[4], float* sW, const float* rss, const size_t row0, const int g, const int lane,
;                  float* const g_h, u16* const g_hb, float* const g_out, const int final_out) {
;     ...
;     const int c4 = l31 * 4;
;     const int col = g * 128 + c4;
; #pragma unroll 2
;     for (int it = 0; it < 16; ++it) {
;       const int r = hh + 2 * it;
;       const size_t row = row0 + r;
;       f32x4 v = *(const f32x4*)(sW + r * 132 + c4);
;       const float rs = c.use_rs ? rsqrtf(rss[r] * invK + 1e-6f) : 1.f;
;       if (c.epi == EPI_QKV) {
;         f32x4 x = v * rs;
;         float s = x[0] * x[0] + x[1] * x[1] + x[2] * x[2] + x[3] * x[3];
;         s += shx(s, 1, ln_); s += shx(s, 2, ln_); s += shx(s, 4, ln_); s += shx(s, 8, ln_);
;         if (g < c.nk_end) {
;           const float r2 = rsqrtf(s * (1.f / 64.f) + 1e-6f) * (g < 8 ? 0.125f * LOG2E : 1.f);
;           f32x4 gn = *(const f32x4*)(c.gain + (g < 8 ? 0 : 64) + (c4 & 63));
.Lqkv2:
	v_and_b32_e32 v222, 15, v185
	v_lshrrev_b32_e32 v223, 4, v185
	s_lshl_b32 s4, s86, 2
	s_add_i32 s4, s4, 0x24000
	v_lshl_add_u32 v224, v223, 4, s4
	ds_read_b128 v[226:229], v224
	ds_read_b128 v[230:233], v224 offset:64
	ds_read_b128 v[234:237], v224 offset:128
	ds_read_b128 v[238:241], v224 offset:192
	v_lshlrev_b32_e32 v206, 2, v222
	global_load_dword v132, v206, s[58:59]
	global_load_dword v134, v206, s[58:59] offset:64
	global_load_dword v136, v206, s[58:59] offset:128
	global_load_dword v138, v206, s[58:59] offset:192
	v_mul_u32_u24_e32 v198, 0x840, v223
	v_lshl_add_u32 v198, v222, 2, v198
	v_add_u32_e32 v198, s53, v198
	v_add_u32_e32 v199, 0x420, v198
	v_add_u32_e32 v200, 0x2100, v198
	v_add_u32_e32 v201, 0x2520, v198
	v_lshrrev_b32_e32 v202, 5, v185
	v_and_b32_e32 v206, 31, v185
	v_mul_u32_u24_e32 v204, 0x210, v202
	v_lshl_add_u32 v204, v206, 4, v204
	v_add_u32_e32 v250, s53, v204
	v_add_u32_e32 v204, s6, v202
	v_mul_lo_u32 v204, v204, s92
	v_lshl_add_u32 v206, v206, 2, s64
	v_lshl_add_u32 v204, v206, 1, v204
	v_mov_b32_e32 v205, 0
	v_lshl_add_u64 v[204:205], v[204:205], 0, s[56:57]
	v_mov_b32_e32 v202, v250
	v_mov_b32_e32 v250, 0x3c800000
	s_lshl_b32 s4, s92, 1
	s_mov_b64 s[8:9], 0
	s_waitcnt lgkmcnt(0)
	v_fmaak_f32 v226, v191, v226, 0x358637bd
	v_fmaak_f32 v227, v191, v227, 0x358637bd
	v_cmp_gt_f32_e32 vcc, s33, v226
	v_cmp_gt_f32_e64 s[14:15], s33, v227
	v_mul_f32_e32 v224, 0x4b800000, v226
	v_mul_f32_e32 v225, 0x4b800000, v227
	v_cndmask_b32_e32 v226, v226, v224, vcc
	v_cndmask_b32_e64 v227, v227, v225, s[14:15]
	v_rsq_f32_e32 v226, v226
	v_rsq_f32_e32 v227, v227
	s_nop 0
	v_mul_f32_e32 v224, 0x45800000, v226
	v_mul_f32_e32 v225, 0x45800000, v227
	v_cndmask_b32_e32 v226, v226, v224, vcc
	v_cndmask_b32_e64 v227, v227, v225, s[14:15]
	v_fmaak_f32 v228, v191, v228, 0x358637bd
	v_fmaak_f32 v229, v191, v229, 0x358637bd
	v_cmp_gt_f32_e32 vcc, s33, v228
	v_cmp_gt_f32_e64 s[14:15], s33, v229
	v_mul_f32_e32 v224, 0x4b800000, v228
	v_mul_f32_e32 v225, 0x4b800000, v229
	v_cndmask_b32_e32 v228, v228, v224, vcc
	v_cndmask_b32_e64 v229, v229, v225, s[14:15]
	v_rsq_f32_e32 v228, v228
	v_rsq_f32_e32 v229, v229
	s_nop 0
	v_mul_f32_e32 v224, 0x45800000, v228
	v_mul_f32_e32 v225, 0x45800000, v229
	v_cndmask_b32_e32 v228, v228, v224, vcc
	v_cndmask_b32_e64 v229, v229, v225, s[14:15]
	v_fmaak_f32 v230, v191, v230, 0x358637bd
	v_fmaak_f32 v231, v191, v231, 0x358637bd
	v_cmp_gt_f32_e32 vcc, s33, v230
	v_cmp_gt_f32_e64 s[14:15], s33, v231
	v_mul_f32_e32 v224, 0x4b800000, v230
	v_mul_f32_e32 v225, 0x4b800000, v231
	v_cndmask_b32_e32 v230, v230, v224, vcc
	v_cndmask_b32_e64 v231, v231, v225, s[14:15]
	v_rsq_f32_e32 v230, v230
	v_rsq_f32_e32 v231, v231
	s_nop 0
	v_mul_f32_e32 v224, 0x45800000, v230
	v_mul_f32_e32 v225, 0x45800000, v231
	v_cndmask_b32_e32 v230, v230, v224, vcc
	v_cndmask_b32_e64 v231, v231, v225, s[14:15]
	v_fmaak_f32 v232, v191, v232, 0x358637bd
	v_fmaak_f32 v233, v191, v233, 0x358637bd
	v_cmp_gt_f32_e32 vcc, s33, v232
	v_cmp_gt_f32_e64 s[14:15], s33, v233
	v_mul_f32_e32 v224, 0x4b800000, v232
	v_mul_f32_e32 v225, 0x4b800000, v233
	v_cndmask_b32_e32 v232, v232, v224, vcc
	v_cndmask_b32_e64 v233, v233, v225, s[14:15]
	v_rsq_f32_e32 v232, v232
	v_rsq_f32_e32 v233, v233
	s_nop 0
	v_mul_f32_e32 v224, 0x45800000, v232
	v_mul_f32_e32 v225, 0x45800000, v233
	v_cndmask_b32_e32 v232, v232, v224, vcc
	v_cndmask_b32_e64 v233, v233, v225, s[14:15]
	v_fmaak_f32 v234, v191, v234, 0x358637bd
	v_fmaak_f32 v235, v191, v235, 0x358637bd
	v_cmp_gt_f32_e32 vcc, s33, v234
	v_cmp_gt_f32_e64 s[14:15], s33, v235
	v_mul_f32_e32 v224, 0x4b800000, v234
	v_mul_f32_e32 v225, 0x4b800000, v235
	v_cndmask_b32_e32 v234, v234, v224, vcc
	v_cndmask_b32_e64 v235, v235, v225, s[14:15]
	v_rsq_f32_e32 v234, v234
	v_rsq_f32_e32 v235, v235
	s_nop 0
	v_mul_f32_e32 v224, 0x45800000, v234
	v_mul_f32_e32 v225, 0x45800000, v235
	v_cndmask_b32_e32 v234, v234, v224, vcc
	v_cndmask_b32_e64 v235, v235, v225, s[14:15]
	v_fmaak_f32 v236, v191, v236, 0x358637bd
	v_fmaak_f32 v237, v191, v237, 0x358637bd
	v_cmp_gt_f32_e32 vcc, s33, v236
	v_cmp_gt_f32_e64 s[14:15], s33, v237
	v_mul_f32_e32 v224, 0x4b800000, v236
	v_mul_f32_e32 v225, 0x4b800000, v237
	v_cndmask_b32_e32 v236, v236, v224, vcc
	v_cndmask_b32_e64 v237, v237, v225, s[14:15]
	v_rsq_f32_e32 v236, v236
	v_rsq_f32_e32 v237, v237
	s_nop 0
	v_mul_f32_e32 v224, 0x45800000, v236
	v_mul_f32_e32 v225, 0x45800000, v237
	v_cndmask_b32_e32 v236, v236, v224, vcc
	v_cndmask_b32_e64 v237, v237, v225, s[14:15]
	v_fmaak_f32 v238, v191, v238, 0x358637bd
	v_fmaak_f32 v239, v191, v239, 0x358637bd
	v_cmp_gt_f32_e32 vcc, s33, v238
	v_cmp_gt_f32_e64 s[14:15], s33, v239
	v_mul_f32_e32 v224, 0x4b800000, v238
	v_mul_f32_e32 v225, 0x4b800000, v239
	v_cndmask_b32_e32 v238, v238, v224, vcc
	v_cndmask_b32_e64 v239, v239, v225, s[14:15]
	v_rsq_f32_e32 v238, v238
	v_rsq_f32_e32 v239, v239
	s_nop 0
	v_mul_f32_e32 v224, 0x45800000, v238
	v_mul_f32_e32 v225, 0x45800000, v239
	v_cndmask_b32_e32 v238, v238, v224, vcc
	v_cndmask_b32_e64 v239, v239, v225, s[14:15]
	v_fmaak_f32 v240, v191, v240, 0x358637bd
	v_fmaak_f32 v241, v191, v241, 0x358637bd
	v_cmp_gt_f32_e32 vcc, s33, v240
	v_cmp_gt_f32_e64 s[14:15], s33, v241
	v_mul_f32_e32 v224, 0x4b800000, v240
	v_mul_f32_e32 v225, 0x4b800000, v241
	v_cndmask_b32_e32 v240, v240, v224, vcc
	v_cndmask_b32_e64 v241, v241, v225, s[14:15]
	v_rsq_f32_e32 v240, v240
	v_rsq_f32_e32 v241, v241
	s_nop 0
	v_mul_f32_e32 v224, 0x45800000, v240
	v_mul_f32_e32 v225, 0x45800000, v241
	v_cndmask_b32_e32 v240, v240, v224, vcc
	v_cndmask_b32_e64 v241, v241, v225, s[14:15]
	s_waitcnt vmcnt(0)
	v_pk_mul_f32 v[64:65], v[64:65], v[226:227]
	v_pk_mul_f32 v[66:67], v[66:67], v[228:229]
	v_pk_mul_f32 v[68:69], v[68:69], v[226:227]
	v_pk_mul_f32 v[70:71], v[70:71], v[228:229]
	v_pk_mul_f32 v[72:73], v[72:73], v[226:227]
	v_pk_mul_f32 v[74:75], v[74:75], v[228:229]
	v_pk_mul_f32 v[76:77], v[76:77], v[226:227]
	v_pk_mul_f32 v[78:79], v[78:79], v[228:229]
	v_pk_mul_f32 v[80:81], v[80:81], v[226:227]
	v_pk_mul_f32 v[82:83], v[82:83], v[228:229]
	v_pk_mul_f32 v[84:85], v[84:85], v[226:227]
	v_pk_mul_f32 v[86:87], v[86:87], v[228:229]
	v_pk_mul_f32 v[88:89], v[88:89], v[226:227]
	v_pk_mul_f32 v[90:91], v[90:91], v[228:229]
	v_pk_mul_f32 v[92:93], v[92:93], v[226:227]
	v_pk_mul_f32 v[94:95], v[94:95], v[228:229]
	s_and_b64 vcc, exec, s[72:73]
	s_cbranch_vccz .Lqkv2_plain0
; DI float shx(float v, int mask, int lane) { return __int_as_float(__builtin_amdgcn_ds_bpermute((lane ^ mask) << 2, __float_as_int(v))); }
; DI void epi_slab(const GemmCfg c, const f32x16 (&acc)[4], float* sW, const float* rss, const size_t row0, const int g, const int lane,
;                  float* const g_h, u16* const g_hb, float* const g_out, const int final_out) {
;     ...
;       if (c.epi == EPI_QKV) {
;         f32x4 x = v * rs;
;         float s = x[0] * x[0] + x[1] * x[1] + x[2] * x[2] + x[3] * x[3];
;         s += shx(s, 1, ln_); s += shx(s, 2, ln_); s += shx(s, 4, ln_); s += shx(s, 8, ln_);
;         if (g < c.nk_end) {
;           const float r2 = rsqrtf(s * (1.f / 64.f) + 1e-6f) * (g < 8 ? 0.125f * LOG2E : 1.f);
;           f32x4 gn = *(const f32x4*)(c.gain + (g < 8 ? 0 : 64) + (c4 & 63));
;           x = x * gn * r2;
;         }
	v_mul_f32_e32 v246, v64, v64
	v_mul_f32_e32 v247, v65, v65
	v_mul_f32_e32 v248, v66, v66
	v_mul_f32_e32 v249, v67, v67
	v_fmac_f32_e32 v246, v68, v68
	v_fmac_f32_e32 v247, v69, v69
	v_fmac_f32_e32 v248, v70, v70
	v_fmac_f32_e32 v249, v71, v71
	v_fmac_f32_e32 v246, v72, v72
	v_fmac_f32_e32 v247, v73, v73
	v_fmac_f32_e32 v248, v74, v74
	v_fmac_f32_e32 v249, v75, v75
	v_fmac_f32_e32 v246, v76, v76
	v_fmac_f32_e32 v247, v77, v77
	v_fmac_f32_e32 v248, v78, v78
	v_fmac_f32_e32 v249, v79, v79
	v_add_f32_dpp v246, v246, v246 quad_perm:[1,0,3,2] row_mask:0xf bank_mask:0xf
	v_add_f32_dpp v247, v247, v247 quad_perm:[1,0,3,2] row_mask:0xf bank_mask:0xf
	v_add_f32_dpp v248, v248, v248 quad_perm:[1,0,3,2] row_mask:0xf bank_mask:0xf
	v_add_f32_dpp v249, v249, v249 quad_perm:[1,0,3,2] row_mask:0xf bank_mask:0xf
	v_add_f32_dpp v246, v246, v246 quad_perm:[2,3,0,1] row_mask:0xf bank_mask:0xf
	v_add_f32_dpp v247, v247, v247 quad_perm:[2,3,0,1] row_mask:0xf bank_mask:0xf
	v_add_f32_dpp v248, v248, v248 quad_perm:[2,3,0,1] row_mask:0xf bank_mask:0xf
	v_add_f32_dpp v249, v249, v249 quad_perm:[2,3,0,1] row_mask:0xf bank_mask:0xf
	v_add_f32_dpp v246, v246, v246 row_half_mirror row_mask:0xf bank_mask:0xf
	v_add_f32_dpp v247, v247, v247 row_half_mirror row_mask:0xf bank_mask:0xf
	v_add_f32_dpp v248, v248, v248 row_half_mirror row_mask:0xf bank_mask:0xf
	v_add_f32_dpp v249, v249, v249 row_half_mirror row_mask:0xf bank_mask:0xf
	v_add_f32_dpp v246, v246, v246 row_mirror row_mask:0xf bank_mask:0xf
	v_add_f32_dpp v247, v247, v247 row_mirror row_mask:0xf bank_mask:0xf
	v_add_f32_dpp v248, v248, v248 row_mirror row_mask:0xf bank_mask:0xf
	v_add_f32_dpp v249, v249, v249 row_mirror row_mask:0xf bank_mask:0xf
	v_fmaak_f32 v246, v250, v246, 0x358637bd
	v_fmaak_f32 v247, v250, v247, 0x358637bd
	v_cmp_gt_f32_e32 vcc, s33, v246
	v_cmp_gt_f32_e64 s[14:15], s33, v247
	v_mul_f32_e32 v224, 0x4b800000, v246
	v_mul_f32_e32 v225, 0x4b800000, v247
	v_cndmask_b32_e32 v246, v246, v224, vcc
	v_cndmask_b32_e64 v247, v247, v225, s[14:15]
	v_rsq_f32_e32 v246, v246
	v_rsq_f32_e32 v247, v247
	s_nop 0
	v_mul_f32_e32 v224, 0x45800000, v246
	v_mul_f32_e32 v225, 0x45800000, v247
	v_cndmask_b32_e32 v246, v246, v224, vcc
	v_cndmask_b32_e64 v247, v247, v225, s[14:15]
	v_mul_f32_e32 v246, v130, v246
	v_mul_f32_e32 v247, v130, v247
	v_fmaak_f32 v248, v250, v248, 0x358637bd
	v_fmaak_f32 v249, v250, v249, 0x358637bd
	v_cmp_gt_f32_e32 vcc, s33, v248
	v_cmp_gt_f32_e64 s[14:15], s33, v249
	v_mul_f32_e32 v224, 0x4b800000, v248
	v_mul_f32_e32 v225, 0x4b800000, v249
	v_cndmask_b32_e32 v248, v248, v224, vcc
	v_cndmask_b32_e64 v249, v249, v225, s[14:15]
	v_rsq_f32_e32 v248, v248
	v_rsq_f32_e32 v249, v249
	s_nop 0
	v_mul_f32_e32 v224, 0x45800000, v248
	v_mul_f32_e32 v225, 0x45800000, v249
	v_cndmask_b32_e32 v248, v248, v224, vcc
	v_cndmask_b32_e64 v249, v249, v225, s[14:15]
	v_mul_f32_e32 v248, v130, v248
	v_mul_f32_e32 v249, v130, v249
	v_pk_mul_f32 v[64:65], v[64:65], v[246:247]
	v_pk_mul_f32 v[66:67], v[66:67], v[248:249]
	v_pk_mul_f32 v[64:65], v[64:65], v[132:133] op_sel_hi:[1,0]
	v_pk_mul_f32 v[66:67], v[66:67], v[132:133] op_sel_hi:[1,0]
	v_pk_mul_f32 v[68:69], v[68:69], v[246:247]
	v_pk_mul_f32 v[70:71], v[70:71], v[248:249]
	v_pk_mul_f32 v[68:69], v[68:69], v[134:135] op_sel_hi:[1,0]
	v_pk_mul_f32 v[70:71], v[70:71], v[134:135] op_sel_hi:[1,0]
	v_pk_mul_f32 v[72:73], v[72:73], v[246:247]
	v_pk_mul_f32 v[74:75], v[74:75], v[248:249]
	v_pk_mul_f32 v[72:73], v[72:73], v[136:137] op_sel_hi:[1,0]
	v_pk_mul_f32 v[74:75], v[74:75], v[136:137] op_sel_hi:[1,0]
	v_pk_mul_f32 v[76:77], v[76:77], v[246:247]
	v_pk_mul_f32 v[78:79], v[78:79], v[248:249]
	v_pk_mul_f32 v[76:77], v[76:77], v[138:139] op_sel_hi:[1,0]
	v_pk_mul_f32 v[78:79], v[78:79], v[138:139] op_sel_hi:[1,0]
	v_mul_f32_e32 v246, v80, v80
	v_mul_f32_e32 v247, v81, v81
	v_mul_f32_e32 v248, v82, v82
	v_mul_f32_e32 v249, v83, v83
	v_fmac_f32_e32 v246, v84, v84
	v_fmac_f32_e32 v247, v85, v85
	v_fmac_f32_e32 v248, v86, v86
	v_fmac_f32_e32 v249, v87, v87
	v_fmac_f32_e32 v246, v88, v88
	v_fmac_f32_e32 v247, v89, v89
	v_fmac_f32_e32 v248, v90, v90
	v_fmac_f32_e32 v249, v91, v91
	v_fmac_f32_e32 v246, v92, v92
	v_fmac_f32_e32 v247, v93, v93
	v_fmac_f32_e32 v248, v94, v94
	v_fmac_f32_e32 v249, v95, v95
	v_add_f32_dpp v246, v246, v246 quad_perm:[1,0,3,2] row_mask:0xf bank_mask:0xf
	v_add_f32_dpp v247, v247, v247 quad_perm:[1,0,3,2] row_mask:0xf bank_mask:0xf
	v_add_f32_dpp v248, v248, v248 quad_perm:[1,0,3,2] row_mask:0xf bank_mask:0xf
	v_add_f32_dpp v249, v249, v249 quad_perm:[1,0,3,2] row_mask:0xf bank_mask:0xf
	v_add_f32_dpp v246, v246, v246 quad_perm:[2,3,0,1] row_mask:0xf bank_mask:0xf
	v_add_f32_dpp v247, v247, v247 quad_perm:[2,3,0,1] row_mask:0xf bank_mask:0xf
	v_add_f32_dpp v248, v248, v248 quad_perm:[2,3,0,1] row_mask:0xf bank_mask:0xf
	v_add_f32_dpp v249, v249, v249 quad_perm:[2,3,0,1] row_mask:0xf bank_mask:0xf
	v_add_f32_dpp v246, v246, v246 row_half_mirror row_mask:0xf bank_mask:0xf
	v_add_f32_dpp v247, v247, v247 row_half_mirror row_mask:0xf bank_mask:0xf
	v_add_f32_dpp v248, v248, v248 row_half_mirror row_mask:0xf bank_mask:0xf
	v_add_f32_dpp v249, v249, v249 row_half_mirror row_mask:0xf bank_mask:0xf
	v_add_f32_dpp v246, v246, v246 row_mirror row_mask:0xf bank_mask:0xf
	v_add_f32_dpp v247, v247, v247 row_mirror row_mask:0xf bank_mask:0xf
	v_add_f32_dpp v248, v248, v248 row_mirror row_mask:0xf bank_mask:0xf
	v_add_f32_dpp v249, v249, v249 row_mirror row_mask:0xf bank_mask:0xf
	v_fmaak_f32 v246, v250, v246, 0x358637bd
	v_fmaak_f32 v247, v250, v247, 0x358637bd
	v_cmp_gt_f32_e32 vcc, s33, v246
	v_cmp_gt_f32_e64 s[14:15], s33, v247
; DI float shx(float v, int mask, int lane) { return __int_as_float(__builtin_amdgcn_ds_bpermute((lane ^ mask) << 2, __float_as_int(v))); }
; DI void epi_slab(const GemmCfg c, const f32x16 (&acc)[4], float* sW, const float* rss, const size_t row0, const int g, const int lane,
;                  float* const g_h, u16* const g_hb, float* const g_out, const int final_out) {
;     ...
;       if (c.epi == EPI_QKV) {
;         f32x4 x = v * rs;
;         float s = x[0] * x[0] + x[1] * x[1] + x[2] * x[2] + x[3] * x[3];
;         s += shx(s, 1, ln_); s += shx(s, 2, ln_); s += shx(s, 4, ln_); s += shx(s, 8, ln_);
;         if (g < c.nk_end) {
;           const float r2 = rsqrtf(s * (1.f / 64.f) + 1e-6f) * (g < 8 ? 0.125f * LOG2E : 1.f);
;           f32x4 gn = *(const f32x4*)(c.gain + (g < 8 ? 0 : 64) + (c4 & 63));
;           x = x * gn * r2;
;         }
	v_mul_f32_e32 v224, 0x4b800000, v246
	v_mul_f32_e32 v225, 0x4b800000, v247
	v_cndmask_b32_e32 v246, v246, v224, vcc
	v_cndmask_b32_e64 v247, v247, v225, s[14:15]
	v_rsq_f32_e32 v246, v246
	v_rsq_f32_e32 v247, v247
	s_nop 0
	v_mul_f32_e32 v224, 0x45800000, v246
	v_mul_f32_e32 v225, 0x45800000, v247
	v_cndmask_b32_e32 v246, v246, v224, vcc
	v_cndmask_b32_e64 v247, v247, v225, s[14:15]
	v_mul_f32_e32 v246, v130, v246
	v_mul_f32_e32 v247, v130, v247
	v_fmaak_f32 v248, v250, v248, 0x358637bd
	v_fmaak_f32 v249, v250, v249, 0x358637bd
	v_cmp_gt_f32_e32 vcc, s33, v248
	v_cmp_gt_f32_e64 s[14:15], s33, v249
	v_mul_f32_e32 v224, 0x4b800000, v248
	v_mul_f32_e32 v225, 0x4b800000, v249
	v_cndmask_b32_e32 v248, v248, v224, vcc
	v_cndmask_b32_e64 v249, v249, v225, s[14:15]
	v_rsq_f32_e32 v248, v248
	v_rsq_f32_e32 v249, v249
	s_nop 0
	v_mul_f32_e32 v224, 0x45800000, v248
	v_mul_f32_e32 v225, 0x45800000, v249
	v_cndmask_b32_e32 v248, v248, v224, vcc
	v_cndmask_b32_e64 v249, v249, v225, s[14:15]
	v_mul_f32_e32 v248, v130, v248
	v_mul_f32_e32 v249, v130, v249
	v_pk_mul_f32 v[80:81], v[80:81], v[246:247]
	v_pk_mul_f32 v[82:83], v[82:83], v[248:249]
	v_pk_mul_f32 v[80:81], v[80:81], v[132:133] op_sel_hi:[1,0]
	v_pk_mul_f32 v[82:83], v[82:83], v[132:133] op_sel_hi:[1,0]
	v_pk_mul_f32 v[84:85], v[84:85], v[246:247]
	v_pk_mul_f32 v[86:87], v[86:87], v[248:249]
	v_pk_mul_f32 v[84:85], v[84:85], v[134:135] op_sel_hi:[1,0]
	v_pk_mul_f32 v[86:87], v[86:87], v[134:135] op_sel_hi:[1,0]
	v_pk_mul_f32 v[88:89], v[88:89], v[246:247]
	v_pk_mul_f32 v[90:91], v[90:91], v[248:249]
	v_pk_mul_f32 v[88:89], v[88:89], v[136:137] op_sel_hi:[1,0]
	v_pk_mul_f32 v[90:91], v[90:91], v[136:137] op_sel_hi:[1,0]
	v_pk_mul_f32 v[92:93], v[92:93], v[246:247]
	v_pk_mul_f32 v[94:95], v[94:95], v[248:249]
	v_pk_mul_f32 v[92:93], v[92:93], v[138:139] op_sel_hi:[1,0]
	v_pk_mul_f32 v[94:95], v[94:95], v[138:139] op_sel_hi:[1,0]
.Lqkv2_plain0:
	ds_write2_b32 v198, v64, v65 offset0:0 offset1:132
	ds_write2_b32 v199, v66, v67 offset0:0 offset1:132
	ds_write2_b32 v198, v68, v69 offset0:16 offset1:148
	ds_write2_b32 v199, v70, v71 offset0:16 offset1:148
	ds_write2_b32 v198, v72, v73 offset0:32 offset1:164
	ds_write2_b32 v199, v74, v75 offset0:32 offset1:164
	ds_write2_b32 v198, v76, v77 offset0:48 offset1:180
	ds_write2_b32 v199, v78, v79 offset0:48 offset1:180
	ds_write2_b32 v198, v80, v81 offset0:64 offset1:196
	ds_write2_b32 v199, v82, v83 offset0:64 offset1:196
	ds_write2_b32 v198, v84, v85 offset0:80 offset1:212
	ds_write2_b32 v199, v86, v87 offset0:80 offset1:212
	ds_write2_b32 v198, v88, v89 offset0:96 offset1:228
	ds_write2_b32 v199, v90, v91 offset0:96 offset1:228
	ds_write2_b32 v198, v92, v93 offset0:112 offset1:244
	ds_write2_b32 v199, v94, v95 offset0:112 offset1:244
	v_pk_mul_f32 v[96:97], v[96:97], v[230:231]
	v_pk_mul_f32 v[98:99], v[98:99], v[232:233]
	v_pk_mul_f32 v[100:101], v[100:101], v[230:231]
	v_pk_mul_f32 v[102:103], v[102:103], v[232:233]
	v_pk_mul_f32 v[104:105], v[104:105], v[230:231]
	v_pk_mul_f32 v[106:107], v[106:107], v[232:233]
	v_pk_mul_f32 v[108:109], v[108:109], v[230:231]
	v_pk_mul_f32 v[110:111], v[110:111], v[232:233]
	v_pk_mul_f32 v[112:113], v[112:113], v[230:231]
	v_pk_mul_f32 v[114:115], v[114:115], v[232:233]
	v_pk_mul_f32 v[116:117], v[116:117], v[230:231]
	v_pk_mul_f32 v[118:119], v[118:119], v[232:233]
	v_pk_mul_f32 v[120:121], v[120:121], v[230:231]
	v_pk_mul_f32 v[122:123], v[122:123], v[232:233]
	v_pk_mul_f32 v[124:125], v[124:125], v[230:231]
	v_pk_mul_f32 v[126:127], v[126:127], v[232:233]
	s_and_b64 vcc, exec, s[72:73]
	s_cbranch_vccz .Lqkv2_plain1
	v_mul_f32_e32 v246, v96, v96
	v_mul_f32_e32 v247, v97, v97
	v_mul_f32_e32 v248, v98, v98
	v_mul_f32_e32 v249, v99, v99
	v_fmac_f32_e32 v246, v100, v100
	v_fmac_f32_e32 v247, v101, v101
	v_fmac_f32_e32 v248, v102, v102
	v_fmac_f32_e32 v249, v103, v103
	v_fmac_f32_e32 v246, v104, v104
	v_fmac_f32_e32 v247, v105, v105
	v_fmac_f32_e32 v248, v106, v106
	v_fmac_f32_e32 v249, v107, v107
	v_fmac_f32_e32 v246, v108, v108
	v_fmac_f32_e32 v247, v109, v109
	v_fmac_f32_e32 v248, v110, v110
	v_fmac_f32_e32 v249, v111, v111
	v_add_f32_dpp v246, v246, v246 quad_perm:[1,0,3,2] row_mask:0xf bank_mask:0xf
	v_add_f32_dpp v247, v247, v247 quad_perm:[1,0,3,2] row_mask:0xf bank_mask:0xf
	v_add_f32_dpp v248, v248, v248 quad_perm:[1,0,3,2] row_mask:0xf bank_mask:0xf
	v_add_f32_dpp v249, v249, v249 quad_perm:[1,0,3,2] row_mask:0xf bank_mask:0xf
	v_add_f32_dpp v246, v246, v246 quad_perm:[2,3,0,1] row_mask:0xf bank_mask:0xf
	v_add_f32_dpp v247, v247, v247 quad_perm:[2,3,0,1] row_mask:0xf bank_mask:0xf
	v_add_f32_dpp v248, v248, v248 quad_perm:[2,3,0,1] row_mask:0xf bank_mask:0xf
	v_add_f32_dpp v249, v249, v249 quad_perm:[2,3,0,1] row_mask:0xf bank_mask:0xf
	v_add_f32_dpp v246, v246, v246 row_half_mirror row_mask:0xf bank_mask:0xf
	v_add_f32_dpp v247, v247, v247 row_half_mirror row_mask:0xf bank_mask:0xf
	v_add_f32_dpp v248, v248, v248 row_half_mirror row_mask:0xf bank_mask:0xf
	v_add_f32_dpp v249, v249, v249 row_half_mirror row_mask:0xf bank_mask:0xf
	v_add_f32_dpp v246, v246, v246 row_mirror row_mask:0xf bank_mask:0xf
	v_add_f32_dpp v247, v247, v247 row_mirror row_mask:0xf bank_mask:0xf
	v_add_f32_dpp v248, v248, v248 row_mirror row_mask:0xf bank_mask:0xf
	v_add_f32_dpp v249, v249, v249 row_mirror row_mask:0xf bank_mask:0xf
	v_fmaak_f32 v246, v250, v246, 0x358637bd
	v_fmaak_f32 v247, v250, v247, 0x358637bd
	v_cmp_gt_f32_e32 vcc, s33, v246
	v_cmp_gt_f32_e64 s[14:15], s33, v247
	v_mul_f32_e32 v224, 0x4b800000, v246
	v_mul_f32_e32 v225, 0x4b800000, v247
	v_cndmask_b32_e32 v246, v246, v224, vcc
	v_cndmask_b32_e64 v247, v247, v225, s[14:15]
; DI float shx(float v, int mask, int lane) { return __int_as_float(__builtin_amdgcn_ds_bpermute((lane ^ mask) << 2, __float_as_int(v))); }
; DI void epi_slab(const GemmCfg c, const f32x16 (&acc)[4], float* sW, const float* rss, const size_t row0, const int g, const int lane,
;                  float* const g_h, u16* const g_hb, float* const g_out, const int final_out) {
;     ...
;       if (c.epi == EPI_QKV) {
;         f32x4 x = v * rs;
;         float s = x[0] * x[0] + x[1] * x[1] + x[2] * x[2] + x[3] * x[3];
;         s += shx(s, 1, ln_); s += shx(s, 2, ln_); s += shx(s, 4, ln_); s += shx(s, 8, ln_);
;         if (g < c.nk_end) {
;           const float r2 = rsqrtf(s * (1.f / 64.f) + 1e-6f) * (g < 8 ? 0.125f * LOG2E : 1.f);
;           f32x4 gn = *(const f32x4*)(c.gain + (g < 8 ? 0 : 64) + (c4 & 63));
;           x = x * gn * r2;
;         }
	v_rsq_f32_e32 v246, v246
	v_rsq_f32_e32 v247, v247
	s_nop 0
	v_mul_f32_e32 v224, 0x45800000, v246
	v_mul_f32_e32 v225, 0x45800000, v247
	v_cndmask_b32_e32 v246, v246, v224, vcc
	v_cndmask_b32_e64 v247, v247, v225, s[14:15]
	v_mul_f32_e32 v246, v130, v246
	v_mul_f32_e32 v247, v130, v247
	v_fmaak_f32 v248, v250, v248, 0x358637bd
	v_fmaak_f32 v249, v250, v249, 0x358637bd
	v_cmp_gt_f32_e32 vcc, s33, v248
	v_cmp_gt_f32_e64 s[14:15], s33, v249
	v_mul_f32_e32 v224, 0x4b800000, v248
	v_mul_f32_e32 v225, 0x4b800000, v249
	v_cndmask_b32_e32 v248, v248, v224, vcc
	v_cndmask_b32_e64 v249, v249, v225, s[14:15]
	v_rsq_f32_e32 v248, v248
	v_rsq_f32_e32 v249, v249
	s_nop 0
	v_mul_f32_e32 v224, 0x45800000, v248
	v_mul_f32_e32 v225, 0x45800000, v249
	v_cndmask_b32_e32 v248, v248, v224, vcc
	v_cndmask_b32_e64 v249, v249, v225, s[14:15]
	v_mul_f32_e32 v248, v130, v248
	v_mul_f32_e32 v249, v130, v249
	v_pk_mul_f32 v[96:97], v[96:97], v[246:247]
	v_pk_mul_f32 v[98:99], v[98:99], v[248:249]
	v_pk_mul_f32 v[96:97], v[96:97], v[132:133] op_sel_hi:[1,0]
	v_pk_mul_f32 v[98:99], v[98:99], v[132:133] op_sel_hi:[1,0]
	v_pk_mul_f32 v[100:101], v[100:101], v[246:247]
	v_pk_mul_f32 v[102:103], v[102:103], v[248:249]
	v_pk_mul_f32 v[100:101], v[100:101], v[134:135] op_sel_hi:[1,0]
	v_pk_mul_f32 v[102:103], v[102:103], v[134:135] op_sel_hi:[1,0]
	v_pk_mul_f32 v[104:105], v[104:105], v[246:247]
	v_pk_mul_f32 v[106:107], v[106:107], v[248:249]
	v_pk_mul_f32 v[104:105], v[104:105], v[136:137] op_sel_hi:[1,0]
	v_pk_mul_f32 v[106:107], v[106:107], v[136:137] op_sel_hi:[1,0]
	v_pk_mul_f32 v[108:109], v[108:109], v[246:247]
	v_pk_mul_f32 v[110:111], v[110:111], v[248:249]
	v_pk_mul_f32 v[108:109], v[108:109], v[138:139] op_sel_hi:[1,0]
	v_pk_mul_f32 v[110:111], v[110:111], v[138:139] op_sel_hi:[1,0]
	v_mul_f32_e32 v246, v112, v112
	v_mul_f32_e32 v247, v113, v113
	v_mul_f32_e32 v248, v114, v114
	v_mul_f32_e32 v249, v115, v115
	v_fmac_f32_e32 v246, v116, v116
	v_fmac_f32_e32 v247, v117, v117
	v_fmac_f32_e32 v248, v118, v118
	v_fmac_f32_e32 v249, v119, v119
	v_fmac_f32_e32 v246, v120, v120
	v_fmac_f32_e32 v247, v121, v121
	v_fmac_f32_e32 v248, v122, v122
	v_fmac_f32_e32 v249, v123, v123
	v_fmac_f32_e32 v246, v124, v124
	v_fmac_f32_e32 v247, v125, v125
	v_fmac_f32_e32 v248, v126, v126
	v_fmac_f32_e32 v249, v127, v127
	v_add_f32_dpp v246, v246, v246 quad_perm:[1,0,3,2] row_mask:0xf bank_mask:0xf
	v_add_f32_dpp v247, v247, v247 quad_perm:[1,0,3,2] row_mask:0xf bank_mask:0xf
	v_add_f32_dpp v248, v248, v248 quad_perm:[1,0,3,2] row_mask:0xf bank_mask:0xf
	v_add_f32_dpp v249, v249, v249 quad_perm:[1,0,3,2] row_mask:0xf bank_mask:0xf
	v_add_f32_dpp v246, v246, v246 quad_perm:[2,3,0,1] row_mask:0xf bank_mask:0xf
	v_add_f32_dpp v247, v247, v247 quad_perm:[2,3,0,1] row_mask:0xf bank_mask:0xf
	v_add_f32_dpp v248, v248, v248 quad_perm:[2,3,0,1] row_mask:0xf bank_mask:0xf
	v_add_f32_dpp v249, v249, v249 quad_perm:[2,3,0,1] row_mask:0xf bank_mask:0xf
	v_add_f32_dpp v246, v246, v246 row_half_mirror row_mask:0xf bank_mask:0xf
	v_add_f32_dpp v247, v247, v247 row_half_mirror row_mask:0xf bank_mask:0xf
	v_add_f32_dpp v248, v248, v248 row_half_mirror row_mask:0xf bank_mask:0xf
	v_add_f32_dpp v249, v249, v249 row_half_mirror row_mask:0xf bank_mask:0xf
	v_add_f32_dpp v246, v246, v246 row_mirror row_mask:0xf bank_mask:0xf
	v_add_f32_dpp v247, v247, v247 row_mirror row_mask:0xf bank_mask:0xf
	v_add_f32_dpp v248, v248, v248 row_mirror row_mask:0xf bank_mask:0xf
	v_add_f32_dpp v249, v249, v249 row_mirror row_mask:0xf bank_mask:0xf
	v_fmaak_f32 v246, v250, v246, 0x358637bd
	v_fmaak_f32 v247, v250, v247, 0x358637bd
	v_cmp_gt_f32_e32 vcc, s33, v246
	v_cmp_gt_f32_e64 s[14:15], s33, v247
	v_mul_f32_e32 v224, 0x4b800000, v246
	v_mul_f32_e32 v225, 0x4b800000, v247
	v_cndmask_b32_e32 v246, v246, v224, vcc
	v_cndmask_b32_e64 v247, v247, v225, s[14:15]
	v_rsq_f32_e32 v246, v246
	v_rsq_f32_e32 v247, v247
	s_nop 0
	v_mul_f32_e32 v224, 0x45800000, v246
	v_mul_f32_e32 v225, 0x45800000, v247
	v_cndmask_b32_e32 v246, v246, v224, vcc
	v_cndmask_b32_e64 v247, v247, v225, s[14:15]
	v_mul_f32_e32 v246, v130, v246
	v_mul_f32_e32 v247, v130, v247
	v_fmaak_f32 v248, v250, v248, 0x358637bd
	v_fmaak_f32 v249, v250, v249, 0x358637bd
	v_cmp_gt_f32_e32 vcc, s33, v248
	v_cmp_gt_f32_e64 s[14:15], s33, v249
	v_mul_f32_e32 v224, 0x4b800000, v248
	v_mul_f32_e32 v225, 0x4b800000, v249
	v_cndmask_b32_e32 v248, v248, v224, vcc
	v_cndmask_b32_e64 v249, v249, v225, s[14:15]
	v_rsq_f32_e32 v248, v248
	v_rsq_f32_e32 v249, v249
	s_nop 0
	v_mul_f32_e32 v224, 0x45800000, v248
	v_mul_f32_e32 v225, 0x45800000, v249
	v_cndmask_b32_e32 v248, v248, v224, vcc
	v_cndmask_b32_e64 v249, v249, v225, s[14:15]
	v_mul_f32_e32 v248, v130, v248
	v_mul_f32_e32 v249, v130, v249
	v_pk_mul_f32 v[112:113], v[112:113], v[246:247]
	v_pk_mul_f32 v[114:115], v[114:115], v[248:249]
	v_pk_mul_f32 v[112:113], v[112:113], v[132:133] op_sel_hi:[1,0]
	v_pk_mul_f32 v[114:115], v[114:115], v[132:133] op_sel_hi:[1,0]
	v_pk_mul_f32 v[116:117], v[116:117], v[246:247]
	v_pk_mul_f32 v[118:119], v[118:119], v[248:249]
	v_pk_mul_f32 v[116:117], v[116:117], v[134:135] op_sel_hi:[1,0]
	v_pk_mul_f32 v[118:119], v[118:119], v[134:135] op_sel_hi:[1,0]
	v_pk_mul_f32 v[120:121], v[120:121], v[246:247]
	v_pk_mul_f32 v[122:123], v[122:123], v[248:249]
	v_pk_mul_f32 v[120:121], v[120:121], v[136:137] op_sel_hi:[1,0]
	v_pk_mul_f32 v[122:123], v[122:123], v[136:137] op_sel_hi:[1,0]
	v_pk_mul_f32 v[124:125], v[124:125], v[246:247]
	v_pk_mul_f32 v[126:127], v[126:127], v[248:249]
	v_pk_mul_f32 v[124:125], v[124:125], v[138:139] op_sel_hi:[1,0]
	v_pk_mul_f32 v[126:127], v[126:127], v[138:139] op_sel_hi:[1,0]
; DI float shx(float v, int mask, int lane) { return __int_as_float(__builtin_amdgcn_ds_bpermute((lane ^ mask) << 2, __float_as_int(v))); }
; DI void epi_slab(const GemmCfg c, const f32x16 (&acc)[4], float* sW, const float* rss, const size_t row0, const int g, const int lane,
;                  float* const g_h, u16* const g_hb, float* const g_out, const int final_out) {
;     ...
;     const int c4 = l31 * 4;
;     const int col = g * 128 + c4;
; #pragma unroll 2
;     for (int it = 0; it < 16; ++it) {
;       const int r = hh + 2 * it;
;       const size_t row = row0 + r;
;       f32x4 v = *(const f32x4*)(sW + r * 132 + c4);
;       const float rs = c.use_rs ? rsqrtf(rss[r] * invK + 1e-6f) : 1.f;
;       if (c.epi == EPI_QKV) {
;         f32x4 x = v * rs;
;         float s = x[0] * x[0] + x[1] * x[1] + x[2] * x[2] + x[3] * x[3];
;         s += shx(s, 1, ln_); s += shx(s, 2, ln_); s += shx(s, 4, ln_); s += shx(s, 8, ln_);
;         if (g < c.nk_end) {
;           const float r2 = rsqrtf(s * (1.f / 64.f) + 1e-6f) * (g < 8 ? 0.125f * LOG2E : 1.f);
;           f32x4 gn = *(const f32x4*)(c.gain + (g < 8 ? 0 : 64) + (c4 & 63));
;           x = x * gn * r2;
;         }
;         *(u32x2*)(c.o16 + row * c.ldo + col) = MK2(pack2(x[0], x[1]), pack2(x[2], x[3]));
.Lqkv2_plain1:
	ds_write2_b32 v200, v96, v97 offset0:0 offset1:132
	ds_write2_b32 v201, v98, v99 offset0:0 offset1:132
	ds_write2_b32 v200, v100, v101 offset0:16 offset1:148
	ds_write2_b32 v201, v102, v103 offset0:16 offset1:148
	ds_write2_b32 v200, v104, v105 offset0:32 offset1:164
	ds_write2_b32 v201, v106, v107 offset0:32 offset1:164
	ds_write2_b32 v200, v108, v109 offset0:48 offset1:180
	ds_write2_b32 v201, v110, v111 offset0:48 offset1:180
	ds_write2_b32 v200, v112, v113 offset0:64 offset1:196
	ds_write2_b32 v201, v114, v115 offset0:64 offset1:196
	ds_write2_b32 v200, v116, v117 offset0:80 offset1:212
	ds_write2_b32 v201, v118, v119 offset0:80 offset1:212
	ds_write2_b32 v200, v120, v121 offset0:96 offset1:228
	ds_write2_b32 v201, v122, v123 offset0:96 offset1:228
	ds_write2_b32 v200, v124, v125 offset0:112 offset1:244
	ds_write2_b32 v201, v126, v127 offset0:112 offset1:244
	s_waitcnt lgkmcnt(0)
	ds_read_b128 v[64:67], v202
	ds_read_b128 v[68:71], v202 offset:1056
	ds_read_b128 v[72:75], v202 offset:2112
	ds_read_b128 v[76:79], v202 offset:3168
	ds_read_b128 v[80:83], v202 offset:4224
	ds_read_b128 v[84:87], v202 offset:5280
	ds_read_b128 v[88:91], v202 offset:6336
	ds_read_b128 v[92:95], v202 offset:7392
	ds_read_b128 v[96:99], v202 offset:8448
	s_waitcnt lgkmcnt(8)
	v_lshl_add_u64 v[206:207], v[204:205], 0, s[8:9]
	v_cvt_pk_bf16_f32 v64, v64, v65
	v_cvt_pk_bf16_f32 v65, v66, v67
	s_add_u32 s8, s8, s4
	s_addc_u32 s9, s9, 0
	global_store_dwordx2 v[206:207], v[64:65], off
	ds_read_b128 v[100:103], v202 offset:9504
	s_waitcnt lgkmcnt(8)
	v_lshl_add_u64 v[206:207], v[204:205], 0, s[8:9]
	v_cvt_pk_bf16_f32 v68, v68, v69
	v_cvt_pk_bf16_f32 v69, v70, v71
	s_add_u32 s8, s8, s4
	s_addc_u32 s9, s9, 0
	global_store_dwordx2 v[206:207], v[68:69], off
	ds_read_b128 v[104:107], v202 offset:10560
	s_waitcnt lgkmcnt(8)
	v_lshl_add_u64 v[206:207], v[204:205], 0, s[8:9]
	v_cvt_pk_bf16_f32 v72, v72, v73
	v_cvt_pk_bf16_f32 v73, v74, v75
	s_add_u32 s8, s8, s4
	s_addc_u32 s9, s9, 0
	global_store_dwordx2 v[206:207], v[72:73], off
	ds_read_b128 v[108:111], v202 offset:11616
	s_waitcnt lgkmcnt(8)
	v_lshl_add_u64 v[206:207], v[204:205], 0, s[8:9]
	v_cvt_pk_bf16_f32 v76, v76, v77
	v_cvt_pk_bf16_f32 v77, v78, v79
	s_add_u32 s8, s8, s4
	s_addc_u32 s9, s9, 0
	global_store_dwordx2 v[206:207], v[76:77], off
	ds_read_b128 v[112:115], v202 offset:12672
	s_waitcnt lgkmcnt(8)
	v_lshl_add_u64 v[206:207], v[204:205], 0, s[8:9]
	v_cvt_pk_bf16_f32 v80, v80, v81
	v_cvt_pk_bf16_f32 v81, v82, v83
	s_add_u32 s8, s8, s4
	s_addc_u32 s9, s9, 0
	global_store_dwordx2 v[206:207], v[80:81], off
	ds_read_b128 v[116:119], v202 offset:13728
	s_waitcnt lgkmcnt(8)
	v_lshl_add_u64 v[206:207], v[204:205], 0, s[8:9]
	v_cvt_pk_bf16_f32 v84, v84, v85
	v_cvt_pk_bf16_f32 v85, v86, v87
	s_add_u32 s8, s8, s4
	s_addc_u32 s9, s9, 0
	global_store_dwordx2 v[206:207], v[84:85], off
	ds_read_b128 v[120:123], v202 offset:14784
	s_waitcnt lgkmcnt(8)
	v_lshl_add_u64 v[206:207], v[204:205], 0, s[8:9]
	v_cvt_pk_bf16_f32 v88, v88, v89
	v_cvt_pk_bf16_f32 v89, v90, v91
	s_add_u32 s8, s8, s4
	s_addc_u32 s9, s9, 0
	global_store_dwordx2 v[206:207], v[88:89], off
	ds_read_b128 v[124:127], v202 offset:15840
	s_waitcnt lgkmcnt(8)
	v_lshl_add_u64 v[206:207], v[204:205], 0, s[8:9]
	v_cvt_pk_bf16_f32 v92, v92, v93
	v_cvt_pk_bf16_f32 v93, v94, v95
	s_add_u32 s8, s8, s4
	s_addc_u32 s9, s9, 0
	global_store_dwordx2 v[206:207], v[92:93], off
	s_waitcnt lgkmcnt(7)
	v_lshl_add_u64 v[206:207], v[204:205], 0, s[8:9]
	v_cvt_pk_bf16_f32 v96, v96, v97
	v_cvt_pk_bf16_f32 v97, v98, v99
	s_add_u32 s8, s8, s4
	s_addc_u32 s9, s9, 0
	global_store_dwordx2 v[206:207], v[96:97], off
	s_waitcnt lgkmcnt(6)
	v_lshl_add_u64 v[206:207], v[204:205], 0, s[8:9]
	v_cvt_pk_bf16_f32 v100, v100, v101
	v_cvt_pk_bf16_f32 v101, v102, v103
	s_add_u32 s8, s8, s4
	s_addc_u32 s9, s9, 0
	global_store_dwordx2 v[206:207], v[100:101], off
	s_waitcnt lgkmcnt(5)
	v_lshl_add_u64 v[206:207], v[204:205], 0, s[8:9]
	v_cvt_pk_bf16_f32 v104, v104, v105
	v_cvt_pk_bf16_f32 v105, v106, v107
	s_add_u32 s8, s8, s4
	s_addc_u32 s9, s9, 0
	global_store_dwordx2 v[206:207], v[104:105], off
	s_waitcnt lgkmcnt(4)
	v_lshl_add_u64 v[206:207], v[204:205], 0, s[8:9]
	v_cvt_pk_bf16_f32 v108, v108, v109
	v_cvt_pk_bf16_f32 v109, v110, v111
	s_add_u32 s8, s8, s4
	s_addc_u32 s9, s9, 0
	global_store_dwordx2 v[206:207], v[108:109], off
	s_waitcnt lgkmcnt(3)
	v_lshl_add_u64 v[206:207], v[204:205], 0, s[8:9]
	v_cvt_pk_bf16_f32 v112, v112, v113
	v_cvt_pk_bf16_f32 v113, v114, v115
	s_add_u32 s8, s8, s4
	s_addc_u32 s9, s9, 0
	global_store_dwordx2 v[206:207], v[112:113], off
	s_waitcnt lgkmcnt(2)
	v_lshl_add_u64 v[206:207], v[204:205], 0, s[8:9]
	v_cvt_pk_bf16_f32 v116, v116, v117
	v_cvt_pk_bf16_f32 v117, v118, v119
	s_add_u32 s8, s8, s4
	s_addc_u32 s9, s9, 0
	global_store_dwordx2 v[206:207], v[116:117], off
	s_waitcnt lgkmcnt(1)
	v_lshl_add_u64 v[206:207], v[204:205], 0, s[8:9]
	v_cvt_pk_bf16_f32 v120, v120, v121
	v_cvt_pk_bf16_f32 v121, v122, v123
	s_add_u32 s8, s8, s4
	s_addc_u32 s9, s9, 0
	global_store_dwordx2 v[206:207], v[120:121], off
	s_waitcnt lgkmcnt(0)
	v_lshl_add_u64 v[206:207], v[204:205], 0, s[8:9]
	v_cvt_pk_bf16_f32 v124, v124, v125
	v_cvt_pk_bf16_f32 v125, v126, v127
	s_add_u32 s8, s8, s4
	s_addc_u32 s9, s9, 0
	global_store_dwordx2 v[206:207], v[124:125], off
	v_pk_mul_f32 v[0:1], v[0:1], v[234:235]
	v_pk_mul_f32 v[2:3], v[2:3], v[236:237]
	v_pk_mul_f32 v[4:5], v[4:5], v[234:235]
	v_pk_mul_f32 v[6:7], v[6:7], v[236:237]
	v_pk_mul_f32 v[8:9], v[8:9], v[234:235]
	v_pk_mul_f32 v[10:11], v[10:11], v[236:237]
	v_pk_mul_f32 v[12:13], v[12:13], v[234:235]
	v_pk_mul_f32 v[14:15], v[14:15], v[236:237]
	v_pk_mul_f32 v[16:17], v[16:17], v[234:235]
	v_pk_mul_f32 v[18:19], v[18:19], v[236:237]
	v_pk_mul_f32 v[20:21], v[20:21], v[234:235]
	v_pk_mul_f32 v[22:23], v[22:23], v[236:237]
	v_pk_mul_f32 v[24:25], v[24:25], v[234:235]
	v_pk_mul_f32 v[26:27], v[26:27], v[236:237]
	v_pk_mul_f32 v[28:29], v[28:29], v[234:235]
	v_pk_mul_f32 v[30:31], v[30:31], v[236:237]
	s_and_b64 vcc, exec, s[72:73]
	s_cbranch_vccz .Lqkv2_plain2
; DI float shx(float v, int mask, int lane) { return __int_as_float(__builtin_amdgcn_ds_bpermute((lane ^ mask) << 2, __float_as_int(v))); }
; DI void epi_slab(const GemmCfg c, const f32x16 (&acc)[4], float* sW, const float* rss, const size_t row0, const int g, const int lane,
;                  float* const g_h, u16* const g_hb, float* const g_out, const int final_out) {
;     ...
;       if (c.epi == EPI_QKV) {
;         f32x4 x = v * rs;
;         float s = x[0] * x[0] + x[1] * x[1] + x[2] * x[2] + x[3] * x[3];
;         s += shx(s, 1, ln_); s += shx(s, 2, ln_); s += shx(s, 4, ln_); s += shx(s, 8, ln_);
;         if (g < c.nk_end) {
;           const float r2 = rsqrtf(s * (1.f / 64.f) + 1e-6f) * (g < 8 ? 0.125f * LOG2E : 1.f);
;           f32x4 gn = *(const f32x4*)(c.gain + (g < 8 ? 0 : 64) + (c4 & 63));
;           x = x * gn * r2;
;         }
;         *(u32x2*)(c.o16 + row * c.ldo + col) = MK2(pack2(x[0], x[1]), pack2(x[2], x[3]));
	v_mul_f32_e32 v246, v0, v0
	v_mul_f32_e32 v247, v1, v1
	v_mul_f32_e32 v248, v2, v2
	v_mul_f32_e32 v249, v3, v3
	v_fmac_f32_e32 v246, v4, v4
	v_fmac_f32_e32 v247, v5, v5
	v_fmac_f32_e32 v248, v6, v6
	v_fmac_f32_e32 v249, v7, v7
	v_fmac_f32_e32 v246, v8, v8
	v_fmac_f32_e32 v247, v9, v9
	v_fmac_f32_e32 v248, v10, v10
	v_fmac_f32_e32 v249, v11, v11
	v_fmac_f32_e32 v246, v12, v12
	v_fmac_f32_e32 v247, v13, v13
	v_fmac_f32_e32 v248, v14, v14
	v_fmac_f32_e32 v249, v15, v15
	v_add_f32_dpp v246, v246, v246 quad_perm:[1,0,3,2] row_mask:0xf bank_mask:0xf
	v_add_f32_dpp v247, v247, v247 quad_perm:[1,0,3,2] row_mask:0xf bank_mask:0xf
	v_add_f32_dpp v248, v248, v248 quad_perm:[1,0,3,2] row_mask:0xf bank_mask:0xf
	v_add_f32_dpp v249, v249, v249 quad_perm:[1,0,3,2] row_mask:0xf bank_mask:0xf
	v_add_f32_dpp v246, v246, v246 quad_perm:[2,3,0,1] row_mask:0xf bank_mask:0xf
	v_add_f32_dpp v247, v247, v247 quad_perm:[2,3,0,1] row_mask:0xf bank_mask:0xf
	v_add_f32_dpp v248, v248, v248 quad_perm:[2,3,0,1] row_mask:0xf bank_mask:0xf
	v_add_f32_dpp v249, v249, v249 quad_perm:[2,3,0,1] row_mask:0xf bank_mask:0xf
	v_add_f32_dpp v246, v246, v246 row_half_mirror row_mask:0xf bank_mask:0xf
	v_add_f32_dpp v247, v247, v247 row_half_mirror row_mask:0xf bank_mask:0xf
	v_add_f32_dpp v248, v248, v248 row_half_mirror row_mask:0xf bank_mask:0xf
	v_add_f32_dpp v249, v249, v249 row_half_mirror row_mask:0xf bank_mask:0xf
	v_add_f32_dpp v246, v246, v246 row_mirror row_mask:0xf bank_mask:0xf
	v_add_f32_dpp v247, v247, v247 row_mirror row_mask:0xf bank_mask:0xf
	v_add_f32_dpp v248, v248, v248 row_mirror row_mask:0xf bank_mask:0xf
	v_add_f32_dpp v249, v249, v249 row_mirror row_mask:0xf bank_mask:0xf
	v_fmaak_f32 v246, v250, v246, 0x358637bd
	v_fmaak_f32 v247, v250, v247, 0x358637bd
	v_cmp_gt_f32_e32 vcc, s33, v246
	v_cmp_gt_f32_e64 s[14:15], s33, v247
	v_mul_f32_e32 v224, 0x4b800000, v246
	v_mul_f32_e32 v225, 0x4b800000, v247
	v_cndmask_b32_e32 v246, v246, v224, vcc
	v_cndmask_b32_e64 v247, v247, v225, s[14:15]
	v_rsq_f32_e32 v246, v246
	v_rsq_f32_e32 v247, v247
	s_nop 0
	v_mul_f32_e32 v224, 0x45800000, v246
	v_mul_f32_e32 v225, 0x45800000, v247
	v_cndmask_b32_e32 v246, v246, v224, vcc
	v_cndmask_b32_e64 v247, v247, v225, s[14:15]
	v_mul_f32_e32 v246, v130, v246
	v_mul_f32_e32 v247, v130, v247
	v_fmaak_f32 v248, v250, v248, 0x358637bd
	v_fmaak_f32 v249, v250, v249, 0x358637bd
	v_cmp_gt_f32_e32 vcc, s33, v248
	v_cmp_gt_f32_e64 s[14:15], s33, v249
	v_mul_f32_e32 v224, 0x4b800000, v248
	v_mul_f32_e32 v225, 0x4b800000, v249
	v_cndmask_b32_e32 v248, v248, v224, vcc
	v_cndmask_b32_e64 v249, v249, v225, s[14:15]
	v_rsq_f32_e32 v248, v248
	v_rsq_f32_e32 v249, v249
	s_nop 0
	v_mul_f32_e32 v224, 0x45800000, v248
	v_mul_f32_e32 v225, 0x45800000, v249
	v_cndmask_b32_e32 v248, v248, v224, vcc
	v_cndmask_b32_e64 v249, v249, v225, s[14:15]
	v_mul_f32_e32 v248, v130, v248
	v_mul_f32_e32 v249, v130, v249
	v_pk_mul_f32 v[0:1], v[0:1], v[246:247]
	v_pk_mul_f32 v[2:3], v[2:3], v[248:249]
	v_pk_mul_f32 v[0:1], v[0:1], v[132:133] op_sel_hi:[1,0]
	v_pk_mul_f32 v[2:3], v[2:3], v[132:133] op_sel_hi:[1,0]
	v_pk_mul_f32 v[4:5], v[4:5], v[246:247]
	v_pk_mul_f32 v[6:7], v[6:7], v[248:249]
	v_pk_mul_f32 v[4:5], v[4:5], v[134:135] op_sel_hi:[1,0]
	v_pk_mul_f32 v[6:7], v[6:7], v[134:135] op_sel_hi:[1,0]
	v_pk_mul_f32 v[8:9], v[8:9], v[246:247]
	v_pk_mul_f32 v[10:11], v[10:11], v[248:249]
	v_pk_mul_f32 v[8:9], v[8:9], v[136:137] op_sel_hi:[1,0]
	v_pk_mul_f32 v[10:11], v[10:11], v[136:137] op_sel_hi:[1,0]
	v_pk_mul_f32 v[12:13], v[12:13], v[246:247]
	v_pk_mul_f32 v[14:15], v[14:15], v[248:249]
	v_pk_mul_f32 v[12:13], v[12:13], v[138:139] op_sel_hi:[1,0]
	v_pk_mul_f32 v[14:15], v[14:15], v[138:139] op_sel_hi:[1,0]
	v_mul_f32_e32 v246, v16, v16
	v_mul_f32_e32 v247, v17, v17
	v_mul_f32_e32 v248, v18, v18
	v_mul_f32_e32 v249, v19, v19
	v_fmac_f32_e32 v246, v20, v20
	v_fmac_f32_e32 v247, v21, v21
	v_fmac_f32_e32 v248, v22, v22
	v_fmac_f32_e32 v249, v23, v23
	v_fmac_f32_e32 v246, v24, v24
	v_fmac_f32_e32 v247, v25, v25
	v_fmac_f32_e32 v248, v26, v26
	v_fmac_f32_e32 v249, v27, v27
	v_fmac_f32_e32 v246, v28, v28
	v_fmac_f32_e32 v247, v29, v29
	v_fmac_f32_e32 v248, v30, v30
	v_fmac_f32_e32 v249, v31, v31
	v_add_f32_dpp v246, v246, v246 quad_perm:[1,0,3,2] row_mask:0xf bank_mask:0xf
	v_add_f32_dpp v247, v247, v247 quad_perm:[1,0,3,2] row_mask:0xf bank_mask:0xf
	v_add_f32_dpp v248, v248, v248 quad_perm:[1,0,3,2] row_mask:0xf bank_mask:0xf
	v_add_f32_dpp v249, v249, v249 quad_perm:[1,0,3,2] row_mask:0xf bank_mask:0xf
	v_add_f32_dpp v246, v246, v246 quad_perm:[2,3,0,1] row_mask:0xf bank_mask:0xf
	v_add_f32_dpp v247, v247, v247 quad_perm:[2,3,0,1] row_mask:0xf bank_mask:0xf
	v_add_f32_dpp v248, v248, v248 quad_perm:[2,3,0,1] row_mask:0xf bank_mask:0xf
	v_add_f32_dpp v249, v249, v249 quad_perm:[2,3,0,1] row_mask:0xf bank_mask:0xf
	v_add_f32_dpp v246, v246, v246 row_half_mirror row_mask:0xf bank_mask:0xf
	v_add_f32_dpp v247, v247, v247 row_half_mirror row_mask:0xf bank_mask:0xf
	v_add_f32_dpp v248, v248, v248 row_half_mirror row_mask:0xf bank_mask:0xf
	v_add_f32_dpp v249, v249, v249 row_half_mirror row_mask:0xf bank_mask:0xf
	v_add_f32_dpp v246, v246, v246 row_mirror row_mask:0xf bank_mask:0xf
	v_add_f32_dpp v247, v247, v247 row_mirror row_mask:0xf bank_mask:0xf
	v_add_f32_dpp v248, v248, v248 row_mirror row_mask:0xf bank_mask:0xf
	v_add_f32_dpp v249, v249, v249 row_mirror row_mask:0xf bank_mask:0xf
	v_fmaak_f32 v246, v250, v246, 0x358637bd
	v_fmaak_f32 v247, v250, v247, 0x358637bd
	v_cmp_gt_f32_e32 vcc, s33, v246
	v_cmp_gt_f32_e64 s[14:15], s33, v247
	v_mul_f32_e32 v224, 0x4b800000, v246
	v_mul_f32_e32 v225, 0x4b800000, v247
; DI float shx(float v, int mask, int lane) { return __int_as_float(__builtin_amdgcn_ds_bpermute((lane ^ mask) << 2, __float_as_int(v))); }
; DI void epi_slab(const GemmCfg c, const f32x16 (&acc)[4], float* sW, const float* rss, const size_t row0, const int g, const int lane,
;                  float* const g_h, u16* const g_hb, float* const g_out, const int final_out) {
;     ...
;       if (c.epi == EPI_QKV) {
;         f32x4 x = v * rs;
;         float s = x[0] * x[0] + x[1] * x[1] + x[2] * x[2] + x[3] * x[3];
;         s += shx(s, 1, ln_); s += shx(s, 2, ln_); s += shx(s, 4, ln_); s += shx(s, 8, ln_);
;         if (g < c.nk_end) {
;           const float r2 = rsqrtf(s * (1.f / 64.f) + 1e-6f) * (g < 8 ? 0.125f * LOG2E : 1.f);
;           f32x4 gn = *(const f32x4*)(c.gain + (g < 8 ? 0 : 64) + (c4 & 63));
;           x = x * gn * r2;
;         }
;         *(u32x2*)(c.o16 + row * c.ldo + col) = MK2(pack2(x[0], x[1]), pack2(x[2], x[3]));
	v_cndmask_b32_e32 v246, v246, v224, vcc
	v_cndmask_b32_e64 v247, v247, v225, s[14:15]
	v_rsq_f32_e32 v246, v246
	v_rsq_f32_e32 v247, v247
	s_nop 0
	v_mul_f32_e32 v224, 0x45800000, v246
	v_mul_f32_e32 v225, 0x45800000, v247
	v_cndmask_b32_e32 v246, v246, v224, vcc
	v_cndmask_b32_e64 v247, v247, v225, s[14:15]
	v_mul_f32_e32 v246, v130, v246
	v_mul_f32_e32 v247, v130, v247
	v_fmaak_f32 v248, v250, v248, 0x358637bd
	v_fmaak_f32 v249, v250, v249, 0x358637bd
	v_cmp_gt_f32_e32 vcc, s33, v248
	v_cmp_gt_f32_e64 s[14:15], s33, v249
	v_mul_f32_e32 v224, 0x4b800000, v248
	v_mul_f32_e32 v225, 0x4b800000, v249
	v_cndmask_b32_e32 v248, v248, v224, vcc
	v_cndmask_b32_e64 v249, v249, v225, s[14:15]
	v_rsq_f32_e32 v248, v248
	v_rsq_f32_e32 v249, v249
	s_nop 0
	v_mul_f32_e32 v224, 0x45800000, v248
	v_mul_f32_e32 v225, 0x45800000, v249
	v_cndmask_b32_e32 v248, v248, v224, vcc
	v_cndmask_b32_e64 v249, v249, v225, s[14:15]
	v_mul_f32_e32 v248, v130, v248
	v_mul_f32_e32 v249, v130, v249
	v_pk_mul_f32 v[16:17], v[16:17], v[246:247]
	v_pk_mul_f32 v[18:19], v[18:19], v[248:249]
	v_pk_mul_f32 v[16:17], v[16:17], v[132:133] op_sel_hi:[1,0]
	v_pk_mul_f32 v[18:19], v[18:19], v[132:133] op_sel_hi:[1,0]
	v_pk_mul_f32 v[20:21], v[20:21], v[246:247]
	v_pk_mul_f32 v[22:23], v[22:23], v[248:249]
	v_pk_mul_f32 v[20:21], v[20:21], v[134:135] op_sel_hi:[1,0]
	v_pk_mul_f32 v[22:23], v[22:23], v[134:135] op_sel_hi:[1,0]
	v_pk_mul_f32 v[24:25], v[24:25], v[246:247]
	v_pk_mul_f32 v[26:27], v[26:27], v[248:249]
	v_pk_mul_f32 v[24:25], v[24:25], v[136:137] op_sel_hi:[1,0]
	v_pk_mul_f32 v[26:27], v[26:27], v[136:137] op_sel_hi:[1,0]
	v_pk_mul_f32 v[28:29], v[28:29], v[246:247]
	v_pk_mul_f32 v[30:31], v[30:31], v[248:249]
	v_pk_mul_f32 v[28:29], v[28:29], v[138:139] op_sel_hi:[1,0]
	v_pk_mul_f32 v[30:31], v[30:31], v[138:139] op_sel_hi:[1,0]
.Lqkv2_plain2:
	ds_write2_b32 v198, v0, v1 offset0:0 offset1:132
	ds_write2_b32 v199, v2, v3 offset0:0 offset1:132
	ds_write2_b32 v198, v4, v5 offset0:16 offset1:148
	ds_write2_b32 v199, v6, v7 offset0:16 offset1:148
	ds_write2_b32 v198, v8, v9 offset0:32 offset1:164
	ds_write2_b32 v199, v10, v11 offset0:32 offset1:164
	ds_write2_b32 v198, v12, v13 offset0:48 offset1:180
	ds_write2_b32 v199, v14, v15 offset0:48 offset1:180
	ds_write2_b32 v198, v16, v17 offset0:64 offset1:196
	ds_write2_b32 v199, v18, v19 offset0:64 offset1:196
	ds_write2_b32 v198, v20, v21 offset0:80 offset1:212
	ds_write2_b32 v199, v22, v23 offset0:80 offset1:212
	ds_write2_b32 v198, v24, v25 offset0:96 offset1:228
	ds_write2_b32 v199, v26, v27 offset0:96 offset1:228
	ds_write2_b32 v198, v28, v29 offset0:112 offset1:244
	ds_write2_b32 v199, v30, v31 offset0:112 offset1:244
	v_pk_mul_f32 v[32:33], v[32:33], v[238:239]
	v_pk_mul_f32 v[34:35], v[34:35], v[240:241]
	v_pk_mul_f32 v[36:37], v[36:37], v[238:239]
	v_pk_mul_f32 v[38:39], v[38:39], v[240:241]
	v_pk_mul_f32 v[40:41], v[40:41], v[238:239]
	v_pk_mul_f32 v[42:43], v[42:43], v[240:241]
	v_pk_mul_f32 v[44:45], v[44:45], v[238:239]
	v_pk_mul_f32 v[46:47], v[46:47], v[240:241]
	v_pk_mul_f32 v[48:49], v[48:49], v[238:239]
	v_pk_mul_f32 v[50:51], v[50:51], v[240:241]
	v_pk_mul_f32 v[52:53], v[52:53], v[238:239]
	v_pk_mul_f32 v[54:55], v[54:55], v[240:241]
	v_pk_mul_f32 v[56:57], v[56:57], v[238:239]
	v_pk_mul_f32 v[58:59], v[58:59], v[240:241]
	v_pk_mul_f32 v[60:61], v[60:61], v[238:239]
	v_pk_mul_f32 v[62:63], v[62:63], v[240:241]
	s_and_b64 vcc, exec, s[72:73]
	s_cbranch_vccz .Lqkv2_plain3
	v_mul_f32_e32 v246, v32, v32
	v_mul_f32_e32 v247, v33, v33
	v_mul_f32_e32 v248, v34, v34
	v_mul_f32_e32 v249, v35, v35
	v_fmac_f32_e32 v246, v36, v36
	v_fmac_f32_e32 v247, v37, v37
	v_fmac_f32_e32 v248, v38, v38
	v_fmac_f32_e32 v249, v39, v39
	v_fmac_f32_e32 v246, v40, v40
	v_fmac_f32_e32 v247, v41, v41
	v_fmac_f32_e32 v248, v42, v42
	v_fmac_f32_e32 v249, v43, v43
	v_fmac_f32_e32 v246, v44, v44
	v_fmac_f32_e32 v247, v45, v45
	v_fmac_f32_e32 v248, v46, v46
	v_fmac_f32_e32 v249, v47, v47
	v_add_f32_dpp v246, v246, v246 quad_perm:[1,0,3,2] row_mask:0xf bank_mask:0xf
	v_add_f32_dpp v247, v247, v247 quad_perm:[1,0,3,2] row_mask:0xf bank_mask:0xf
	v_add_f32_dpp v248, v248, v248 quad_perm:[1,0,3,2] row_mask:0xf bank_mask:0xf
	v_add_f32_dpp v249, v249, v249 quad_perm:[1,0,3,2] row_mask:0xf bank_mask:0xf
	v_add_f32_dpp v246, v246, v246 quad_perm:[2,3,0,1] row_mask:0xf bank_mask:0xf
	v_add_f32_dpp v247, v247, v247 quad_perm:[2,3,0,1] row_mask:0xf bank_mask:0xf
	v_add_f32_dpp v248, v248, v248 quad_perm:[2,3,0,1] row_mask:0xf bank_mask:0xf
	v_add_f32_dpp v249, v249, v249 quad_perm:[2,3,0,1] row_mask:0xf bank_mask:0xf
	v_add_f32_dpp v246, v246, v246 row_half_mirror row_mask:0xf bank_mask:0xf
	v_add_f32_dpp v247, v247, v247 row_half_mirror row_mask:0xf bank_mask:0xf
	v_add_f32_dpp v248, v248, v248 row_half_mirror row_mask:0xf bank_mask:0xf
	v_add_f32_dpp v249, v249, v249 row_half_mirror row_mask:0xf bank_mask:0xf
	v_add_f32_dpp v246, v246, v246 row_mirror row_mask:0xf bank_mask:0xf
	v_add_f32_dpp v247, v247, v247 row_mirror row_mask:0xf bank_mask:0xf
	v_add_f32_dpp v248, v248, v248 row_mirror row_mask:0xf bank_mask:0xf
	v_add_f32_dpp v249, v249, v249 row_mirror row_mask:0xf bank_mask:0xf
	v_fmaak_f32 v246, v250, v246, 0x358637bd
	v_fmaak_f32 v247, v250, v247, 0x358637bd
	v_cmp_gt_f32_e32 vcc, s33, v246
	v_cmp_gt_f32_e64 s[14:15], s33, v247
	v_mul_f32_e32 v224, 0x4b800000, v246
	v_mul_f32_e32 v225, 0x4b800000, v247
	v_cndmask_b32_e32 v246, v246, v224, vcc
	v_cndmask_b32_e64 v247, v247, v225, s[14:15]
; DI float shx(float v, int mask, int lane) { return __int_as_float(__builtin_amdgcn_ds_bpermute((lane ^ mask) << 2, __float_as_int(v))); }
; DI void epi_slab(const GemmCfg c, const f32x16 (&acc)[4], float* sW, const float* rss, const size_t row0, const int g, const int lane,
;                  float* const g_h, u16* const g_hb, float* const g_out, const int final_out) {
;     ...
;       if (c.epi == EPI_QKV) {
;         f32x4 x = v * rs;
;         float s = x[0] * x[0] + x[1] * x[1] + x[2] * x[2] + x[3] * x[3];
;         s += shx(s, 1, ln_); s += shx(s, 2, ln_); s += shx(s, 4, ln_); s += shx(s, 8, ln_);
;         if (g < c.nk_end) {
;           const float r2 = rsqrtf(s * (1.f / 64.f) + 1e-6f) * (g < 8 ? 0.125f * LOG2E : 1.f);
;           f32x4 gn = *(const f32x4*)(c.gain + (g < 8 ? 0 : 64) + (c4 & 63));
;           x = x * gn * r2;
;         }
;         *(u32x2*)(c.o16 + row * c.ldo + col) = MK2(pack2(x[0], x[1]), pack2(x[2], x[3]));
	v_rsq_f32_e32 v246, v246
	v_rsq_f32_e32 v247, v247
	s_nop 0
	v_mul_f32_e32 v224, 0x45800000, v246
	v_mul_f32_e32 v225, 0x45800000, v247
	v_cndmask_b32_e32 v246, v246, v224, vcc
	v_cndmask_b32_e64 v247, v247, v225, s[14:15]
	v_mul_f32_e32 v246, v130, v246
	v_mul_f32_e32 v247, v130, v247
	v_fmaak_f32 v248, v250, v248, 0x358637bd
	v_fmaak_f32 v249, v250, v249, 0x358637bd
	v_cmp_gt_f32_e32 vcc, s33, v248
	v_cmp_gt_f32_e64 s[14:15], s33, v249
	v_mul_f32_e32 v224, 0x4b800000, v248
	v_mul_f32_e32 v225, 0x4b800000, v249
	v_cndmask_b32_e32 v248, v248, v224, vcc
	v_cndmask_b32_e64 v249, v249, v225, s[14:15]
	v_rsq_f32_e32 v248, v248
	v_rsq_f32_e32 v249, v249
	s_nop 0
	v_mul_f32_e32 v224, 0x45800000, v248
	v_mul_f32_e32 v225, 0x45800000, v249
	v_cndmask_b32_e32 v248, v248, v224, vcc
	v_cndmask_b32_e64 v249, v249, v225, s[14:15]
	v_mul_f32_e32 v248, v130, v248
	v_mul_f32_e32 v249, v130, v249
	v_pk_mul_f32 v[32:33], v[32:33], v[246:247]
	v_pk_mul_f32 v[34:35], v[34:35], v[248:249]
	v_pk_mul_f32 v[32:33], v[32:33], v[132:133] op_sel_hi:[1,0]
	v_pk_mul_f32 v[34:35], v[34:35], v[132:133] op_sel_hi:[1,0]
	v_pk_mul_f32 v[36:37], v[36:37], v[246:247]
	v_pk_mul_f32 v[38:39], v[38:39], v[248:249]
	v_pk_mul_f32 v[36:37], v[36:37], v[134:135] op_sel_hi:[1,0]
	v_pk_mul_f32 v[38:39], v[38:39], v[134:135] op_sel_hi:[1,0]
	v_pk_mul_f32 v[40:41], v[40:41], v[246:247]
	v_pk_mul_f32 v[42:43], v[42:43], v[248:249]
	v_pk_mul_f32 v[40:41], v[40:41], v[136:137] op_sel_hi:[1,0]
	v_pk_mul_f32 v[42:43], v[42:43], v[136:137] op_sel_hi:[1,0]
	v_pk_mul_f32 v[44:45], v[44:45], v[246:247]
	v_pk_mul_f32 v[46:47], v[46:47], v[248:249]
	v_pk_mul_f32 v[44:45], v[44:45], v[138:139] op_sel_hi:[1,0]
	v_pk_mul_f32 v[46:47], v[46:47], v[138:139] op_sel_hi:[1,0]
	v_mul_f32_e32 v246, v48, v48
	v_mul_f32_e32 v247, v49, v49
	v_mul_f32_e32 v248, v50, v50
	v_mul_f32_e32 v249, v51, v51
	v_fmac_f32_e32 v246, v52, v52
	v_fmac_f32_e32 v247, v53, v53
	v_fmac_f32_e32 v248, v54, v54
	v_fmac_f32_e32 v249, v55, v55
	v_fmac_f32_e32 v246, v56, v56
	v_fmac_f32_e32 v247, v57, v57
	v_fmac_f32_e32 v248, v58, v58
	v_fmac_f32_e32 v249, v59, v59
	v_fmac_f32_e32 v246, v60, v60
	v_fmac_f32_e32 v247, v61, v61
	v_fmac_f32_e32 v248, v62, v62
	v_fmac_f32_e32 v249, v63, v63
	v_add_f32_dpp v246, v246, v246 quad_perm:[1,0,3,2] row_mask:0xf bank_mask:0xf
	v_add_f32_dpp v247, v247, v247 quad_perm:[1,0,3,2] row_mask:0xf bank_mask:0xf
	v_add_f32_dpp v248, v248, v248 quad_perm:[1,0,3,2] row_mask:0xf bank_mask:0xf
	v_add_f32_dpp v249, v249, v249 quad_perm:[1,0,3,2] row_mask:0xf bank_mask:0xf
	v_add_f32_dpp v246, v246, v246 quad_perm:[2,3,0,1] row_mask:0xf bank_mask:0xf
	v_add_f32_dpp v247, v247, v247 quad_perm:[2,3,0,1] row_mask:0xf bank_mask:0xf
	v_add_f32_dpp v248, v248, v248 quad_perm:[2,3,0,1] row_mask:0xf bank_mask:0xf
	v_add_f32_dpp v249, v249, v249 quad_perm:[2,3,0,1] row_mask:0xf bank_mask:0xf
	v_add_f32_dpp v246, v246, v246 row_half_mirror row_mask:0xf bank_mask:0xf
	v_add_f32_dpp v247, v247, v247 row_half_mirror row_mask:0xf bank_mask:0xf
	v_add_f32_dpp v248, v248, v248 row_half_mirror row_mask:0xf bank_mask:0xf
	v_add_f32_dpp v249, v249, v249 row_half_mirror row_mask:0xf bank_mask:0xf
	v_add_f32_dpp v246, v246, v246 row_mirror row_mask:0xf bank_mask:0xf
	v_add_f32_dpp v247, v247, v247 row_mirror row_mask:0xf bank_mask:0xf
	v_add_f32_dpp v248, v248, v248 row_mirror row_mask:0xf bank_mask:0xf
	v_add_f32_dpp v249, v249, v249 row_mirror row_mask:0xf bank_mask:0xf
	v_fmaak_f32 v246, v250, v246, 0x358637bd
	v_fmaak_f32 v247, v250, v247, 0x358637bd
	v_cmp_gt_f32_e32 vcc, s33, v246
	v_cmp_gt_f32_e64 s[14:15], s33, v247
	v_mul_f32_e32 v224, 0x4b800000, v246
	v_mul_f32_e32 v225, 0x4b800000, v247
	v_cndmask_b32_e32 v246, v246, v224, vcc
	v_cndmask_b32_e64 v247, v247, v225, s[14:15]
	v_rsq_f32_e32 v246, v246
	v_rsq_f32_e32 v247, v247
	s_nop 0
	v_mul_f32_e32 v224, 0x45800000, v246
	v_mul_f32_e32 v225, 0x45800000, v247
	v_cndmask_b32_e32 v246, v246, v224, vcc
	v_cndmask_b32_e64 v247, v247, v225, s[14:15]
	v_mul_f32_e32 v246, v130, v246
	v_mul_f32_e32 v247, v130, v247
	v_fmaak_f32 v248, v250, v248, 0x358637bd
	v_fmaak_f32 v249, v250, v249, 0x358637bd
	v_cmp_gt_f32_e32 vcc, s33, v248
	v_cmp_gt_f32_e64 s[14:15], s33, v249
	v_mul_f32_e32 v224, 0x4b800000, v248
	v_mul_f32_e32 v225, 0x4b800000, v249
	v_cndmask_b32_e32 v248, v248, v224, vcc
	v_cndmask_b32_e64 v249, v249, v225, s[14:15]
	v_rsq_f32_e32 v248, v248
	v_rsq_f32_e32 v249, v249
	s_nop 0
	v_mul_f32_e32 v224, 0x45800000, v248
	v_mul_f32_e32 v225, 0x45800000, v249
	v_cndmask_b32_e32 v248, v248, v224, vcc
	v_cndmask_b32_e64 v249, v249, v225, s[14:15]
	v_mul_f32_e32 v248, v130, v248
	v_mul_f32_e32 v249, v130, v249
	v_pk_mul_f32 v[48:49], v[48:49], v[246:247]
	v_pk_mul_f32 v[50:51], v[50:51], v[248:249]
	v_pk_mul_f32 v[48:49], v[48:49], v[132:133] op_sel_hi:[1,0]
	v_pk_mul_f32 v[50:51], v[50:51], v[132:133] op_sel_hi:[1,0]
	v_pk_mul_f32 v[52:53], v[52:53], v[246:247]
	v_pk_mul_f32 v[54:55], v[54:55], v[248:249]
	v_pk_mul_f32 v[52:53], v[52:53], v[134:135] op_sel_hi:[1,0]
	v_pk_mul_f32 v[54:55], v[54:55], v[134:135] op_sel_hi:[1,0]
	v_pk_mul_f32 v[56:57], v[56:57], v[246:247]
	v_pk_mul_f32 v[58:59], v[58:59], v[248:249]
	v_pk_mul_f32 v[56:57], v[56:57], v[136:137] op_sel_hi:[1,0]
	v_pk_mul_f32 v[58:59], v[58:59], v[136:137] op_sel_hi:[1,0]
	v_pk_mul_f32 v[60:61], v[60:61], v[246:247]
	v_pk_mul_f32 v[62:63], v[62:63], v[248:249]
	v_pk_mul_f32 v[60:61], v[60:61], v[138:139] op_sel_hi:[1,0]
	v_pk_mul_f32 v[62:63], v[62:63], v[138:139] op_sel_hi:[1,0]

; DI float shx(float v, int mask, int lane) { return __int_as_float(__builtin_amdgcn_ds_bpermute((lane ^ mask) << 2, __float_as_int(v))); }
; DI void epi_slab(const GemmCfg c, const f32x16 (&acc)[4], float* sW, const float* rss, const size_t row0, const int g, const int lane,
;                  float* const g_h, u16* const g_hb, float* const g_out, const int final_out) {
;     ...
;     for (int it = 0; it < 16; ++it) {
;       const int r = hh + 2 * it;
;       const size_t row = row0 + r;
;       f32x4 v = *(const f32x4*)(sW + r * 132 + c4);
;       const float rs = c.use_rs ? rsqrtf(rss[r] * invK + 1e-6f) : 1.f;
;     ...
;       } else if (c.epi == EPI_QABS) {
;         f32x4 x = v * rs;
;         float s = x[0] * x[0] + x[1] * x[1] + x[2] * x[2] + x[3] * x[3];
;         s += shx(s, 1, ln_); s += shx(s, 2, ln_); s += shx(s, 4, ln_); s += shx(s, 8, ln_); s += shx(s, 16, ln_);
;         if (l31 == 0) c.f0[row * 32 + g] = s;
;         *(u32x2*)(c.o16 + row * 4096 + col) = MK2(pack2(x[0], x[1]), pack2(x[2], x[3]));
.Lqabs2:
	v_and_b32_e32 v222, 15, v185
	v_lshrrev_b32_e32 v223, 4, v185
	s_lshl_b32 s4, s86, 2
	s_add_i32 s4, s4, 0x24000
	v_lshl_add_u32 v224, v223, 4, s4
	ds_read_b128 v[226:229], v224
	ds_read_b128 v[230:233], v224 offset:64
	ds_read_b128 v[234:237], v224 offset:128
	ds_read_b128 v[238:241], v224 offset:192
	v_mul_u32_u24_e32 v198, 0x840, v223
	v_lshl_add_u32 v198, v222, 2, v198
	v_add_u32_e32 v198, s53, v198
	v_add_u32_e32 v199, 0x420, v198
	v_add_u32_e32 v200, 0x2100, v198
	v_add_u32_e32 v201, 0x2520, v198
	v_lshrrev_b32_e32 v202, 5, v185
	v_and_b32_e32 v206, 31, v185
	v_mul_u32_u24_e32 v204, 0x210, v202
	v_lshl_add_u32 v204, v206, 4, v204
	v_add_u32_e32 v250, s53, v204
	v_add_u32_e32 v204, s6, v202
	v_lshlrev_b32_e32 v204, 13, v204
	v_lshl_add_u32 v206, v206, 2, s64
	v_lshl_add_u32 v204, v206, 1, v204
	v_mov_b32_e32 v205, 0
	v_lshl_add_u64 v[204:205], v[204:205], 0, s[56:57]
	v_mov_b32_e32 v202, v250
	v_mov_b32_e32 v250, 0x3c800000
	v_lshl_add_u32 v242, v223, 2, s6
	v_lshlrev_b32_e32 v242, 7, v242
	s_lshr_b32 s5, s64, 5
	v_add_u32_e32 v242, s5, v242
	v_mov_b32_e32 v243, 0
	v_lshl_add_u64 v[242:243], v[242:243], 0, s[76:77]
	v_mov_b32_e32 v244, 0x1000
	v_mov_b32_e32 v245, 0
	s_movk_i32 s4, 0x4000
	s_mov_b64 s[8:9], 0
	s_waitcnt lgkmcnt(0)
	v_fmaak_f32 v226, v191, v226, 0x358637bd
	v_fmaak_f32 v227, v191, v227, 0x358637bd
	v_cmp_gt_f32_e32 vcc, s33, v226
	v_cmp_gt_f32_e64 s[14:15], s33, v227
	v_mul_f32_e32 v224, 0x4b800000, v226
	v_mul_f32_e32 v225, 0x4b800000, v227
	v_cndmask_b32_e32 v226, v226, v224, vcc
	v_cndmask_b32_e64 v227, v227, v225, s[14:15]
	v_rsq_f32_e32 v226, v226
	v_rsq_f32_e32 v227, v227
	s_nop 0
	v_mul_f32_e32 v224, 0x45800000, v226
	v_mul_f32_e32 v225, 0x45800000, v227
	v_cndmask_b32_e32 v226, v226, v224, vcc
	v_cndmask_b32_e64 v227, v227, v225, s[14:15]
	v_fmaak_f32 v228, v191, v228, 0x358637bd
	v_fmaak_f32 v229, v191, v229, 0x358637bd
	v_cmp_gt_f32_e32 vcc, s33, v228
	v_cmp_gt_f32_e64 s[14:15], s33, v229
	v_mul_f32_e32 v224, 0x4b800000, v228
	v_mul_f32_e32 v225, 0x4b800000, v229
	v_cndmask_b32_e32 v228, v228, v224, vcc
	v_cndmask_b32_e64 v229, v229, v225, s[14:15]
	v_rsq_f32_e32 v228, v228
	v_rsq_f32_e32 v229, v229
	s_nop 0
	v_mul_f32_e32 v224, 0x45800000, v228
	v_mul_f32_e32 v225, 0x45800000, v229
	v_cndmask_b32_e32 v228, v228, v224, vcc
	v_cndmask_b32_e64 v229, v229, v225, s[14:15]
	v_fmaak_f32 v230, v191, v230, 0x358637bd
	v_fmaak_f32 v231, v191, v231, 0x358637bd
	v_cmp_gt_f32_e32 vcc, s33, v230
	v_cmp_gt_f32_e64 s[14:15], s33, v231
	v_mul_f32_e32 v224, 0x4b800000, v230
	v_mul_f32_e32 v225, 0x4b800000, v231
	v_cndmask_b32_e32 v230, v230, v224, vcc
	v_cndmask_b32_e64 v231, v231, v225, s[14:15]
	v_rsq_f32_e32 v230, v230
	v_rsq_f32_e32 v231, v231
	s_nop 0
	v_mul_f32_e32 v224, 0x45800000, v230
	v_mul_f32_e32 v225, 0x45800000, v231
	v_cndmask_b32_e32 v230, v230, v224, vcc
	v_cndmask_b32_e64 v231, v231, v225, s[14:15]
	v_fmaak_f32 v232, v191, v232, 0x358637bd
	v_fmaak_f32 v233, v191, v233, 0x358637bd
	v_cmp_gt_f32_e32 vcc, s33, v232
	v_cmp_gt_f32_e64 s[14:15], s33, v233
	v_mul_f32_e32 v224, 0x4b800000, v232
	v_mul_f32_e32 v225, 0x4b800000, v233
	v_cndmask_b32_e32 v232, v232, v224, vcc
	v_cndmask_b32_e64 v233, v233, v225, s[14:15]
	v_rsq_f32_e32 v232, v232
	v_rsq_f32_e32 v233, v233
	s_nop 0
	v_mul_f32_e32 v224, 0x45800000, v232
	v_mul_f32_e32 v225, 0x45800000, v233
	v_cndmask_b32_e32 v232, v232, v224, vcc
	v_cndmask_b32_e64 v233, v233, v225, s[14:15]
	v_fmaak_f32 v234, v191, v234, 0x358637bd
	v_fmaak_f32 v235, v191, v235, 0x358637bd
	v_cmp_gt_f32_e32 vcc, s33, v234
	v_cmp_gt_f32_e64 s[14:15], s33, v235
	v_mul_f32_e32 v224, 0x4b800000, v234
	v_mul_f32_e32 v225, 0x4b800000, v235
	v_cndmask_b32_e32 v234, v234, v224, vcc
	v_cndmask_b32_e64 v235, v235, v225, s[14:15]
	v_rsq_f32_e32 v234, v234
	v_rsq_f32_e32 v235, v235
	s_nop 0
	v_mul_f32_e32 v224, 0x45800000, v234
	v_mul_f32_e32 v225, 0x45800000, v235
	v_cndmask_b32_e32 v234, v234, v224, vcc
	v_cndmask_b32_e64 v235, v235, v225, s[14:15]
	v_fmaak_f32 v236, v191, v236, 0x358637bd
	v_fmaak_f32 v237, v191, v237, 0x358637bd
	v_cmp_gt_f32_e32 vcc, s33, v236
	v_cmp_gt_f32_e64 s[14:15], s33, v237
	v_mul_f32_e32 v224, 0x4b800000, v236
	v_mul_f32_e32 v225, 0x4b800000, v237
	v_cndmask_b32_e32 v236, v236, v224, vcc
	v_cndmask_b32_e64 v237, v237, v225, s[14:15]
	v_rsq_f32_e32 v236, v236
	v_rsq_f32_e32 v237, v237
	s_nop 0
	v_mul_f32_e32 v224, 0x45800000, v236
	v_mul_f32_e32 v225, 0x45800000, v237
	v_cndmask_b32_e32 v236, v236, v224, vcc
	v_cndmask_b32_e64 v237, v237, v225, s[14:15]
	v_fmaak_f32 v238, v191, v238, 0x358637bd
	v_fmaak_f32 v239, v191, v239, 0x358637bd
	v_cmp_gt_f32_e32 vcc, s33, v238
	v_cmp_gt_f32_e64 s[14:15], s33, v239
	v_mul_f32_e32 v224, 0x4b800000, v238
	v_mul_f32_e32 v225, 0x4b800000, v239
	v_cndmask_b32_e32 v238, v238, v224, vcc
	v_cndmask_b32_e64 v239, v239, v225, s[14:15]
	v_rsq_f32_e32 v238, v238
	v_rsq_f32_e32 v239, v239
	s_nop 0
	v_mul_f32_e32 v224, 0x45800000, v238
	v_mul_f32_e32 v225, 0x45800000, v239
	v_cndmask_b32_e32 v238, v238, v224, vcc
	v_cndmask_b32_e64 v239, v239, v225, s[14:15]
	v_fmaak_f32 v240, v191, v240, 0x358637bd
	v_fmaak_f32 v241, v191, v241, 0x358637bd
	v_cmp_gt_f32_e32 vcc, s33, v240
	v_cmp_gt_f32_e64 s[14:15], s33, v241
	v_mul_f32_e32 v224, 0x4b800000, v240
	v_mul_f32_e32 v225, 0x4b800000, v241
	v_cndmask_b32_e32 v240, v240, v224, vcc
	v_cndmask_b32_e64 v241, v241, v225, s[14:15]
	v_rsq_f32_e32 v240, v240
	v_rsq_f32_e32 v241, v241
	s_nop 0
	v_mul_f32_e32 v224, 0x45800000, v240
	v_mul_f32_e32 v225, 0x45800000, v241
	v_cndmask_b32_e32 v240, v240, v224, vcc
	v_cndmask_b32_e64 v241, v241, v225, s[14:15]
	v_pk_mul_f32 v[64:65], v[64:65], v[226:227]
; DI float shx(float v, int mask, int lane) { return __int_as_float(__builtin_amdgcn_ds_bpermute((lane ^ mask) << 2, __float_as_int(v))); }
; DI void epi_slab(const GemmCfg c, const f32x16 (&acc)[4], float* sW, const float* rss, const size_t row0, const int g, const int lane,
;                  float* const g_h, u16* const g_hb, float* const g_out, const int final_out) {
;     ...
;       } else if (c.epi == EPI_QABS) {
;         f32x4 x = v * rs;
;         float s = x[0] * x[0] + x[1] * x[1] + x[2] * x[2] + x[3] * x[3];
;         s += shx(s, 1, ln_); s += shx(s, 2, ln_); s += shx(s, 4, ln_); s += shx(s, 8, ln_); s += shx(s, 16, ln_);
;         if (l31 == 0) c.f0[row * 32 + g] = s;
;         *(u32x2*)(c.o16 + row * 4096 + col) = MK2(pack2(x[0], x[1]), pack2(x[2], x[3]));
	v_pk_mul_f32 v[66:67], v[66:67], v[228:229]
	v_pk_mul_f32 v[68:69], v[68:69], v[226:227]
	v_pk_mul_f32 v[70:71], v[70:71], v[228:229]
	v_pk_mul_f32 v[72:73], v[72:73], v[226:227]
	v_pk_mul_f32 v[74:75], v[74:75], v[228:229]
	v_pk_mul_f32 v[76:77], v[76:77], v[226:227]
	v_pk_mul_f32 v[78:79], v[78:79], v[228:229]
	v_pk_mul_f32 v[80:81], v[80:81], v[226:227]
	v_pk_mul_f32 v[82:83], v[82:83], v[228:229]
	v_pk_mul_f32 v[84:85], v[84:85], v[226:227]
	v_pk_mul_f32 v[86:87], v[86:87], v[228:229]
	v_pk_mul_f32 v[88:89], v[88:89], v[226:227]
	v_pk_mul_f32 v[90:91], v[90:91], v[228:229]
	v_pk_mul_f32 v[92:93], v[92:93], v[226:227]
	v_pk_mul_f32 v[94:95], v[94:95], v[228:229]
	v_mul_f32_e32 v246, v64, v64
	v_mul_f32_e32 v247, v65, v65
	v_mul_f32_e32 v248, v66, v66
	v_mul_f32_e32 v249, v67, v67
	v_fmac_f32_e32 v246, v68, v68
	v_fmac_f32_e32 v247, v69, v69
	v_fmac_f32_e32 v248, v70, v70
	v_fmac_f32_e32 v249, v71, v71
	v_fmac_f32_e32 v246, v72, v72
	v_fmac_f32_e32 v247, v73, v73
	v_fmac_f32_e32 v248, v74, v74
	v_fmac_f32_e32 v249, v75, v75
	v_fmac_f32_e32 v246, v76, v76
	v_fmac_f32_e32 v247, v77, v77
	v_fmac_f32_e32 v248, v78, v78
	v_fmac_f32_e32 v249, v79, v79
	v_fmac_f32_e32 v246, v80, v80
	v_fmac_f32_e32 v247, v81, v81
	v_fmac_f32_e32 v248, v82, v82
	v_fmac_f32_e32 v249, v83, v83
	v_fmac_f32_e32 v246, v84, v84
	v_fmac_f32_e32 v247, v85, v85
	v_fmac_f32_e32 v248, v86, v86
	v_fmac_f32_e32 v249, v87, v87
	v_fmac_f32_e32 v246, v88, v88
	v_fmac_f32_e32 v247, v89, v89
	v_fmac_f32_e32 v248, v90, v90
	v_fmac_f32_e32 v249, v91, v91
	v_fmac_f32_e32 v246, v92, v92
	v_fmac_f32_e32 v247, v93, v93
	v_fmac_f32_e32 v248, v94, v94
	v_fmac_f32_e32 v249, v95, v95
	v_add_f32_dpp v246, v246, v246 quad_perm:[1,0,3,2] row_mask:0xf bank_mask:0xf
	v_add_f32_dpp v247, v247, v247 quad_perm:[1,0,3,2] row_mask:0xf bank_mask:0xf
	v_add_f32_dpp v248, v248, v248 quad_perm:[1,0,3,2] row_mask:0xf bank_mask:0xf
	v_add_f32_dpp v249, v249, v249 quad_perm:[1,0,3,2] row_mask:0xf bank_mask:0xf
	v_add_f32_dpp v246, v246, v246 quad_perm:[2,3,0,1] row_mask:0xf bank_mask:0xf
	v_add_f32_dpp v247, v247, v247 quad_perm:[2,3,0,1] row_mask:0xf bank_mask:0xf
	v_add_f32_dpp v248, v248, v248 quad_perm:[2,3,0,1] row_mask:0xf bank_mask:0xf
	v_add_f32_dpp v249, v249, v249 quad_perm:[2,3,0,1] row_mask:0xf bank_mask:0xf
	v_add_f32_dpp v246, v246, v246 row_half_mirror row_mask:0xf bank_mask:0xf
	v_add_f32_dpp v247, v247, v247 row_half_mirror row_mask:0xf bank_mask:0xf
	v_add_f32_dpp v248, v248, v248 row_half_mirror row_mask:0xf bank_mask:0xf
	v_add_f32_dpp v249, v249, v249 row_half_mirror row_mask:0xf bank_mask:0xf
	v_add_f32_dpp v246, v246, v246 row_mirror row_mask:0xf bank_mask:0xf
	v_add_f32_dpp v247, v247, v247 row_mirror row_mask:0xf bank_mask:0xf
	v_add_f32_dpp v248, v248, v248 row_mirror row_mask:0xf bank_mask:0xf
	v_add_f32_dpp v249, v249, v249 row_mirror row_mask:0xf bank_mask:0xf
	global_store_dword v[242:243], v246, off offset:0
	global_store_dword v[242:243], v247, off offset:128
	global_store_dword v[242:243], v248, off offset:256
	global_store_dword v[242:243], v249, off offset:384
	ds_write2_b32 v198, v64, v65 offset0:0 offset1:132
	ds_write2_b32 v199, v66, v67 offset0:0 offset1:132
	ds_write2_b32 v198, v68, v69 offset0:16 offset1:148
	ds_write2_b32 v199, v70, v71 offset0:16 offset1:148
	ds_write2_b32 v198, v72, v73 offset0:32 offset1:164
	ds_write2_b32 v199, v74, v75 offset0:32 offset1:164
	ds_write2_b32 v198, v76, v77 offset0:48 offset1:180
	ds_write2_b32 v199, v78, v79 offset0:48 offset1:180
	ds_write2_b32 v198, v80, v81 offset0:64 offset1:196
	ds_write2_b32 v199, v82, v83 offset0:64 offset1:196
	ds_write2_b32 v198, v84, v85 offset0:80 offset1:212
	ds_write2_b32 v199, v86, v87 offset0:80 offset1:212
	ds_write2_b32 v198, v88, v89 offset0:96 offset1:228
	ds_write2_b32 v199, v90, v91 offset0:96 offset1:228
	ds_write2_b32 v198, v92, v93 offset0:112 offset1:244
	ds_write2_b32 v199, v94, v95 offset0:112 offset1:244
	v_pk_mul_f32 v[96:97], v[96:97], v[230:231]
	v_pk_mul_f32 v[98:99], v[98:99], v[232:233]
	v_pk_mul_f32 v[100:101], v[100:101], v[230:231]
	v_pk_mul_f32 v[102:103], v[102:103], v[232:233]
	v_pk_mul_f32 v[104:105], v[104:105], v[230:231]
	v_pk_mul_f32 v[106:107], v[106:107], v[232:233]
	v_pk_mul_f32 v[108:109], v[108:109], v[230:231]
	v_pk_mul_f32 v[110:111], v[110:111], v[232:233]
	v_pk_mul_f32 v[112:113], v[112:113], v[230:231]
	v_pk_mul_f32 v[114:115], v[114:115], v[232:233]
	v_pk_mul_f32 v[116:117], v[116:117], v[230:231]
	v_pk_mul_f32 v[118:119], v[118:119], v[232:233]
	v_pk_mul_f32 v[120:121], v[120:121], v[230:231]
	v_pk_mul_f32 v[122:123], v[122:123], v[232:233]
	v_pk_mul_f32 v[124:125], v[124:125], v[230:231]
	v_pk_mul_f32 v[126:127], v[126:127], v[232:233]
	v_mul_f32_e32 v246, v96, v96
	v_mul_f32_e32 v247, v97, v97
	v_mul_f32_e32 v248, v98, v98
	v_mul_f32_e32 v249, v99, v99
	v_fmac_f32_e32 v246, v100, v100
	v_fmac_f32_e32 v247, v101, v101
	v_fmac_f32_e32 v248, v102, v102
	v_fmac_f32_e32 v249, v103, v103
	v_fmac_f32_e32 v246, v104, v104
	v_fmac_f32_e32 v247, v105, v105
	v_fmac_f32_e32 v248, v106, v106
	v_fmac_f32_e32 v249, v107, v107
	v_fmac_f32_e32 v246, v108, v108
	v_fmac_f32_e32 v247, v109, v109
	v_fmac_f32_e32 v248, v110, v110
	v_fmac_f32_e32 v249, v111, v111
	v_fmac_f32_e32 v246, v112, v112
	v_fmac_f32_e32 v247, v113, v113
	v_fmac_f32_e32 v248, v114, v114
	v_fmac_f32_e32 v249, v115, v115
	v_fmac_f32_e32 v246, v116, v116
	v_fmac_f32_e32 v247, v117, v117
	v_fmac_f32_e32 v248, v118, v118
	v_fmac_f32_e32 v249, v119, v119
	v_fmac_f32_e32 v246, v120, v120
	v_fmac_f32_e32 v247, v121, v121
	v_fmac_f32_e32 v248, v122, v122
	v_fmac_f32_e32 v249, v123, v123
	v_fmac_f32_e32 v246, v124, v124
; DI float shx(float v, int mask, int lane) { return __int_as_float(__builtin_amdgcn_ds_bpermute((lane ^ mask) << 2, __float_as_int(v))); }
; DI void epi_slab(const GemmCfg c, const f32x16 (&acc)[4], float* sW, const float* rss, const size_t row0, const int g, const int lane,
;                  float* const g_h, u16* const g_hb, float* const g_out, const int final_out) {
;     ...
;       } else if (c.epi == EPI_QABS) {
;         f32x4 x = v * rs;
;         float s = x[0] * x[0] + x[1] * x[1] + x[2] * x[2] + x[3] * x[3];
;         s += shx(s, 1, ln_); s += shx(s, 2, ln_); s += shx(s, 4, ln_); s += shx(s, 8, ln_); s += shx(s, 16, ln_);
;         if (l31 == 0) c.f0[row * 32 + g] = s;
;         *(u32x2*)(c.o16 + row * 4096 + col) = MK2(pack2(x[0], x[1]), pack2(x[2], x[3]));
	v_fmac_f32_e32 v247, v125, v125
	v_fmac_f32_e32 v248, v126, v126
	v_fmac_f32_e32 v249, v127, v127
	v_add_f32_dpp v246, v246, v246 quad_perm:[1,0,3,2] row_mask:0xf bank_mask:0xf
	v_add_f32_dpp v247, v247, v247 quad_perm:[1,0,3,2] row_mask:0xf bank_mask:0xf
	v_add_f32_dpp v248, v248, v248 quad_perm:[1,0,3,2] row_mask:0xf bank_mask:0xf
	v_add_f32_dpp v249, v249, v249 quad_perm:[1,0,3,2] row_mask:0xf bank_mask:0xf
	v_add_f32_dpp v246, v246, v246 quad_perm:[2,3,0,1] row_mask:0xf bank_mask:0xf
	v_add_f32_dpp v247, v247, v247 quad_perm:[2,3,0,1] row_mask:0xf bank_mask:0xf
	v_add_f32_dpp v248, v248, v248 quad_perm:[2,3,0,1] row_mask:0xf bank_mask:0xf
	v_add_f32_dpp v249, v249, v249 quad_perm:[2,3,0,1] row_mask:0xf bank_mask:0xf
	v_add_f32_dpp v246, v246, v246 row_half_mirror row_mask:0xf bank_mask:0xf
	v_add_f32_dpp v247, v247, v247 row_half_mirror row_mask:0xf bank_mask:0xf
	v_add_f32_dpp v248, v248, v248 row_half_mirror row_mask:0xf bank_mask:0xf
	v_add_f32_dpp v249, v249, v249 row_half_mirror row_mask:0xf bank_mask:0xf
	v_add_f32_dpp v246, v246, v246 row_mirror row_mask:0xf bank_mask:0xf
	v_add_f32_dpp v247, v247, v247 row_mirror row_mask:0xf bank_mask:0xf
	v_add_f32_dpp v248, v248, v248 row_mirror row_mask:0xf bank_mask:0xf
	v_add_f32_dpp v249, v249, v249 row_mirror row_mask:0xf bank_mask:0xf
	global_store_dword v[242:243], v246, off offset:2048
	global_store_dword v[242:243], v247, off offset:2176
	global_store_dword v[242:243], v248, off offset:2304
	global_store_dword v[242:243], v249, off offset:2432
	ds_write2_b32 v200, v96, v97 offset0:0 offset1:132
	ds_write2_b32 v201, v98, v99 offset0:0 offset1:132
	ds_write2_b32 v200, v100, v101 offset0:16 offset1:148
	ds_write2_b32 v201, v102, v103 offset0:16 offset1:148
	ds_write2_b32 v200, v104, v105 offset0:32 offset1:164
	ds_write2_b32 v201, v106, v107 offset0:32 offset1:164
	ds_write2_b32 v200, v108, v109 offset0:48 offset1:180
	ds_write2_b32 v201, v110, v111 offset0:48 offset1:180
	ds_write2_b32 v200, v112, v113 offset0:64 offset1:196
	ds_write2_b32 v201, v114, v115 offset0:64 offset1:196
	ds_write2_b32 v200, v116, v117 offset0:80 offset1:212
	ds_write2_b32 v201, v118, v119 offset0:80 offset1:212
	ds_write2_b32 v200, v120, v121 offset0:96 offset1:228
	ds_write2_b32 v201, v122, v123 offset0:96 offset1:228
	ds_write2_b32 v200, v124, v125 offset0:112 offset1:244
	ds_write2_b32 v201, v126, v127 offset0:112 offset1:244
	v_lshl_add_u64 v[242:243], v[242:243], 0, v[244:245]
	s_waitcnt lgkmcnt(0)
	ds_read_b128 v[64:67], v202
	ds_read_b128 v[68:71], v202 offset:1056
	ds_read_b128 v[72:75], v202 offset:2112
	ds_read_b128 v[76:79], v202 offset:3168
	ds_read_b128 v[80:83], v202 offset:4224
	ds_read_b128 v[84:87], v202 offset:5280
	ds_read_b128 v[88:91], v202 offset:6336
	ds_read_b128 v[92:95], v202 offset:7392
	ds_read_b128 v[96:99], v202 offset:8448
	s_waitcnt lgkmcnt(8)
	v_lshl_add_u64 v[206:207], v[204:205], 0, s[8:9]
	v_cvt_pk_bf16_f32 v64, v64, v65
	v_cvt_pk_bf16_f32 v65, v66, v67
	s_add_u32 s8, s8, s4
	s_addc_u32 s9, s9, 0
	global_store_dwordx2 v[206:207], v[64:65], off
	ds_read_b128 v[100:103], v202 offset:9504
	s_waitcnt lgkmcnt(8)
	v_lshl_add_u64 v[206:207], v[204:205], 0, s[8:9]
	v_cvt_pk_bf16_f32 v68, v68, v69
	v_cvt_pk_bf16_f32 v69, v70, v71
	s_add_u32 s8, s8, s4
	s_addc_u32 s9, s9, 0
	global_store_dwordx2 v[206:207], v[68:69], off
	ds_read_b128 v[104:107], v202 offset:10560
	s_waitcnt lgkmcnt(8)
	v_lshl_add_u64 v[206:207], v[204:205], 0, s[8:9]
	v_cvt_pk_bf16_f32 v72, v72, v73
	v_cvt_pk_bf16_f32 v73, v74, v75
	s_add_u32 s8, s8, s4
	s_addc_u32 s9, s9, 0
	global_store_dwordx2 v[206:207], v[72:73], off
	ds_read_b128 v[108:111], v202 offset:11616
	s_waitcnt lgkmcnt(8)
	v_lshl_add_u64 v[206:207], v[204:205], 0, s[8:9]
	v_cvt_pk_bf16_f32 v76, v76, v77
	v_cvt_pk_bf16_f32 v77, v78, v79
	s_add_u32 s8, s8, s4
	s_addc_u32 s9, s9, 0
	global_store_dwordx2 v[206:207], v[76:77], off
	ds_read_b128 v[112:115], v202 offset:12672
	s_waitcnt lgkmcnt(8)
	v_lshl_add_u64 v[206:207], v[204:205], 0, s[8:9]
	v_cvt_pk_bf16_f32 v80, v80, v81
	v_cvt_pk_bf16_f32 v81, v82, v83
	s_add_u32 s8, s8, s4
	s_addc_u32 s9, s9, 0
	global_store_dwordx2 v[206:207], v[80:81], off
	ds_read_b128 v[116:119], v202 offset:13728
	s_waitcnt lgkmcnt(8)
	v_lshl_add_u64 v[206:207], v[204:205], 0, s[8:9]
	v_cvt_pk_bf16_f32 v84, v84, v85
	v_cvt_pk_bf16_f32 v85, v86, v87
	s_add_u32 s8, s8, s4
	s_addc_u32 s9, s9, 0
	global_store_dwordx2 v[206:207], v[84:85], off
	ds_read_b128 v[120:123], v202 offset:14784
	s_waitcnt lgkmcnt(8)
	v_lshl_add_u64 v[206:207], v[204:205], 0, s[8:9]
	v_cvt_pk_bf16_f32 v88, v88, v89
	v_cvt_pk_bf16_f32 v89, v90, v91
	s_add_u32 s8, s8, s4
	s_addc_u32 s9, s9, 0
	global_store_dwordx2 v[206:207], v[88:89], off
	ds_read_b128 v[124:127], v202 offset:15840
	s_waitcnt lgkmcnt(8)
	v_lshl_add_u64 v[206:207], v[204:205], 0, s[8:9]
	v_cvt_pk_bf16_f32 v92, v92, v93
	v_cvt_pk_bf16_f32 v93, v94, v95
	s_add_u32 s8, s8, s4
	s_addc_u32 s9, s9, 0
	global_store_dwordx2 v[206:207], v[92:93], off
	s_waitcnt lgkmcnt(7)
	v_lshl_add_u64 v[206:207], v[204:205], 0, s[8:9]
	v_cvt_pk_bf16_f32 v96, v96, v97
	v_cvt_pk_bf16_f32 v97, v98, v99
	s_add_u32 s8, s8, s4
	s_addc_u32 s9, s9, 0
	global_store_dwordx2 v[206:207], v[96:97], off
	s_waitcnt lgkmcnt(6)
	v_lshl_add_u64 v[206:207], v[204:205], 0, s[8:9]
	v_cvt_pk_bf16_f32 v100, v100, v101
	v_cvt_pk_bf16_f32 v101, v102, v103
	s_add_u32 s8, s8, s4
	s_addc_u32 s9, s9, 0
	global_store_dwordx2 v[206:207], v[100:101], off
	s_waitcnt lgkmcnt(5)
	v_lshl_add_u64 v[206:207], v[204:205], 0, s[8:9]
	v_cvt_pk_bf16_f32 v104, v104, v105
	v_cvt_pk_bf16_f32 v105, v106, v107
	s_add_u32 s8, s8, s4
	s_addc_u32 s9, s9, 0
	global_store_dwordx2 v[206:207], v[104:105], off
	s_waitcnt lgkmcnt(4)
; DI float shx(float v, int mask, int lane) { return __int_as_float(__builtin_amdgcn_ds_bpermute((lane ^ mask) << 2, __float_as_int(v))); }
; DI void epi_slab(const GemmCfg c, const f32x16 (&acc)[4], float* sW, const float* rss, const size_t row0, const int g, const int lane,
;                  float* const g_h, u16* const g_hb, float* const g_out, const int final_out) {
;     ...
;       } else if (c.epi == EPI_QABS) {
;         f32x4 x = v * rs;
;         float s = x[0] * x[0] + x[1] * x[1] + x[2] * x[2] + x[3] * x[3];
;         s += shx(s, 1, ln_); s += shx(s, 2, ln_); s += shx(s, 4, ln_); s += shx(s, 8, ln_); s += shx(s, 16, ln_);
;         if (l31 == 0) c.f0[row * 32 + g] = s;
;         *(u32x2*)(c.o16 + row * 4096 + col) = MK2(pack2(x[0], x[1]), pack2(x[2], x[3]));
	v_lshl_add_u64 v[206:207], v[204:205], 0, s[8:9]
	v_cvt_pk_bf16_f32 v108, v108, v109
	v_cvt_pk_bf16_f32 v109, v110, v111
	s_add_u32 s8, s8, s4
	s_addc_u32 s9, s9, 0
	global_store_dwordx2 v[206:207], v[108:109], off
	s_waitcnt lgkmcnt(3)
	v_lshl_add_u64 v[206:207], v[204:205], 0, s[8:9]
	v_cvt_pk_bf16_f32 v112, v112, v113
	v_cvt_pk_bf16_f32 v113, v114, v115
	s_add_u32 s8, s8, s4
	s_addc_u32 s9, s9, 0
	global_store_dwordx2 v[206:207], v[112:113], off
	s_waitcnt lgkmcnt(2)
	v_lshl_add_u64 v[206:207], v[204:205], 0, s[8:9]
	v_cvt_pk_bf16_f32 v116, v116, v117
	v_cvt_pk_bf16_f32 v117, v118, v119
	s_add_u32 s8, s8, s4
	s_addc_u32 s9, s9, 0
	global_store_dwordx2 v[206:207], v[116:117], off
	s_waitcnt lgkmcnt(1)
	v_lshl_add_u64 v[206:207], v[204:205], 0, s[8:9]
	v_cvt_pk_bf16_f32 v120, v120, v121
	v_cvt_pk_bf16_f32 v121, v122, v123
	s_add_u32 s8, s8, s4
	s_addc_u32 s9, s9, 0
	global_store_dwordx2 v[206:207], v[120:121], off
	s_waitcnt lgkmcnt(0)
	v_lshl_add_u64 v[206:207], v[204:205], 0, s[8:9]
	v_cvt_pk_bf16_f32 v124, v124, v125
	v_cvt_pk_bf16_f32 v125, v126, v127
	s_add_u32 s8, s8, s4
	s_addc_u32 s9, s9, 0
	global_store_dwordx2 v[206:207], v[124:125], off
	v_pk_mul_f32 v[0:1], v[0:1], v[234:235]
	v_pk_mul_f32 v[2:3], v[2:3], v[236:237]
	v_pk_mul_f32 v[4:5], v[4:5], v[234:235]
	v_pk_mul_f32 v[6:7], v[6:7], v[236:237]
	v_pk_mul_f32 v[8:9], v[8:9], v[234:235]
	v_pk_mul_f32 v[10:11], v[10:11], v[236:237]
	v_pk_mul_f32 v[12:13], v[12:13], v[234:235]
	v_pk_mul_f32 v[14:15], v[14:15], v[236:237]
	v_pk_mul_f32 v[16:17], v[16:17], v[234:235]
	v_pk_mul_f32 v[18:19], v[18:19], v[236:237]
	v_pk_mul_f32 v[20:21], v[20:21], v[234:235]
	v_pk_mul_f32 v[22:23], v[22:23], v[236:237]
	v_pk_mul_f32 v[24:25], v[24:25], v[234:235]
	v_pk_mul_f32 v[26:27], v[26:27], v[236:237]
	v_pk_mul_f32 v[28:29], v[28:29], v[234:235]
	v_pk_mul_f32 v[30:31], v[30:31], v[236:237]
	v_mul_f32_e32 v246, v0, v0
	v_mul_f32_e32 v247, v1, v1
	v_mul_f32_e32 v248, v2, v2
	v_mul_f32_e32 v249, v3, v3
	v_fmac_f32_e32 v246, v4, v4
	v_fmac_f32_e32 v247, v5, v5
	v_fmac_f32_e32 v248, v6, v6
	v_fmac_f32_e32 v249, v7, v7
	v_fmac_f32_e32 v246, v8, v8
	v_fmac_f32_e32 v247, v9, v9
	v_fmac_f32_e32 v248, v10, v10
	v_fmac_f32_e32 v249, v11, v11
	v_fmac_f32_e32 v246, v12, v12
	v_fmac_f32_e32 v247, v13, v13
	v_fmac_f32_e32 v248, v14, v14
	v_fmac_f32_e32 v249, v15, v15
	v_fmac_f32_e32 v246, v16, v16
	v_fmac_f32_e32 v247, v17, v17
	v_fmac_f32_e32 v248, v18, v18
	v_fmac_f32_e32 v249, v19, v19
	v_fmac_f32_e32 v246, v20, v20
	v_fmac_f32_e32 v247, v21, v21
	v_fmac_f32_e32 v248, v22, v22
	v_fmac_f32_e32 v249, v23, v23
	v_fmac_f32_e32 v246, v24, v24
	v_fmac_f32_e32 v247, v25, v25
	v_fmac_f32_e32 v248, v26, v26
	v_fmac_f32_e32 v249, v27, v27
	v_fmac_f32_e32 v246, v28, v28
	v_fmac_f32_e32 v247, v29, v29
	v_fmac_f32_e32 v248, v30, v30
	v_fmac_f32_e32 v249, v31, v31
	v_add_f32_dpp v246, v246, v246 quad_perm:[1,0,3,2] row_mask:0xf bank_mask:0xf
	v_add_f32_dpp v247, v247, v247 quad_perm:[1,0,3,2] row_mask:0xf bank_mask:0xf
	v_add_f32_dpp v248, v248, v248 quad_perm:[1,0,3,2] row_mask:0xf bank_mask:0xf
	v_add_f32_dpp v249, v249, v249 quad_perm:[1,0,3,2] row_mask:0xf bank_mask:0xf
	v_add_f32_dpp v246, v246, v246 quad_perm:[2,3,0,1] row_mask:0xf bank_mask:0xf
	v_add_f32_dpp v247, v247, v247 quad_perm:[2,3,0,1] row_mask:0xf bank_mask:0xf
	v_add_f32_dpp v248, v248, v248 quad_perm:[2,3,0,1] row_mask:0xf bank_mask:0xf
	v_add_f32_dpp v249, v249, v249 quad_perm:[2,3,0,1] row_mask:0xf bank_mask:0xf
	v_add_f32_dpp v246, v246, v246 row_half_mirror row_mask:0xf bank_mask:0xf
	v_add_f32_dpp v247, v247, v247 row_half_mirror row_mask:0xf bank_mask:0xf
	v_add_f32_dpp v248, v248, v248 row_half_mirror row_mask:0xf bank_mask:0xf
	v_add_f32_dpp v249, v249, v249 row_half_mirror row_mask:0xf bank_mask:0xf
	v_add_f32_dpp v246, v246, v246 row_mirror row_mask:0xf bank_mask:0xf
	v_add_f32_dpp v247, v247, v247 row_mirror row_mask:0xf bank_mask:0xf
	v_add_f32_dpp v248, v248, v248 row_mirror row_mask:0xf bank_mask:0xf
	v_add_f32_dpp v249, v249, v249 row_mirror row_mask:0xf bank_mask:0xf
	global_store_dword v[242:243], v246, off offset:0
	global_store_dword v[242:243], v247, off offset:128
	global_store_dword v[242:243], v248, off offset:256
	global_store_dword v[242:243], v249, off offset:384
	ds_write2_b32 v198, v0, v1 offset0:0 offset1:132
	ds_write2_b32 v199, v2, v3 offset0:0 offset1:132
	ds_write2_b32 v198, v4, v5 offset0:16 offset1:148
	ds_write2_b32 v199, v6, v7 offset0:16 offset1:148
	ds_write2_b32 v198, v8, v9 offset0:32 offset1:164
	ds_write2_b32 v199, v10, v11 offset0:32 offset1:164
	ds_write2_b32 v198, v12, v13 offset0:48 offset1:180
	ds_write2_b32 v199, v14, v15 offset0:48 offset1:180
	ds_write2_b32 v198, v16, v17 offset0:64 offset1:196
	ds_write2_b32 v199, v18, v19 offset0:64 offset1:196
	ds_write2_b32 v198, v20, v21 offset0:80 offset1:212
	ds_write2_b32 v199, v22, v23 offset0:80 offset1:212
	ds_write2_b32 v198, v24, v25 offset0:96 offset1:228
	ds_write2_b32 v199, v26, v27 offset0:96 offset1:228
	ds_write2_b32 v198, v28, v29 offset0:112 offset1:244
	ds_write2_b32 v199, v30, v31 offset0:112 offset1:244
	v_pk_mul_f32 v[32:33], v[32:33], v[238:239]
	v_pk_mul_f32 v[34:35], v[34:35], v[240:241]
	v_pk_mul_f32 v[36:37], v[36:37], v[238:239]
	v_pk_mul_f32 v[38:39], v[38:39], v[240:241]
	v_pk_mul_f32 v[40:41], v[40:41], v[238:239]
	v_pk_mul_f32 v[42:43], v[42:43], v[240:241]
	v_pk_mul_f32 v[44:45], v[44:45], v[238:239]
	v_pk_mul_f32 v[46:47], v[46:47], v[240:241]
	v_pk_mul_f32 v[48:49], v[48:49], v[238:239]
	v_pk_mul_f32 v[50:51], v[50:51], v[240:241]
	v_pk_mul_f32 v[52:53], v[52:53], v[238:239]
	v_pk_mul_f32 v[54:55], v[54:55], v[240:241]
; DI float shx(float v, int mask, int lane) { return __int_as_float(__builtin_amdgcn_ds_bpermute((lane ^ mask) << 2, __float_as_int(v))); }
; DI void epi_slab(const GemmCfg c, const f32x16 (&acc)[4], float* sW, const float* rss, const size_t row0, const int g, const int lane,
;                  float* const g_h, u16* const g_hb, float* const g_out, const int final_out) {
;     ...
;       } else if (c.epi == EPI_QABS) {
;         f32x4 x = v * rs;
;         float s = x[0] * x[0] + x[1] * x[1] + x[2] * x[2] + x[3] * x[3];
;         s += shx(s, 1, ln_); s += shx(s, 2, ln_); s += shx(s, 4, ln_); s += shx(s, 8, ln_); s += shx(s, 16, ln_);
;         if (l31 == 0) c.f0[row * 32 + g] = s;
;         *(u32x2*)(c.o16 + row * 4096 + col) = MK2(pack2(x[0], x[1]), pack2(x[2], x[3]));
	v_pk_mul_f32 v[56:57], v[56:57], v[238:239]
	v_pk_mul_f32 v[58:59], v[58:59], v[240:241]
	v_pk_mul_f32 v[60:61], v[60:61], v[238:239]
	v_pk_mul_f32 v[62:63], v[62:63], v[240:241]
	v_mul_f32_e32 v246, v32, v32
	v_mul_f32_e32 v247, v33, v33
	v_mul_f32_e32 v248, v34, v34
	v_mul_f32_e32 v249, v35, v35
	v_fmac_f32_e32 v246, v36, v36
	v_fmac_f32_e32 v247, v37, v37
	v_fmac_f32_e32 v248, v38, v38
	v_fmac_f32_e32 v249, v39, v39
	v_fmac_f32_e32 v246, v40, v40
	v_fmac_f32_e32 v247, v41, v41
	v_fmac_f32_e32 v248, v42, v42
	v_fmac_f32_e32 v249, v43, v43
	v_fmac_f32_e32 v246, v44, v44
	v_fmac_f32_e32 v247, v45, v45
	v_fmac_f32_e32 v248, v46, v46
	v_fmac_f32_e32 v249, v47, v47
	v_fmac_f32_e32 v246, v48, v48
	v_fmac_f32_e32 v247, v49, v49
	v_fmac_f32_e32 v248, v50, v50
	v_fmac_f32_e32 v249, v51, v51
	v_fmac_f32_e32 v246, v52, v52
	v_fmac_f32_e32 v247, v53, v53
	v_fmac_f32_e32 v248, v54, v54
	v_fmac_f32_e32 v249, v55, v55
	v_fmac_f32_e32 v246, v56, v56
	v_fmac_f32_e32 v247, v57, v57
	v_fmac_f32_e32 v248, v58, v58
	v_fmac_f32_e32 v249, v59, v59
	v_fmac_f32_e32 v246, v60, v60
	v_fmac_f32_e32 v247, v61, v61
	v_fmac_f32_e32 v248, v62, v62
	v_fmac_f32_e32 v249, v63, v63
	v_add_f32_dpp v246, v246, v246 quad_perm:[1,0,3,2] row_mask:0xf bank_mask:0xf
	v_add_f32_dpp v247, v247, v247 quad_perm:[1,0,3,2] row_mask:0xf bank_mask:0xf
	v_add_f32_dpp v248, v248, v248 quad_perm:[1,0,3,2] row_mask:0xf bank_mask:0xf
	v_add_f32_dpp v249, v249, v249 quad_perm:[1,0,3,2] row_mask:0xf bank_mask:0xf
	v_add_f32_dpp v246, v246, v246 quad_perm:[2,3,0,1] row_mask:0xf bank_mask:0xf
	v_add_f32_dpp v247, v247, v247 quad_perm:[2,3,0,1] row_mask:0xf bank_mask:0xf
	v_add_f32_dpp v248, v248, v248 quad_perm:[2,3,0,1] row_mask:0xf bank_mask:0xf
	v_add_f32_dpp v249, v249, v249 quad_perm:[2,3,0,1] row_mask:0xf bank_mask:0xf
	v_add_f32_dpp v246, v246, v246 row_half_mirror row_mask:0xf bank_mask:0xf
	v_add_f32_dpp v247, v247, v247 row_half_mirror row_mask:0xf bank_mask:0xf
	v_add_f32_dpp v248, v248, v248 row_half_mirror row_mask:0xf bank_mask:0xf
	v_add_f32_dpp v249, v249, v249 row_half_mirror row_mask:0xf bank_mask:0xf
	v_add_f32_dpp v246, v246, v246 row_mirror row_mask:0xf bank_mask:0xf
	v_add_f32_dpp v247, v247, v247 row_mirror row_mask:0xf bank_mask:0xf
	v_add_f32_dpp v248, v248, v248 row_mirror row_mask:0xf bank_mask:0xf
	v_add_f32_dpp v249, v249, v249 row_mirror row_mask:0xf bank_mask:0xf
	global_store_dword v[242:243], v246, off offset:2048
	global_store_dword v[242:243], v247, off offset:2176
	global_store_dword v[242:243], v248, off offset:2304
	global_store_dword v[242:243], v249, off offset:2432
	ds_write2_b32 v200, v32, v33 offset0:0 offset1:132
	ds_write2_b32 v201, v34, v35 offset0:0 offset1:132
	ds_write2_b32 v200, v36, v37 offset0:16 offset1:148
	ds_write2_b32 v201, v38, v39 offset0:16 offset1:148
	ds_write2_b32 v200, v40, v41 offset0:32 offset1:164
	ds_write2_b32 v201, v42, v43 offset0:32 offset1:164
	ds_write2_b32 v200, v44, v45 offset0:48 offset1:180
	ds_write2_b32 v201, v46, v47 offset0:48 offset1:180
	ds_write2_b32 v200, v48, v49 offset0:64 offset1:196
	ds_write2_b32 v201, v50, v51 offset0:64 offset1:196
	ds_write2_b32 v200, v52, v53 offset0:80 offset1:212
	ds_write2_b32 v201, v54, v55 offset0:80 offset1:212
	ds_write2_b32 v200, v56, v57 offset0:96 offset1:228
	ds_write2_b32 v201, v58, v59 offset0:96 offset1:228
	ds_write2_b32 v200, v60, v61 offset0:112 offset1:244
	ds_write2_b32 v201, v62, v63 offset0:112 offset1:244
	s_waitcnt lgkmcnt(0)
	ds_read_b128 v[0:3], v202
	ds_read_b128 v[4:7], v202 offset:1056
	ds_read_b128 v[8:11], v202 offset:2112
	ds_read_b128 v[12:15], v202 offset:3168
	ds_read_b128 v[16:19], v202 offset:4224
	ds_read_b128 v[20:23], v202 offset:5280
	ds_read_b128 v[24:27], v202 offset:6336
	ds_read_b128 v[28:31], v202 offset:7392
	ds_read_b128 v[32:35], v202 offset:8448
	s_waitcnt lgkmcnt(8)
	v_lshl_add_u64 v[206:207], v[204:205], 0, s[8:9]
	v_cvt_pk_bf16_f32 v0, v0, v1
	v_cvt_pk_bf16_f32 v1, v2, v3
	s_add_u32 s8, s8, s4
	s_addc_u32 s9, s9, 0
	global_store_dwordx2 v[206:207], v[0:1], off
	ds_read_b128 v[36:39], v202 offset:9504
	s_waitcnt lgkmcnt(8)
	v_lshl_add_u64 v[206:207], v[204:205], 0, s[8:9]
	v_cvt_pk_bf16_f32 v4, v4, v5
	v_cvt_pk_bf16_f32 v5, v6, v7
	s_add_u32 s8, s8, s4
	s_addc_u32 s9, s9, 0
	global_store_dwordx2 v[206:207], v[4:5], off
	ds_read_b128 v[40:43], v202 offset:10560
	s_waitcnt lgkmcnt(8)
	v_lshl_add_u64 v[206:207], v[204:205], 0, s[8:9]
	v_cvt_pk_bf16_f32 v8, v8, v9
	v_cvt_pk_bf16_f32 v9, v10, v11
	s_add_u32 s8, s8, s4
	s_addc_u32 s9, s9, 0
	global_store_dwordx2 v[206:207], v[8:9], off
	ds_read_b128 v[44:47], v202 offset:11616
	s_waitcnt lgkmcnt(8)
	v_lshl_add_u64 v[206:207], v[204:205], 0, s[8:9]
	v_cvt_pk_bf16_f32 v12, v12, v13
	v_cvt_pk_bf16_f32 v13, v14, v15
	s_add_u32 s8, s8, s4
	s_addc_u32 s9, s9, 0
	global_store_dwordx2 v[206:207], v[12:13], off
	ds_read_b128 v[48:51], v202 offset:12672
	s_waitcnt lgkmcnt(8)
	v_lshl_add_u64 v[206:207], v[204:205], 0, s[8:9]
	v_cvt_pk_bf16_f32 v16, v16, v17
	v_cvt_pk_bf16_f32 v17, v18, v19
	s_add_u32 s8, s8, s4
	s_addc_u32 s9, s9, 0
	global_store_dwordx2 v[206:207], v[16:17], off
	ds_read_b128 v[52:55], v202 offset:13728
	s_waitcnt lgkmcnt(8)
	v_lshl_add_u64 v[206:207], v[204:205], 0, s[8:9]
	v_cvt_pk_bf16_f32 v20, v20, v21
	v_cvt_pk_bf16_f32 v21, v22, v23
	s_add_u32 s8, s8, s4
	s_addc_u32 s9, s9, 0
	global_store_dwordx2 v[206:207], v[20:21], off
	ds_read_b128 v[56:59], v202 offset:14784
	s_waitcnt lgkmcnt(8)
	v_lshl_add_u64 v[206:207], v[204:205], 0, s[8:9]
	v_cvt_pk_bf16_f32 v24, v24, v25
	v_cvt_pk_bf16_f32 v25, v26, v27
	s_add_u32 s8, s8, s4
	s_addc_u32 s9, s9, 0
	global_store_dwordx2 v[206:207], v[24:25], off
	ds_read_b128 v[60:63], v202 offset:15840
	s_waitcnt lgkmcnt(8)
; DI float shx(float v, int mask, int lane) { return __int_as_float(__builtin_amdgcn_ds_bpermute((lane ^ mask) << 2, __float_as_int(v))); }
; DI void epi_slab(const GemmCfg c, const f32x16 (&acc)[4], float* sW, const float* rss, const size_t row0, const int g, const int lane,
;                  float* const g_h, u16* const g_hb, float* const g_out, const int final_out) {
;     ...
;       } else if (c.epi == EPI_QIDX) {
;         f32x4 x = v * (rs * 0.125f);
;         *(u32x2*)(c.o16 + row * 512 + col) = MK2(pack2(x[0], x[1]), pack2(x[2], x[3]));
;       } else if (c.epi == EPI_QABS) {
;         f32x4 x = v * rs;
;         float s = x[0] * x[0] + x[1] * x[1] + x[2] * x[2] + x[3] * x[3];
;         s += shx(s, 1, ln_); s += shx(s, 2, ln_); s += shx(s, 4, ln_); s += shx(s, 8, ln_); s += shx(s, 16, ln_);
;         if (l31 == 0) c.f0[row * 32 + g] = s;
;         *(u32x2*)(c.o16 + row * 4096 + col) = MK2(pack2(x[0], x[1]), pack2(x[2], x[3]));
	v_lshl_add_u64 v[206:207], v[204:205], 0, s[8:9]
	v_cvt_pk_bf16_f32 v28, v28, v29
	v_cvt_pk_bf16_f32 v29, v30, v31
	s_add_u32 s8, s8, s4
	s_addc_u32 s9, s9, 0
	global_store_dwordx2 v[206:207], v[28:29], off
	s_waitcnt lgkmcnt(7)
	v_lshl_add_u64 v[206:207], v[204:205], 0, s[8:9]
	v_cvt_pk_bf16_f32 v32, v32, v33
	v_cvt_pk_bf16_f32 v33, v34, v35
	s_add_u32 s8, s8, s4
	s_addc_u32 s9, s9, 0
	global_store_dwordx2 v[206:207], v[32:33], off
	s_waitcnt lgkmcnt(6)
	v_lshl_add_u64 v[206:207], v[204:205], 0, s[8:9]
	v_cvt_pk_bf16_f32 v36, v36, v37
	v_cvt_pk_bf16_f32 v37, v38, v39
	s_add_u32 s8, s8, s4
	s_addc_u32 s9, s9, 0
	global_store_dwordx2 v[206:207], v[36:37], off
	s_waitcnt lgkmcnt(5)
	v_lshl_add_u64 v[206:207], v[204:205], 0, s[8:9]
	v_cvt_pk_bf16_f32 v40, v40, v41
	v_cvt_pk_bf16_f32 v41, v42, v43
	s_add_u32 s8, s8, s4
	s_addc_u32 s9, s9, 0
	global_store_dwordx2 v[206:207], v[40:41], off
	s_waitcnt lgkmcnt(4)
	v_lshl_add_u64 v[206:207], v[204:205], 0, s[8:9]
	v_cvt_pk_bf16_f32 v44, v44, v45
	v_cvt_pk_bf16_f32 v45, v46, v47
	s_add_u32 s8, s8, s4
	s_addc_u32 s9, s9, 0
	global_store_dwordx2 v[206:207], v[44:45], off
	s_waitcnt lgkmcnt(3)
	v_lshl_add_u64 v[206:207], v[204:205], 0, s[8:9]
	v_cvt_pk_bf16_f32 v48, v48, v49
	v_cvt_pk_bf16_f32 v49, v50, v51
	s_add_u32 s8, s8, s4
	s_addc_u32 s9, s9, 0
	global_store_dwordx2 v[206:207], v[48:49], off
	s_waitcnt lgkmcnt(2)
	v_lshl_add_u64 v[206:207], v[204:205], 0, s[8:9]
	v_cvt_pk_bf16_f32 v52, v52, v53
	v_cvt_pk_bf16_f32 v53, v54, v55
	s_add_u32 s8, s8, s4
	s_addc_u32 s9, s9, 0
	global_store_dwordx2 v[206:207], v[52:53], off
	s_waitcnt lgkmcnt(1)
	v_lshl_add_u64 v[206:207], v[204:205], 0, s[8:9]
	v_cvt_pk_bf16_f32 v56, v56, v57
	v_cvt_pk_bf16_f32 v57, v58, v59
	s_add_u32 s8, s8, s4
	s_addc_u32 s9, s9, 0
	global_store_dwordx2 v[206:207], v[56:57], off
	s_waitcnt lgkmcnt(0)
	v_lshl_add_u64 v[206:207], v[204:205], 0, s[8:9]
	v_cvt_pk_bf16_f32 v60, v60, v61
	v_cvt_pk_bf16_f32 v61, v62, v63
	s_add_u32 s8, s8, s4
	s_addc_u32 s9, s9, 0
	global_store_dwordx2 v[206:207], v[60:61], off
	s_branch .LBB0_108
.Lqidx2:
	v_and_b32_e32 v222, 15, v185
	v_lshrrev_b32_e32 v223, 4, v185
	s_lshl_b32 s4, s86, 2
	s_add_i32 s4, s4, 0x24000
	v_lshl_add_u32 v224, v223, 4, s4
	ds_read_b128 v[226:229], v224
	ds_read_b128 v[230:233], v224 offset:64
	ds_read_b128 v[234:237], v224 offset:128
	ds_read_b128 v[238:241], v224 offset:192
	v_mul_u32_u24_e32 v198, 0x840, v223
	v_lshl_add_u32 v198, v222, 2, v198
	v_add_u32_e32 v198, s53, v198
	v_add_u32_e32 v199, 0x420, v198
	v_add_u32_e32 v200, 0x2100, v198
	v_add_u32_e32 v201, 0x2520, v198
	v_lshrrev_b32_e32 v202, 5, v185
	v_and_b32_e32 v206, 31, v185
	v_mul_u32_u24_e32 v204, 0x210, v202
	v_lshl_add_u32 v204, v206, 4, v204
	v_add_u32_e32 v250, s53, v204
	v_add_u32_e32 v204, s6, v202
	v_lshlrev_b32_e32 v204, 10, v204
	v_lshl_add_u32 v206, v206, 2, s64
	v_lshl_add_u32 v204, v206, 1, v204
	v_mov_b32_e32 v205, 0
	v_lshl_add_u64 v[204:205], v[204:205], 0, s[56:57]
	v_mov_b32_e32 v202, v250
	v_mov_b32_e32 v250, 0x3c800000
	s_movk_i32 s4, 0x800
	s_mov_b64 s[8:9], 0
	s_waitcnt lgkmcnt(0)
	v_fmaak_f32 v226, v191, v226, 0x358637bd
	v_fmaak_f32 v227, v191, v227, 0x358637bd
	v_cmp_gt_f32_e32 vcc, s33, v226
	v_cmp_gt_f32_e64 s[14:15], s33, v227
	v_mul_f32_e32 v224, 0x4b800000, v226
	v_mul_f32_e32 v225, 0x4b800000, v227
	v_cndmask_b32_e32 v226, v226, v224, vcc
	v_cndmask_b32_e64 v227, v227, v225, s[14:15]
	v_rsq_f32_e32 v226, v226
	v_rsq_f32_e32 v227, v227
	s_nop 0
	v_mul_f32_e32 v224, 0x45800000, v226
	v_mul_f32_e32 v225, 0x45800000, v227
	v_cndmask_b32_e32 v226, v226, v224, vcc
	v_cndmask_b32_e64 v227, v227, v225, s[14:15]
	v_mul_f32_e32 v226, 0.125, v226
	v_mul_f32_e32 v227, 0.125, v227
	v_fmaak_f32 v228, v191, v228, 0x358637bd
	v_fmaak_f32 v229, v191, v229, 0x358637bd
	v_cmp_gt_f32_e32 vcc, s33, v228
	v_cmp_gt_f32_e64 s[14:15], s33, v229
	v_mul_f32_e32 v224, 0x4b800000, v228
	v_mul_f32_e32 v225, 0x4b800000, v229
	v_cndmask_b32_e32 v228, v228, v224, vcc
	v_cndmask_b32_e64 v229, v229, v225, s[14:15]
	v_rsq_f32_e32 v228, v228
	v_rsq_f32_e32 v229, v229
	s_nop 0
	v_mul_f32_e32 v224, 0x45800000, v228
	v_mul_f32_e32 v225, 0x45800000, v229
	v_cndmask_b32_e32 v228, v228, v224, vcc
	v_cndmask_b32_e64 v229, v229, v225, s[14:15]
	v_mul_f32_e32 v228, 0.125, v228
	v_mul_f32_e32 v229, 0.125, v229
	v_fmaak_f32 v230, v191, v230, 0x358637bd
	v_fmaak_f32 v231, v191, v231, 0x358637bd
	v_cmp_gt_f32_e32 vcc, s33, v230
	v_cmp_gt_f32_e64 s[14:15], s33, v231
	v_mul_f32_e32 v224, 0x4b800000, v230
	v_mul_f32_e32 v225, 0x4b800000, v231
	v_cndmask_b32_e32 v230, v230, v224, vcc
	v_cndmask_b32_e64 v231, v231, v225, s[14:15]
	v_rsq_f32_e32 v230, v230
	v_rsq_f32_e32 v231, v231
	s_nop 0
	v_mul_f32_e32 v224, 0x45800000, v230
	v_mul_f32_e32 v225, 0x45800000, v231
	v_cndmask_b32_e32 v230, v230, v224, vcc
	v_cndmask_b32_e64 v231, v231, v225, s[14:15]
	v_mul_f32_e32 v230, 0.125, v230
	v_mul_f32_e32 v231, 0.125, v231
	v_fmaak_f32 v232, v191, v232, 0x358637bd
	v_fmaak_f32 v233, v191, v233, 0x358637bd
	v_cmp_gt_f32_e32 vcc, s33, v232
	v_cmp_gt_f32_e64 s[14:15], s33, v233
	v_mul_f32_e32 v224, 0x4b800000, v232
	v_mul_f32_e32 v225, 0x4b800000, v233
	v_cndmask_b32_e32 v232, v232, v224, vcc
	v_cndmask_b32_e64 v233, v233, v225, s[14:15]
	v_rsq_f32_e32 v232, v232
	v_rsq_f32_e32 v233, v233
	s_nop 0
	v_mul_f32_e32 v224, 0x45800000, v232
	v_mul_f32_e32 v225, 0x45800000, v233
	v_cndmask_b32_e32 v232, v232, v224, vcc
	v_cndmask_b32_e64 v233, v233, v225, s[14:15]
	v_mul_f32_e32 v232, 0.125, v232
	v_mul_f32_e32 v233, 0.125, v233
	v_fmaak_f32 v234, v191, v234, 0x358637bd
	v_fmaak_f32 v235, v191, v235, 0x358637bd
	v_cmp_gt_f32_e32 vcc, s33, v234
; DI void epi_slab(const GemmCfg c, const f32x16 (&acc)[4], float* sW, const float* rss, const size_t row0, const int g, const int lane,
;                  float* const g_h, u16* const g_hb, float* const g_out, const int final_out) {
;     ...
;     for (int it = 0; it < 16; ++it) {
;       const int r = hh + 2 * it;
;       const size_t row = row0 + r;
;       f32x4 v = *(const f32x4*)(sW + r * 132 + c4);
;       const float rs = c.use_rs ? rsqrtf(rss[r] * invK + 1e-6f) : 1.f;
;     ...
;       } else if (c.epi == EPI_QIDX) {
;         f32x4 x = v * (rs * 0.125f);
;         *(u32x2*)(c.o16 + row * 512 + col) = MK2(pack2(x[0], x[1]), pack2(x[2], x[3]));
	v_cmp_gt_f32_e64 s[14:15], s33, v235
	v_mul_f32_e32 v224, 0x4b800000, v234
	v_mul_f32_e32 v225, 0x4b800000, v235
	v_cndmask_b32_e32 v234, v234, v224, vcc
	v_cndmask_b32_e64 v235, v235, v225, s[14:15]
	v_rsq_f32_e32 v234, v234
	v_rsq_f32_e32 v235, v235
	s_nop 0
	v_mul_f32_e32 v224, 0x45800000, v234
	v_mul_f32_e32 v225, 0x45800000, v235
	v_cndmask_b32_e32 v234, v234, v224, vcc
	v_cndmask_b32_e64 v235, v235, v225, s[14:15]
	v_mul_f32_e32 v234, 0.125, v234
	v_mul_f32_e32 v235, 0.125, v235
	v_fmaak_f32 v236, v191, v236, 0x358637bd
	v_fmaak_f32 v237, v191, v237, 0x358637bd
	v_cmp_gt_f32_e32 vcc, s33, v236
	v_cmp_gt_f32_e64 s[14:15], s33, v237
	v_mul_f32_e32 v224, 0x4b800000, v236
	v_mul_f32_e32 v225, 0x4b800000, v237
	v_cndmask_b32_e32 v236, v236, v224, vcc
	v_cndmask_b32_e64 v237, v237, v225, s[14:15]
	v_rsq_f32_e32 v236, v236
	v_rsq_f32_e32 v237, v237
	s_nop 0
	v_mul_f32_e32 v224, 0x45800000, v236
	v_mul_f32_e32 v225, 0x45800000, v237
	v_cndmask_b32_e32 v236, v236, v224, vcc
	v_cndmask_b32_e64 v237, v237, v225, s[14:15]
	v_mul_f32_e32 v236, 0.125, v236
	v_mul_f32_e32 v237, 0.125, v237
	v_fmaak_f32 v238, v191, v238, 0x358637bd
	v_fmaak_f32 v239, v191, v239, 0x358637bd
	v_cmp_gt_f32_e32 vcc, s33, v238
	v_cmp_gt_f32_e64 s[14:15], s33, v239
	v_mul_f32_e32 v224, 0x4b800000, v238
	v_mul_f32_e32 v225, 0x4b800000, v239
	v_cndmask_b32_e32 v238, v238, v224, vcc
	v_cndmask_b32_e64 v239, v239, v225, s[14:15]
	v_rsq_f32_e32 v238, v238
	v_rsq_f32_e32 v239, v239
	s_nop 0
	v_mul_f32_e32 v224, 0x45800000, v238
	v_mul_f32_e32 v225, 0x45800000, v239
	v_cndmask_b32_e32 v238, v238, v224, vcc
	v_cndmask_b32_e64 v239, v239, v225, s[14:15]
	v_mul_f32_e32 v238, 0.125, v238
	v_mul_f32_e32 v239, 0.125, v239
	v_fmaak_f32 v240, v191, v240, 0x358637bd
	v_fmaak_f32 v241, v191, v241, 0x358637bd
	v_cmp_gt_f32_e32 vcc, s33, v240
	v_cmp_gt_f32_e64 s[14:15], s33, v241
	v_mul_f32_e32 v224, 0x4b800000, v240
	v_mul_f32_e32 v225, 0x4b800000, v241
	v_cndmask_b32_e32 v240, v240, v224, vcc
	v_cndmask_b32_e64 v241, v241, v225, s[14:15]
	v_rsq_f32_e32 v240, v240
	v_rsq_f32_e32 v241, v241
	s_nop 0
	v_mul_f32_e32 v224, 0x45800000, v240
	v_mul_f32_e32 v225, 0x45800000, v241
	v_cndmask_b32_e32 v240, v240, v224, vcc
	v_cndmask_b32_e64 v241, v241, v225, s[14:15]
	v_mul_f32_e32 v240, 0.125, v240
	v_mul_f32_e32 v241, 0.125, v241
	v_pk_mul_f32 v[64:65], v[64:65], v[226:227]
	v_pk_mul_f32 v[66:67], v[66:67], v[228:229]
	v_pk_mul_f32 v[68:69], v[68:69], v[226:227]
	v_pk_mul_f32 v[70:71], v[70:71], v[228:229]
	v_pk_mul_f32 v[72:73], v[72:73], v[226:227]
	v_pk_mul_f32 v[74:75], v[74:75], v[228:229]
	v_pk_mul_f32 v[76:77], v[76:77], v[226:227]
	v_pk_mul_f32 v[78:79], v[78:79], v[228:229]
	v_pk_mul_f32 v[80:81], v[80:81], v[226:227]
	v_pk_mul_f32 v[82:83], v[82:83], v[228:229]
	v_pk_mul_f32 v[84:85], v[84:85], v[226:227]
	v_pk_mul_f32 v[86:87], v[86:87], v[228:229]
	v_pk_mul_f32 v[88:89], v[88:89], v[226:227]
	v_pk_mul_f32 v[90:91], v[90:91], v[228:229]
	v_pk_mul_f32 v[92:93], v[92:93], v[226:227]
	v_pk_mul_f32 v[94:95], v[94:95], v[228:229]
	ds_write2_b32 v198, v64, v65 offset0:0 offset1:132
	ds_write2_b32 v199, v66, v67 offset0:0 offset1:132
	ds_write2_b32 v198, v68, v69 offset0:16 offset1:148
	ds_write2_b32 v199, v70, v71 offset0:16 offset1:148
	ds_write2_b32 v198, v72, v73 offset0:32 offset1:164
	ds_write2_b32 v199, v74, v75 offset0:32 offset1:164
	ds_write2_b32 v198, v76, v77 offset0:48 offset1:180
	ds_write2_b32 v199, v78, v79 offset0:48 offset1:180
	ds_write2_b32 v198, v80, v81 offset0:64 offset1:196
	ds_write2_b32 v199, v82, v83 offset0:64 offset1:196
	ds_write2_b32 v198, v84, v85 offset0:80 offset1:212
	ds_write2_b32 v199, v86, v87 offset0:80 offset1:212
	ds_write2_b32 v198, v88, v89 offset0:96 offset1:228
	ds_write2_b32 v199, v90, v91 offset0:96 offset1:228
	ds_write2_b32 v198, v92, v93 offset0:112 offset1:244
	ds_write2_b32 v199, v94, v95 offset0:112 offset1:244
	v_pk_mul_f32 v[96:97], v[96:97], v[230:231]
	v_pk_mul_f32 v[98:99], v[98:99], v[232:233]
	v_pk_mul_f32 v[100:101], v[100:101], v[230:231]
	v_pk_mul_f32 v[102:103], v[102:103], v[232:233]
	v_pk_mul_f32 v[104:105], v[104:105], v[230:231]
	v_pk_mul_f32 v[106:107], v[106:107], v[232:233]
	v_pk_mul_f32 v[108:109], v[108:109], v[230:231]
	v_pk_mul_f32 v[110:111], v[110:111], v[232:233]
	v_pk_mul_f32 v[112:113], v[112:113], v[230:231]
	v_pk_mul_f32 v[114:115], v[114:115], v[232:233]
	v_pk_mul_f32 v[116:117], v[116:117], v[230:231]
	v_pk_mul_f32 v[118:119], v[118:119], v[232:233]
	v_pk_mul_f32 v[120:121], v[120:121], v[230:231]
	v_pk_mul_f32 v[122:123], v[122:123], v[232:233]
	v_pk_mul_f32 v[124:125], v[124:125], v[230:231]
	v_pk_mul_f32 v[126:127], v[126:127], v[232:233]
	ds_write2_b32 v200, v96, v97 offset0:0 offset1:132
	ds_write2_b32 v201, v98, v99 offset0:0 offset1:132
	ds_write2_b32 v200, v100, v101 offset0:16 offset1:148
	ds_write2_b32 v201, v102, v103 offset0:16 offset1:148
	ds_write2_b32 v200, v104, v105 offset0:32 offset1:164
	ds_write2_b32 v201, v106, v107 offset0:32 offset1:164
	ds_write2_b32 v200, v108, v109 offset0:48 offset1:180
	ds_write2_b32 v201, v110, v111 offset0:48 offset1:180
	ds_write2_b32 v200, v112, v113 offset0:64 offset1:196
	ds_write2_b32 v201, v114, v115 offset0:64 offset1:196
	ds_write2_b32 v200, v116, v117 offset0:80 offset1:212
	ds_write2_b32 v201, v118, v119 offset0:80 offset1:212
	ds_write2_b32 v200, v120, v121 offset0:96 offset1:228
	ds_write2_b32 v201, v122, v123 offset0:96 offset1:228
	ds_write2_b32 v200, v124, v125 offset0:112 offset1:244
	ds_write2_b32 v201, v126, v127 offset0:112 offset1:244
	s_waitcnt lgkmcnt(0)
; DI void epi_slab(const GemmCfg c, const f32x16 (&acc)[4], float* sW, const float* rss, const size_t row0, const int g, const int lane,
;                  float* const g_h, u16* const g_hb, float* const g_out, const int final_out) {
;     ...
;       } else if (c.epi == EPI_QIDX) {
;         f32x4 x = v * (rs * 0.125f);
;         *(u32x2*)(c.o16 + row * 512 + col) = MK2(pack2(x[0], x[1]), pack2(x[2], x[3]));
	ds_read_b128 v[64:67], v202
	ds_read_b128 v[68:71], v202 offset:1056
	ds_read_b128 v[72:75], v202 offset:2112
	ds_read_b128 v[76:79], v202 offset:3168
	ds_read_b128 v[80:83], v202 offset:4224
	ds_read_b128 v[84:87], v202 offset:5280
	ds_read_b128 v[88:91], v202 offset:6336
	ds_read_b128 v[92:95], v202 offset:7392
	ds_read_b128 v[96:99], v202 offset:8448
	s_waitcnt lgkmcnt(8)
	v_lshl_add_u64 v[206:207], v[204:205], 0, s[8:9]
	v_cvt_pk_bf16_f32 v64, v64, v65
	v_cvt_pk_bf16_f32 v65, v66, v67
	s_add_u32 s8, s8, s4
	s_addc_u32 s9, s9, 0
	global_store_dwordx2 v[206:207], v[64:65], off
	ds_read_b128 v[100:103], v202 offset:9504
	s_waitcnt lgkmcnt(8)
	v_lshl_add_u64 v[206:207], v[204:205], 0, s[8:9]
	v_cvt_pk_bf16_f32 v68, v68, v69
	v_cvt_pk_bf16_f32 v69, v70, v71
	s_add_u32 s8, s8, s4
	s_addc_u32 s9, s9, 0
	global_store_dwordx2 v[206:207], v[68:69], off
	ds_read_b128 v[104:107], v202 offset:10560
	s_waitcnt lgkmcnt(8)
	v_lshl_add_u64 v[206:207], v[204:205], 0, s[8:9]
	v_cvt_pk_bf16_f32 v72, v72, v73
	v_cvt_pk_bf16_f32 v73, v74, v75
	s_add_u32 s8, s8, s4
	s_addc_u32 s9, s9, 0
	global_store_dwordx2 v[206:207], v[72:73], off
	ds_read_b128 v[108:111], v202 offset:11616
	s_waitcnt lgkmcnt(8)
	v_lshl_add_u64 v[206:207], v[204:205], 0, s[8:9]
	v_cvt_pk_bf16_f32 v76, v76, v77
	v_cvt_pk_bf16_f32 v77, v78, v79
	s_add_u32 s8, s8, s4
	s_addc_u32 s9, s9, 0
	global_store_dwordx2 v[206:207], v[76:77], off
	ds_read_b128 v[112:115], v202 offset:12672
	s_waitcnt lgkmcnt(8)
	v_lshl_add_u64 v[206:207], v[204:205], 0, s[8:9]
	v_cvt_pk_bf16_f32 v80, v80, v81
	v_cvt_pk_bf16_f32 v81, v82, v83
	s_add_u32 s8, s8, s4
	s_addc_u32 s9, s9, 0
	global_store_dwordx2 v[206:207], v[80:81], off
	ds_read_b128 v[116:119], v202 offset:13728
	s_waitcnt lgkmcnt(8)
	v_lshl_add_u64 v[206:207], v[204:205], 0, s[8:9]
	v_cvt_pk_bf16_f32 v84, v84, v85
	v_cvt_pk_bf16_f32 v85, v86, v87
	s_add_u32 s8, s8, s4
	s_addc_u32 s9, s9, 0
	global_store_dwordx2 v[206:207], v[84:85], off
	ds_read_b128 v[120:123], v202 offset:14784
	s_waitcnt lgkmcnt(8)
	v_lshl_add_u64 v[206:207], v[204:205], 0, s[8:9]
	v_cvt_pk_bf16_f32 v88, v88, v89
	v_cvt_pk_bf16_f32 v89, v90, v91
	s_add_u32 s8, s8, s4
	s_addc_u32 s9, s9, 0
	global_store_dwordx2 v[206:207], v[88:89], off
	ds_read_b128 v[124:127], v202 offset:15840
	s_waitcnt lgkmcnt(8)
	v_lshl_add_u64 v[206:207], v[204:205], 0, s[8:9]
	v_cvt_pk_bf16_f32 v92, v92, v93
	v_cvt_pk_bf16_f32 v93, v94, v95
	s_add_u32 s8, s8, s4
	s_addc_u32 s9, s9, 0
	global_store_dwordx2 v[206:207], v[92:93], off
	s_waitcnt lgkmcnt(7)
	v_lshl_add_u64 v[206:207], v[204:205], 0, s[8:9]
	v_cvt_pk_bf16_f32 v96, v96, v97
	v_cvt_pk_bf16_f32 v97, v98, v99
	s_add_u32 s8, s8, s4
	s_addc_u32 s9, s9, 0
	global_store_dwordx2 v[206:207], v[96:97], off
	s_waitcnt lgkmcnt(6)
	v_lshl_add_u64 v[206:207], v[204:205], 0, s[8:9]
	v_cvt_pk_bf16_f32 v100, v100, v101
	v_cvt_pk_bf16_f32 v101, v102, v103
	s_add_u32 s8, s8, s4
	s_addc_u32 s9, s9, 0
	global_store_dwordx2 v[206:207], v[100:101], off
	s_waitcnt lgkmcnt(5)
	v_lshl_add_u64 v[206:207], v[204:205], 0, s[8:9]
	v_cvt_pk_bf16_f32 v104, v104, v105
	v_cvt_pk_bf16_f32 v105, v106, v107
	s_add_u32 s8, s8, s4
	s_addc_u32 s9, s9, 0
	global_store_dwordx2 v[206:207], v[104:105], off
	s_waitcnt lgkmcnt(4)
	v_lshl_add_u64 v[206:207], v[204:205], 0, s[8:9]
	v_cvt_pk_bf16_f32 v108, v108, v109
	v_cvt_pk_bf16_f32 v109, v110, v111
	s_add_u32 s8, s8, s4
	s_addc_u32 s9, s9, 0
	global_store_dwordx2 v[206:207], v[108:109], off
	s_waitcnt lgkmcnt(3)
	v_lshl_add_u64 v[206:207], v[204:205], 0, s[8:9]
	v_cvt_pk_bf16_f32 v112, v112, v113
	v_cvt_pk_bf16_f32 v113, v114, v115
	s_add_u32 s8, s8, s4
	s_addc_u32 s9, s9, 0
	global_store_dwordx2 v[206:207], v[112:113], off
	s_waitcnt lgkmcnt(2)
	v_lshl_add_u64 v[206:207], v[204:205], 0, s[8:9]
	v_cvt_pk_bf16_f32 v116, v116, v117
	v_cvt_pk_bf16_f32 v117, v118, v119
	s_add_u32 s8, s8, s4
	s_addc_u32 s9, s9, 0
	global_store_dwordx2 v[206:207], v[116:117], off
	s_waitcnt lgkmcnt(1)
	v_lshl_add_u64 v[206:207], v[204:205], 0, s[8:9]
	v_cvt_pk_bf16_f32 v120, v120, v121
	v_cvt_pk_bf16_f32 v121, v122, v123
	s_add_u32 s8, s8, s4
	s_addc_u32 s9, s9, 0
	global_store_dwordx2 v[206:207], v[120:121], off
	s_waitcnt lgkmcnt(0)
	v_lshl_add_u64 v[206:207], v[204:205], 0, s[8:9]
	v_cvt_pk_bf16_f32 v124, v124, v125
	v_cvt_pk_bf16_f32 v125, v126, v127
	s_add_u32 s8, s8, s4
	s_addc_u32 s9, s9, 0
	global_store_dwordx2 v[206:207], v[124:125], off
	v_pk_mul_f32 v[0:1], v[0:1], v[234:235]
	v_pk_mul_f32 v[2:3], v[2:3], v[236:237]
	v_pk_mul_f32 v[4:5], v[4:5], v[234:235]
	v_pk_mul_f32 v[6:7], v[6:7], v[236:237]
	v_pk_mul_f32 v[8:9], v[8:9], v[234:235]
	v_pk_mul_f32 v[10:11], v[10:11], v[236:237]
	v_pk_mul_f32 v[12:13], v[12:13], v[234:235]
	v_pk_mul_f32 v[14:15], v[14:15], v[236:237]
	v_pk_mul_f32 v[16:17], v[16:17], v[234:235]
	v_pk_mul_f32 v[18:19], v[18:19], v[236:237]
	v_pk_mul_f32 v[20:21], v[20:21], v[234:235]
	v_pk_mul_f32 v[22:23], v[22:23], v[236:237]
	v_pk_mul_f32 v[24:25], v[24:25], v[234:235]
	v_pk_mul_f32 v[26:27], v[26:27], v[236:237]
	v_pk_mul_f32 v[28:29], v[28:29], v[234:235]
	v_pk_mul_f32 v[30:31], v[30:31], v[236:237]
	ds_write2_b32 v198, v0, v1 offset0:0 offset1:132
	ds_write2_b32 v199, v2, v3 offset0:0 offset1:132
	ds_write2_b32 v198, v4, v5 offset0:16 offset1:148
	ds_write2_b32 v199, v6, v7 offset0:16 offset1:148
	ds_write2_b32 v198, v8, v9 offset0:32 offset1:164
	ds_write2_b32 v199, v10, v11 offset0:32 offset1:164
	ds_write2_b32 v198, v12, v13 offset0:48 offset1:180
	ds_write2_b32 v199, v14, v15 offset0:48 offset1:180
	ds_write2_b32 v198, v16, v17 offset0:64 offset1:196
	ds_write2_b32 v199, v18, v19 offset0:64 offset1:196
; DI void epi_slab(const GemmCfg c, const f32x16 (&acc)[4], float* sW, const float* rss, const size_t row0, const int g, const int lane,
;                  float* const g_h, u16* const g_hb, float* const g_out, const int final_out) {
;     ...
;       } else if (c.epi == EPI_QIDX) {
;         f32x4 x = v * (rs * 0.125f);
;         *(u32x2*)(c.o16 + row * 512 + col) = MK2(pack2(x[0], x[1]), pack2(x[2], x[3]));
	ds_write2_b32 v198, v20, v21 offset0:80 offset1:212
	ds_write2_b32 v199, v22, v23 offset0:80 offset1:212
	ds_write2_b32 v198, v24, v25 offset0:96 offset1:228
	ds_write2_b32 v199, v26, v27 offset0:96 offset1:228
	ds_write2_b32 v198, v28, v29 offset0:112 offset1:244
	ds_write2_b32 v199, v30, v31 offset0:112 offset1:244
	v_pk_mul_f32 v[32:33], v[32:33], v[238:239]
	v_pk_mul_f32 v[34:35], v[34:35], v[240:241]
	v_pk_mul_f32 v[36:37], v[36:37], v[238:239]
	v_pk_mul_f32 v[38:39], v[38:39], v[240:241]
	v_pk_mul_f32 v[40:41], v[40:41], v[238:239]
	v_pk_mul_f32 v[42:43], v[42:43], v[240:241]
	v_pk_mul_f32 v[44:45], v[44:45], v[238:239]
	v_pk_mul_f32 v[46:47], v[46:47], v[240:241]
	v_pk_mul_f32 v[48:49], v[48:49], v[238:239]
	v_pk_mul_f32 v[50:51], v[50:51], v[240:241]
	v_pk_mul_f32 v[52:53], v[52:53], v[238:239]
	v_pk_mul_f32 v[54:55], v[54:55], v[240:241]
	v_pk_mul_f32 v[56:57], v[56:57], v[238:239]
	v_pk_mul_f32 v[58:59], v[58:59], v[240:241]
	v_pk_mul_f32 v[60:61], v[60:61], v[238:239]
	v_pk_mul_f32 v[62:63], v[62:63], v[240:241]
	ds_write2_b32 v200, v32, v33 offset0:0 offset1:132
	ds_write2_b32 v201, v34, v35 offset0:0 offset1:132
	ds_write2_b32 v200, v36, v37 offset0:16 offset1:148
	ds_write2_b32 v201, v38, v39 offset0:16 offset1:148
	ds_write2_b32 v200, v40, v41 offset0:32 offset1:164
	ds_write2_b32 v201, v42, v43 offset0:32 offset1:164
	ds_write2_b32 v200, v44, v45 offset0:48 offset1:180
	ds_write2_b32 v201, v46, v47 offset0:48 offset1:180
	ds_write2_b32 v200, v48, v49 offset0:64 offset1:196
	ds_write2_b32 v201, v50, v51 offset0:64 offset1:196
	ds_write2_b32 v200, v52, v53 offset0:80 offset1:212
	ds_write2_b32 v201, v54, v55 offset0:80 offset1:212
	ds_write2_b32 v200, v56, v57 offset0:96 offset1:228
	ds_write2_b32 v201, v58, v59 offset0:96 offset1:228
	ds_write2_b32 v200, v60, v61 offset0:112 offset1:244
	ds_write2_b32 v201, v62, v63 offset0:112 offset1:244
	s_waitcnt lgkmcnt(0)
	ds_read_b128 v[0:3], v202
	ds_read_b128 v[4:7], v202 offset:1056
	ds_read_b128 v[8:11], v202 offset:2112
	ds_read_b128 v[12:15], v202 offset:3168
	ds_read_b128 v[16:19], v202 offset:4224
	ds_read_b128 v[20:23], v202 offset:5280
	ds_read_b128 v[24:27], v202 offset:6336
	ds_read_b128 v[28:31], v202 offset:7392
	ds_read_b128 v[32:35], v202 offset:8448
	s_waitcnt lgkmcnt(8)
	v_lshl_add_u64 v[206:207], v[204:205], 0, s[8:9]
	v_cvt_pk_bf16_f32 v0, v0, v1
	v_cvt_pk_bf16_f32 v1, v2, v3
	s_add_u32 s8, s8, s4
	s_addc_u32 s9, s9, 0
	global_store_dwordx2 v[206:207], v[0:1], off
	ds_read_b128 v[36:39], v202 offset:9504
	s_waitcnt lgkmcnt(8)
	v_lshl_add_u64 v[206:207], v[204:205], 0, s[8:9]
	v_cvt_pk_bf16_f32 v4, v4, v5
	v_cvt_pk_bf16_f32 v5, v6, v7
	s_add_u32 s8, s8, s4
	s_addc_u32 s9, s9, 0
	global_store_dwordx2 v[206:207], v[4:5], off
	ds_read_b128 v[40:43], v202 offset:10560
	s_waitcnt lgkmcnt(8)
	v_lshl_add_u64 v[206:207], v[204:205], 0, s[8:9]
	v_cvt_pk_bf16_f32 v8, v8, v9
	v_cvt_pk_bf16_f32 v9, v10, v11
	s_add_u32 s8, s8, s4
	s_addc_u32 s9, s9, 0
	global_store_dwordx2 v[206:207], v[8:9], off
	ds_read_b128 v[44:47], v202 offset:11616
	s_waitcnt lgkmcnt(8)
	v_lshl_add_u64 v[206:207], v[204:205], 0, s[8:9]
	v_cvt_pk_bf16_f32 v12, v12, v13
	v_cvt_pk_bf16_f32 v13, v14, v15
	s_add_u32 s8, s8, s4
	s_addc_u32 s9, s9, 0
	global_store_dwordx2 v[206:207], v[12:13], off
	ds_read_b128 v[48:51], v202 offset:12672
	s_waitcnt lgkmcnt(8)
	v_lshl_add_u64 v[206:207], v[204:205], 0, s[8:9]
	v_cvt_pk_bf16_f32 v16, v16, v17
	v_cvt_pk_bf16_f32 v17, v18, v19
	s_add_u32 s8, s8, s4
	s_addc_u32 s9, s9, 0
	global_store_dwordx2 v[206:207], v[16:17], off
	ds_read_b128 v[52:55], v202 offset:13728
	s_waitcnt lgkmcnt(8)
	v_lshl_add_u64 v[206:207], v[204:205], 0, s[8:9]
	v_cvt_pk_bf16_f32 v20, v20, v21
	v_cvt_pk_bf16_f32 v21, v22, v23
	s_add_u32 s8, s8, s4
	s_addc_u32 s9, s9, 0
	global_store_dwordx2 v[206:207], v[20:21], off
	ds_read_b128 v[56:59], v202 offset:14784
	s_waitcnt lgkmcnt(8)
	v_lshl_add_u64 v[206:207], v[204:205], 0, s[8:9]
	v_cvt_pk_bf16_f32 v24, v24, v25
	v_cvt_pk_bf16_f32 v25, v26, v27
	s_add_u32 s8, s8, s4
	s_addc_u32 s9, s9, 0
	global_store_dwordx2 v[206:207], v[24:25], off
	ds_read_b128 v[60:63], v202 offset:15840
	s_waitcnt lgkmcnt(8)
	v_lshl_add_u64 v[206:207], v[204:205], 0, s[8:9]
	v_cvt_pk_bf16_f32 v28, v28, v29
	v_cvt_pk_bf16_f32 v29, v30, v31
	s_add_u32 s8, s8, s4
	s_addc_u32 s9, s9, 0
	global_store_dwordx2 v[206:207], v[28:29], off
	s_waitcnt lgkmcnt(7)
	v_lshl_add_u64 v[206:207], v[204:205], 0, s[8:9]
	v_cvt_pk_bf16_f32 v32, v32, v33
	v_cvt_pk_bf16_f32 v33, v34, v35
	s_add_u32 s8, s8, s4
	s_addc_u32 s9, s9, 0
	global_store_dwordx2 v[206:207], v[32:33], off
	s_waitcnt lgkmcnt(6)
	v_lshl_add_u64 v[206:207], v[204:205], 0, s[8:9]
	v_cvt_pk_bf16_f32 v36, v36, v37
	v_cvt_pk_bf16_f32 v37, v38, v39
	s_add_u32 s8, s8, s4
	s_addc_u32 s9, s9, 0
	global_store_dwordx2 v[206:207], v[36:37], off
	s_waitcnt lgkmcnt(5)
	v_lshl_add_u64 v[206:207], v[204:205], 0, s[8:9]
	v_cvt_pk_bf16_f32 v40, v40, v41
	v_cvt_pk_bf16_f32 v41, v42, v43
	s_add_u32 s8, s8, s4
	s_addc_u32 s9, s9, 0
	global_store_dwordx2 v[206:207], v[40:41], off
	s_waitcnt lgkmcnt(4)
	v_lshl_add_u64 v[206:207], v[204:205], 0, s[8:9]
	v_cvt_pk_bf16_f32 v44, v44, v45
	v_cvt_pk_bf16_f32 v45, v46, v47
	s_add_u32 s8, s8, s4
	s_addc_u32 s9, s9, 0
	global_store_dwordx2 v[206:207], v[44:45], off
	s_waitcnt lgkmcnt(3)
	v_lshl_add_u64 v[206:207], v[204:205], 0, s[8:9]
	v_cvt_pk_bf16_f32 v48, v48, v49
	v_cvt_pk_bf16_f32 v49, v50, v51
	s_add_u32 s8, s8, s4
	s_addc_u32 s9, s9, 0
	global_store_dwordx2 v[206:207], v[48:49], off
	s_waitcnt lgkmcnt(2)
	v_lshl_add_u64 v[206:207], v[204:205], 0, s[8:9]
	v_cvt_pk_bf16_f32 v52, v52, v53
	v_cvt_pk_bf16_f32 v53, v54, v55
	s_add_u32 s8, s8, s4
	s_addc_u32 s9, s9, 0
	global_store_dwordx2 v[206:207], v[52:53], off
	s_waitcnt lgkmcnt(1)
	v_lshl_add_u64 v[206:207], v[204:205], 0, s[8:9]
	v_cvt_pk_bf16_f32 v56, v56, v57
	v_cvt_pk_bf16_f32 v57, v58, v59
	s_add_u32 s8, s8, s4
	s_addc_u32 s9, s9, 0
	global_store_dwordx2 v[206:207], v[56:57], off
	s_waitcnt lgkmcnt(0)
	v_lshl_add_u64 v[206:207], v[204:205], 0, s[8:9]
	v_cvt_pk_bf16_f32 v60, v60, v61
	v_cvt_pk_bf16_f32 v61, v62, v63
	s_add_u32 s8, s8, s4
	s_addc_u32 s9, s9, 0
	global_store_dwordx2 v[206:207], v[60:61], off
	s_branch .LBB0_108
; DI void epi_slab(const GemmCfg c, const f32x16 (&acc)[4], float* sW, const float* rss, const size_t row0, const int g, const int lane,
;                  float* const g_h, u16* const g_hb, float* const g_out, const int final_out) {
;     ...
;     const int c4 = l31 * 4;
;     const int col = g * 128 + c4;
; #pragma unroll 2
;     for (int it = 0; it < 16; ++it) {
;       const int r = hh + 2 * it;
;       const size_t row = row0 + r;
;       f32x4 v = *(const f32x4*)(sW + r * 132 + c4);
;     ...
;       } else {
;         *(u32x2*)(c.o16 + row * c.ldo + col) = MK2(pack2(v[0], v[1]), pack2(v[2], v[3]));
;       }
.Lplain2:
	v_and_b32_e32 v222, 15, v185
	v_lshrrev_b32_e32 v223, 4, v185
	v_mul_u32_u24_e32 v198, 0x840, v223
	v_lshl_add_u32 v198, v222, 2, v198
	v_add_u32_e32 v198, s53, v198
	v_add_u32_e32 v199, 0x420, v198
	v_add_u32_e32 v200, 0x2100, v198
	v_add_u32_e32 v201, 0x2520, v198
	v_lshrrev_b32_e32 v202, 5, v185
	v_and_b32_e32 v206, 31, v185
	v_mul_u32_u24_e32 v204, 0x210, v202
	v_lshl_add_u32 v204, v206, 4, v204
	v_add_u32_e32 v250, s53, v204
	v_add_u32_e32 v204, s6, v202
	v_mul_lo_u32 v204, v204, s92
	v_lshl_add_u32 v206, v206, 2, s64
	v_lshl_add_u32 v204, v206, 1, v204
	v_mov_b32_e32 v205, 0
	v_lshl_add_u64 v[204:205], v[204:205], 0, s[56:57]
	v_mov_b32_e32 v202, v250
	v_mov_b32_e32 v250, 0x3c800000
	s_lshl_b32 s4, s92, 1
	s_mov_b64 s[8:9], 0
	ds_write2_b32 v198, v64, v65 offset0:0 offset1:132
	ds_write2_b32 v199, v66, v67 offset0:0 offset1:132
	ds_write2_b32 v198, v68, v69 offset0:16 offset1:148
	ds_write2_b32 v199, v70, v71 offset0:16 offset1:148
	ds_write2_b32 v198, v72, v73 offset0:32 offset1:164
	ds_write2_b32 v199, v74, v75 offset0:32 offset1:164
	ds_write2_b32 v198, v76, v77 offset0:48 offset1:180
	ds_write2_b32 v199, v78, v79 offset0:48 offset1:180
	ds_write2_b32 v198, v80, v81 offset0:64 offset1:196
	ds_write2_b32 v199, v82, v83 offset0:64 offset1:196
	ds_write2_b32 v198, v84, v85 offset0:80 offset1:212
	ds_write2_b32 v199, v86, v87 offset0:80 offset1:212
	ds_write2_b32 v198, v88, v89 offset0:96 offset1:228
	ds_write2_b32 v199, v90, v91 offset0:96 offset1:228
	ds_write2_b32 v198, v92, v93 offset0:112 offset1:244
	ds_write2_b32 v199, v94, v95 offset0:112 offset1:244
	ds_write2_b32 v200, v96, v97 offset0:0 offset1:132
	ds_write2_b32 v201, v98, v99 offset0:0 offset1:132
	ds_write2_b32 v200, v100, v101 offset0:16 offset1:148
	ds_write2_b32 v201, v102, v103 offset0:16 offset1:148
	ds_write2_b32 v200, v104, v105 offset0:32 offset1:164
	ds_write2_b32 v201, v106, v107 offset0:32 offset1:164
	ds_write2_b32 v200, v108, v109 offset0:48 offset1:180
	ds_write2_b32 v201, v110, v111 offset0:48 offset1:180
	ds_write2_b32 v200, v112, v113 offset0:64 offset1:196
	ds_write2_b32 v201, v114, v115 offset0:64 offset1:196
	ds_write2_b32 v200, v116, v117 offset0:80 offset1:212
	ds_write2_b32 v201, v118, v119 offset0:80 offset1:212
	ds_write2_b32 v200, v120, v121 offset0:96 offset1:228
	ds_write2_b32 v201, v122, v123 offset0:96 offset1:228
	ds_write2_b32 v200, v124, v125 offset0:112 offset1:244
	ds_write2_b32 v201, v126, v127 offset0:112 offset1:244
	s_waitcnt lgkmcnt(0)
	ds_read_b128 v[64:67], v202
	ds_read_b128 v[68:71], v202 offset:1056
	ds_read_b128 v[72:75], v202 offset:2112
	ds_read_b128 v[76:79], v202 offset:3168
	ds_read_b128 v[80:83], v202 offset:4224
	ds_read_b128 v[84:87], v202 offset:5280
	ds_read_b128 v[88:91], v202 offset:6336
	ds_read_b128 v[92:95], v202 offset:7392
	ds_read_b128 v[96:99], v202 offset:8448
	s_waitcnt lgkmcnt(8)
	v_lshl_add_u64 v[206:207], v[204:205], 0, s[8:9]
	v_cvt_pk_bf16_f32 v64, v64, v65
	v_cvt_pk_bf16_f32 v65, v66, v67
	s_add_u32 s8, s8, s4
	s_addc_u32 s9, s9, 0
	global_store_dwordx2 v[206:207], v[64:65], off
	ds_read_b128 v[100:103], v202 offset:9504
	s_waitcnt lgkmcnt(8)
	v_lshl_add_u64 v[206:207], v[204:205], 0, s[8:9]
	v_cvt_pk_bf16_f32 v68, v68, v69
	v_cvt_pk_bf16_f32 v69, v70, v71
	s_add_u32 s8, s8, s4
	s_addc_u32 s9, s9, 0
	global_store_dwordx2 v[206:207], v[68:69], off
	ds_read_b128 v[104:107], v202 offset:10560
	s_waitcnt lgkmcnt(8)
	v_lshl_add_u64 v[206:207], v[204:205], 0, s[8:9]
	v_cvt_pk_bf16_f32 v72, v72, v73
	v_cvt_pk_bf16_f32 v73, v74, v75
	s_add_u32 s8, s8, s4
	s_addc_u32 s9, s9, 0
	global_store_dwordx2 v[206:207], v[72:73], off
	ds_read_b128 v[108:111], v202 offset:11616
	s_waitcnt lgkmcnt(8)
	v_lshl_add_u64 v[206:207], v[204:205], 0, s[8:9]
	v_cvt_pk_bf16_f32 v76, v76, v77
	v_cvt_pk_bf16_f32 v77, v78, v79
	s_add_u32 s8, s8, s4
	s_addc_u32 s9, s9, 0
	global_store_dwordx2 v[206:207], v[76:77], off
	ds_read_b128 v[112:115], v202 offset:12672
	s_waitcnt lgkmcnt(8)
	v_lshl_add_u64 v[206:207], v[204:205], 0, s[8:9]
	v_cvt_pk_bf16_f32 v80, v80, v81
	v_cvt_pk_bf16_f32 v81, v82, v83
	s_add_u32 s8, s8, s4
	s_addc_u32 s9, s9, 0
	global_store_dwordx2 v[206:207], v[80:81], off
	ds_read_b128 v[116:119], v202 offset:13728
	s_waitcnt lgkmcnt(8)
	v_lshl_add_u64 v[206:207], v[204:205], 0, s[8:9]
	v_cvt_pk_bf16_f32 v84, v84, v85
	v_cvt_pk_bf16_f32 v85, v86, v87
	s_add_u32 s8, s8, s4
	s_addc_u32 s9, s9, 0
	global_store_dwordx2 v[206:207], v[84:85], off
	ds_read_b128 v[120:123], v202 offset:14784
	s_waitcnt lgkmcnt(8)
	v_lshl_add_u64 v[206:207], v[204:205], 0, s[8:9]
	v_cvt_pk_bf16_f32 v88, v88, v89
	v_cvt_pk_bf16_f32 v89, v90, v91
	s_add_u32 s8, s8, s4
	s_addc_u32 s9, s9, 0
	global_store_dwordx2 v[206:207], v[88:89], off
	ds_read_b128 v[124:127], v202 offset:15840
	s_waitcnt lgkmcnt(8)
	v_lshl_add_u64 v[206:207], v[204:205], 0, s[8:9]
	v_cvt_pk_bf16_f32 v92, v92, v93
	v_cvt_pk_bf16_f32 v93, v94, v95
	s_add_u32 s8, s8, s4
	s_addc_u32 s9, s9, 0
	global_store_dwordx2 v[206:207], v[92:93], off
	s_waitcnt lgkmcnt(7)
	v_lshl_add_u64 v[206:207], v[204:205], 0, s[8:9]
	v_cvt_pk_bf16_f32 v96, v96, v97
	v_cvt_pk_bf16_f32 v97, v98, v99
	s_add_u32 s8, s8, s4
	s_addc_u32 s9, s9, 0
	global_store_dwordx2 v[206:207], v[96:97], off
	s_waitcnt lgkmcnt(6)
	v_lshl_add_u64 v[206:207], v[204:205], 0, s[8:9]
	v_cvt_pk_bf16_f32 v100, v100, v101
	v_cvt_pk_bf16_f32 v101, v102, v103
	s_add_u32 s8, s8, s4
	s_addc_u32 s9, s9, 0
	global_store_dwordx2 v[206:207], v[100:101], off
	s_waitcnt lgkmcnt(5)
	v_lshl_add_u64 v[206:207], v[204:205], 0, s[8:9]
	v_cvt_pk_bf16_f32 v104, v104, v105
	v_cvt_pk_bf16_f32 v105, v106, v107
	s_add_u32 s8, s8, s4
	s_addc_u32 s9, s9, 0
	global_store_dwordx2 v[206:207], v[104:105], off
	s_waitcnt lgkmcnt(4)
; DI void epi_slab(const GemmCfg c, const f32x16 (&acc)[4], float* sW, const float* rss, const size_t row0, const int g, const int lane,
;                  float* const g_h, u16* const g_hb, float* const g_out, const int final_out) {
;     ...
;       } else {
;         *(u32x2*)(c.o16 + row * c.ldo + col) = MK2(pack2(v[0], v[1]), pack2(v[2], v[3]));
;       }
	v_lshl_add_u64 v[206:207], v[204:205], 0, s[8:9]
	v_cvt_pk_bf16_f32 v108, v108, v109
	v_cvt_pk_bf16_f32 v109, v110, v111
	s_add_u32 s8, s8, s4
	s_addc_u32 s9, s9, 0
	global_store_dwordx2 v[206:207], v[108:109], off
	s_waitcnt lgkmcnt(3)
	v_lshl_add_u64 v[206:207], v[204:205], 0, s[8:9]
	v_cvt_pk_bf16_f32 v112, v112, v113
	v_cvt_pk_bf16_f32 v113, v114, v115
	s_add_u32 s8, s8, s4
	s_addc_u32 s9, s9, 0
	global_store_dwordx2 v[206:207], v[112:113], off
	s_waitcnt lgkmcnt(2)
	v_lshl_add_u64 v[206:207], v[204:205], 0, s[8:9]
	v_cvt_pk_bf16_f32 v116, v116, v117
	v_cvt_pk_bf16_f32 v117, v118, v119
	s_add_u32 s8, s8, s4
	s_addc_u32 s9, s9, 0
	global_store_dwordx2 v[206:207], v[116:117], off
	s_waitcnt lgkmcnt(1)
	v_lshl_add_u64 v[206:207], v[204:205], 0, s[8:9]
	v_cvt_pk_bf16_f32 v120, v120, v121
	v_cvt_pk_bf16_f32 v121, v122, v123
	s_add_u32 s8, s8, s4
	s_addc_u32 s9, s9, 0
	global_store_dwordx2 v[206:207], v[120:121], off
	s_waitcnt lgkmcnt(0)
	v_lshl_add_u64 v[206:207], v[204:205], 0, s[8:9]
	v_cvt_pk_bf16_f32 v124, v124, v125
	v_cvt_pk_bf16_f32 v125, v126, v127
	s_add_u32 s8, s8, s4
	s_addc_u32 s9, s9, 0
	global_store_dwordx2 v[206:207], v[124:125], off
	ds_write2_b32 v198, v0, v1 offset0:0 offset1:132
	ds_write2_b32 v199, v2, v3 offset0:0 offset1:132
	ds_write2_b32 v198, v4, v5 offset0:16 offset1:148
	ds_write2_b32 v199, v6, v7 offset0:16 offset1:148
	ds_write2_b32 v198, v8, v9 offset0:32 offset1:164
	ds_write2_b32 v199, v10, v11 offset0:32 offset1:164
	ds_write2_b32 v198, v12, v13 offset0:48 offset1:180
	ds_write2_b32 v199, v14, v15 offset0:48 offset1:180
	ds_write2_b32 v198, v16, v17 offset0:64 offset1:196
	ds_write2_b32 v199, v18, v19 offset0:64 offset1:196
	ds_write2_b32 v198, v20, v21 offset0:80 offset1:212
	ds_write2_b32 v199, v22, v23 offset0:80 offset1:212
	ds_write2_b32 v198, v24, v25 offset0:96 offset1:228
	ds_write2_b32 v199, v26, v27 offset0:96 offset1:228
	ds_write2_b32 v198, v28, v29 offset0:112 offset1:244
	ds_write2_b32 v199, v30, v31 offset0:112 offset1:244
	ds_write2_b32 v200, v32, v33 offset0:0 offset1:132
	ds_write2_b32 v201, v34, v35 offset0:0 offset1:132
	ds_write2_b32 v200, v36, v37 offset0:16 offset1:148
	ds_write2_b32 v201, v38, v39 offset0:16 offset1:148
	ds_write2_b32 v200, v40, v41 offset0:32 offset1:164
	ds_write2_b32 v201, v42, v43 offset0:32 offset1:164
	ds_write2_b32 v200, v44, v45 offset0:48 offset1:180
	ds_write2_b32 v201, v46, v47 offset0:48 offset1:180
	ds_write2_b32 v200, v48, v49 offset0:64 offset1:196
	ds_write2_b32 v201, v50, v51 offset0:64 offset1:196
	ds_write2_b32 v200, v52, v53 offset0:80 offset1:212
	ds_write2_b32 v201, v54, v55 offset0:80 offset1:212
	ds_write2_b32 v200, v56, v57 offset0:96 offset1:228
	ds_write2_b32 v201, v58, v59 offset0:96 offset1:228
	ds_write2_b32 v200, v60, v61 offset0:112 offset1:244
	ds_write2_b32 v201, v62, v63 offset0:112 offset1:244
	s_waitcnt lgkmcnt(0)
	ds_read_b128 v[0:3], v202
	ds_read_b128 v[4:7], v202 offset:1056
	ds_read_b128 v[8:11], v202 offset:2112
	ds_read_b128 v[12:15], v202 offset:3168
	ds_read_b128 v[16:19], v202 offset:4224
	ds_read_b128 v[20:23], v202 offset:5280
	ds_read_b128 v[24:27], v202 offset:6336
	ds_read_b128 v[28:31], v202 offset:7392
	ds_read_b128 v[32:35], v202 offset:8448
	s_waitcnt lgkmcnt(8)
	v_lshl_add_u64 v[206:207], v[204:205], 0, s[8:9]
	v_cvt_pk_bf16_f32 v0, v0, v1
	v_cvt_pk_bf16_f32 v1, v2, v3
	s_add_u32 s8, s8, s4
	s_addc_u32 s9, s9, 0
	global_store_dwordx2 v[206:207], v[0:1], off
	ds_read_b128 v[36:39], v202 offset:9504
	s_waitcnt lgkmcnt(8)
; DI void epi_slab(const GemmCfg c, const f32x16 (&acc)[4], float* sW, const float* rss, const size_t row0, const int g, const int lane,
;                  float* const g_h, u16* const g_hb, float* const g_out, const int final_out) {
;     ...
;       } else {
;         *(u32x2*)(c.o16 + row * c.ldo + col) = MK2(pack2(v[0], v[1]), pack2(v[2], v[3]));
;       }
	v_lshl_add_u64 v[206:207], v[204:205], 0, s[8:9]
	v_cvt_pk_bf16_f32 v4, v4, v5
	v_cvt_pk_bf16_f32 v5, v6, v7
	s_add_u32 s8, s8, s4
	s_addc_u32 s9, s9, 0
	global_store_dwordx2 v[206:207], v[4:5], off
	ds_read_b128 v[40:43], v202 offset:10560
	s_waitcnt lgkmcnt(8)
	v_lshl_add_u64 v[206:207], v[204:205], 0, s[8:9]
	v_cvt_pk_bf16_f32 v8, v8, v9
	v_cvt_pk_bf16_f32 v9, v10, v11
	s_add_u32 s8, s8, s4
	s_addc_u32 s9, s9, 0
	global_store_dwordx2 v[206:207], v[8:9], off
	ds_read_b128 v[44:47], v202 offset:11616
	s_waitcnt lgkmcnt(8)
	v_lshl_add_u64 v[206:207], v[204:205], 0, s[8:9]
	v_cvt_pk_bf16_f32 v12, v12, v13
	v_cvt_pk_bf16_f32 v13, v14, v15
	s_add_u32 s8, s8, s4
	s_addc_u32 s9, s9, 0
	global_store_dwordx2 v[206:207], v[12:13], off
	ds_read_b128 v[48:51], v202 offset:12672
	s_waitcnt lgkmcnt(8)
	v_lshl_add_u64 v[206:207], v[204:205], 0, s[8:9]
	v_cvt_pk_bf16_f32 v16, v16, v17
	v_cvt_pk_bf16_f32 v17, v18, v19
	s_add_u32 s8, s8, s4
	s_addc_u32 s9, s9, 0
	global_store_dwordx2 v[206:207], v[16:17], off
	ds_read_b128 v[52:55], v202 offset:13728
	s_waitcnt lgkmcnt(8)
	v_lshl_add_u64 v[206:207], v[204:205], 0, s[8:9]
	v_cvt_pk_bf16_f32 v20, v20, v21
	v_cvt_pk_bf16_f32 v21, v22, v23
	s_add_u32 s8, s8, s4
	s_addc_u32 s9, s9, 0
	global_store_dwordx2 v[206:207], v[20:21], off
	ds_read_b128 v[56:59], v202 offset:14784
	s_waitcnt lgkmcnt(8)
	v_lshl_add_u64 v[206:207], v[204:205], 0, s[8:9]
	v_cvt_pk_bf16_f32 v24, v24, v25
	v_cvt_pk_bf16_f32 v25, v26, v27
	s_add_u32 s8, s8, s4
	s_addc_u32 s9, s9, 0
	global_store_dwordx2 v[206:207], v[24:25], off
	ds_read_b128 v[60:63], v202 offset:15840
	s_waitcnt lgkmcnt(8)
	v_lshl_add_u64 v[206:207], v[204:205], 0, s[8:9]
	v_cvt_pk_bf16_f32 v28, v28, v29
	v_cvt_pk_bf16_f32 v29, v30, v31
	s_add_u32 s8, s8, s4
	s_addc_u32 s9, s9, 0
	global_store_dwordx2 v[206:207], v[28:29], off
	s_waitcnt lgkmcnt(7)
	v_lshl_add_u64 v[206:207], v[204:205], 0, s[8:9]
	v_cvt_pk_bf16_f32 v32, v32, v33
	v_cvt_pk_bf16_f32 v33, v34, v35
	s_add_u32 s8, s8, s4
	s_addc_u32 s9, s9, 0
	global_store_dwordx2 v[206:207], v[32:33], off
	s_waitcnt lgkmcnt(6)
	v_lshl_add_u64 v[206:207], v[204:205], 0, s[8:9]
	v_cvt_pk_bf16_f32 v36, v36, v37
	v_cvt_pk_bf16_f32 v37, v38, v39
	s_add_u32 s8, s8, s4
	s_addc_u32 s9, s9, 0
	global_store_dwordx2 v[206:207], v[36:37], off
	s_waitcnt lgkmcnt(5)
	v_lshl_add_u64 v[206:207], v[204:205], 0, s[8:9]
	v_cvt_pk_bf16_f32 v40, v40, v41
	v_cvt_pk_bf16_f32 v41, v42, v43
	s_add_u32 s8, s8, s4
	s_addc_u32 s9, s9, 0
	global_store_dwordx2 v[206:207], v[40:41], off
	s_waitcnt lgkmcnt(4)
	v_lshl_add_u64 v[206:207], v[204:205], 0, s[8:9]
	v_cvt_pk_bf16_f32 v44, v44, v45
	v_cvt_pk_bf16_f32 v45, v46, v47
	s_add_u32 s8, s8, s4
	s_addc_u32 s9, s9, 0
	global_store_dwordx2 v[206:207], v[44:45], off
	s_waitcnt lgkmcnt(3)
	v_lshl_add_u64 v[206:207], v[204:205], 0, s[8:9]
	v_cvt_pk_bf16_f32 v48, v48, v49
	v_cvt_pk_bf16_f32 v49, v50, v51
	s_add_u32 s8, s8, s4
	s_addc_u32 s9, s9, 0
	global_store_dwordx2 v[206:207], v[48:49], off
	s_waitcnt lgkmcnt(2)
	v_lshl_add_u64 v[206:207], v[204:205], 0, s[8:9]
	v_cvt_pk_bf16_f32 v52, v52, v53
	v_cvt_pk_bf16_f32 v53, v54, v55
	s_add_u32 s8, s8, s4
	s_addc_u32 s9, s9, 0
	global_store_dwordx2 v[206:207], v[52:53], off
	s_waitcnt lgkmcnt(1)
	v_lshl_add_u64 v[206:207], v[204:205], 0, s[8:9]
	v_cvt_pk_bf16_f32 v56, v56, v57
	v_cvt_pk_bf16_f32 v57, v58, v59
	s_add_u32 s8, s8, s4
	s_addc_u32 s9, s9, 0
	global_store_dwordx2 v[206:207], v[56:57], off
	s_waitcnt lgkmcnt(0)
	v_lshl_add_u64 v[206:207], v[204:205], 0, s[8:9]
	v_cvt_pk_bf16_f32 v60, v60, v61
	v_cvt_pk_bf16_f32 v61, v62, v63
	s_add_u32 s8, s8, s4
	s_addc_u32 s9, s9, 0
	global_store_dwordx2 v[206:207], v[60:61], off
	s_branch .LBB0_108
